# LRU-A/LRU-B 4-row scans: ds_bpermute xor16/xor32 shuffles replaced by v_permlane16/32_swap + cndmask (bit-identical data movement), lgkmcnt recounted
# baseline (speedup 1.0000x reference)
; #define LAS __attribute__((address_space(3)))
; __device__ __forceinline__ unsigned pk2(float lo, float hi) { return f2bf(lo) | (f2bf(hi) << 16); }
; template <bool PHASE_B>
; __device__ __forceinline__ void lru_item(const Params& p, LAS unsigned char* lds, int ci, int ci_next, int jb, const int tid, v4u (&xvn)[3]) {
;     ...
;     const LAS float* CW = (const LAS float*)(lds + LR_CW); const LAS float* CB = (const LAS float*)(lds + LR_CB); const LAS float* GC = (const LAS float*)(lds + LR_GC);
;     bf16x8 af[2];
; #pragma unroll
;     for (int ks = 0; ks < 2; ++ks) { const int cb0 = 32 * ks + 8 * fq;
;         f32x4 s0 = *(const LAS f32x4*)(CB + cb0), s1 = *(const LAS f32x4*)(CB + cb0 + 4);
; #pragma unroll
;         for (int tap = 0; tap < 4; ++tap) { const v4u v = *(const LAS v4u*)(lds + LR_XR + (16 * rt + fr + tap) * 144 + cb0 * 2);
;             const f32x4 w0 = *(const LAS f32x4*)(CW + tap * 64 + cb0), w1 = *(const LAS f32x4*)(CW + tap * 64 + cb0 + 4);
;             s0 += (f32x4){bflo(v.x), bfhi(v.x), bflo(v.y), bfhi(v.y)} * w0; s1 += (f32x4){bflo(v.z), bfhi(v.z), bflo(v.w), bfhi(v.w)} * w1; }
;         v4u o; o.x = pk2(s0[0], s0[1]); o.y = pk2(s0[2], s0[3]); o.z = pk2(s1[0], s1[1]); o.w = pk2(s1[2], s1[3]);
;         af[ks] = __builtin_bit_cast(bf16x8, o); }
.LBB0_339:
	s_mov_b32 s98, 0xffff0000
	s_mov_b32 s99, 0xffff0000
	s_mov_b32 s100, 0
	s_mov_b32 s101, -1
	v_add_u32_e32 v1, v167, v157
	ds_read_b128 v[14:17], v165 offset:56832
	ds_read_b128 v[18:21], v165 offset:56848
	ds_read_b128 v[22:25], v1
	v_add_u32_e32 v31, v167, v166
	ds_read_b128 v[26:29], v31 offset:55808
	ds_read_b128 v[36:39], v31 offset:55824
	v_add_u32_e32 v50, 0xd800, v170
	v_add_u32_e32 v51, 0xdc00, v170
	s_waitcnt lgkmcnt(2)
	v_lshlrev_b32_e32 v40, 16, v22
	v_and_b32_e32 v41, 0xffff0000, v22
	v_lshlrev_b32_e32 v22, 16, v23
	v_and_b32_e32 v23, 0xffff0000, v23
	s_waitcnt lgkmcnt(1)
	v_pk_fma_f32 v[28:29], v[28:29], v[22:23], v[16:17]
	v_pk_fma_f32 v[26:27], v[26:27], v[40:41], v[14:15]
	v_lshlrev_b32_e32 v14, 16, v24
	v_and_b32_e32 v15, 0xffff0000, v24
	v_lshlrev_b32_e32 v16, 16, v25
	v_and_b32_e32 v17, 0xffff0000, v25
	s_waitcnt lgkmcnt(0)
	v_pk_fma_f32 v[38:39], v[38:39], v[16:17], v[20:21]
	v_pk_fma_f32 v[36:37], v[36:37], v[14:15], v[18:19]
	ds_read_b128 v[14:17], v1 offset:144
	ds_read_b128 v[18:21], v31 offset:56064
	ds_read_b128 v[22:25], v31 offset:56080
	v_add_u32_e32 v132, v173, v166
	s_and_b64 vcc, exec, s[6:7]
	s_waitcnt lgkmcnt(2)
	v_lshlrev_b32_e32 v40, 16, v14
	v_and_b32_e32 v41, 0xffff0000, v14
	v_lshlrev_b32_e32 v14, 16, v15
	v_and_b32_e32 v15, 0xffff0000, v15
	s_waitcnt lgkmcnt(1)
	v_pk_fma_f32 v[28:29], v[20:21], v[14:15], v[28:29]
	v_lshlrev_b32_e32 v14, 16, v16
	v_and_b32_e32 v15, 0xffff0000, v16
	v_lshlrev_b32_e32 v16, 16, v17
	v_and_b32_e32 v17, 0xffff0000, v17
	v_pk_fma_f32 v[26:27], v[18:19], v[40:41], v[26:27]
	s_waitcnt lgkmcnt(0)
	v_pk_fma_f32 v[38:39], v[24:25], v[16:17], v[38:39]
	v_pk_fma_f32 v[36:37], v[22:23], v[14:15], v[36:37]
	ds_read_b128 v[14:17], v1 offset:288
	ds_read_b128 v[18:21], v31 offset:56320
	ds_read_b128 v[22:25], v31 offset:56336
	s_waitcnt lgkmcnt(2)
	v_lshlrev_b32_e32 v40, 16, v14
	v_and_b32_e32 v41, 0xffff0000, v14
	v_lshlrev_b32_e32 v14, 16, v15
	v_and_b32_e32 v15, 0xffff0000, v15
	s_waitcnt lgkmcnt(1)
	v_pk_fma_f32 v[28:29], v[20:21], v[14:15], v[28:29]
	v_lshlrev_b32_e32 v14, 16, v16
	v_and_b32_e32 v15, 0xffff0000, v16
	v_lshlrev_b32_e32 v16, 16, v17
	v_and_b32_e32 v17, 0xffff0000, v17
	v_pk_fma_f32 v[26:27], v[18:19], v[40:41], v[26:27]
	s_waitcnt lgkmcnt(0)
	v_pk_fma_f32 v[36:37], v[22:23], v[14:15], v[36:37]
	v_pk_fma_f32 v[38:39], v[24:25], v[16:17], v[38:39]
	ds_read_b128 v[14:17], v1 offset:432
	ds_read_b128 v[18:21], v31 offset:56576
	ds_read_b128 v[22:25], v31 offset:56592
	s_waitcnt lgkmcnt(2)
	v_lshlrev_b32_e32 v40, 16, v14
	v_and_b32_e32 v41, 0xffff0000, v14
	v_lshlrev_b32_e32 v14, 16, v15
	v_and_b32_e32 v15, 0xffff0000, v15
	s_waitcnt lgkmcnt(1)
	v_pk_fma_f32 v[20:21], v[20:21], v[14:15], v[28:29]
	v_pk_fma_f32 v[14:15], v[18:19], v[40:41], v[26:27]
	v_lshlrev_b32_e32 v18, 16, v16
	v_bfe_u32 v1, v14, 16, 1
	v_add3_u32 v1, v14, v1, s33
	v_bfe_u32 v14, v15, 16, 1
	v_lshrrev_b32_e32 v1, 16, v1
	v_add3_u32 v14, v15, v14, s33
	v_and_or_b32 v14, v14, s11, v1
	v_and_b32_e32 v19, 0xffff0000, v16
	v_lshlrev_b32_e32 v16, 16, v17
	v_and_b32_e32 v17, 0xffff0000, v17
	s_waitcnt lgkmcnt(0)
	v_pk_fma_f32 v[24:25], v[24:25], v[16:17], v[38:39]
	v_pk_fma_f32 v[16:17], v[22:23], v[18:19], v[36:37]
	v_cvt_pk_bf16_f32 v15, v20, v21
	v_bfe_u32 v1, v16, 16, 1
	v_add3_u32 v1, v16, v1, s33
	v_bfe_u32 v16, v17, 16, 1
	v_lshrrev_b32_e32 v1, 16, v1
	v_add3_u32 v16, v17, v16, s33
	v_and_or_b32 v16, v16, s11, v1
	v_bfe_u32 v1, v24, 16, 1
	v_bfe_u32 v17, v25, 16, 1
	v_add3_u32 v1, v24, v1, s33
	v_add3_u32 v17, v25, v17, s33
	ds_read_b128 v[18:21], v31 offset:56960
	ds_read_b128 v[22:25], v31 offset:56976
	ds_read_b128 v[26:29], v198
	ds_read_b128 v[36:39], v31 offset:55936
	ds_read_b128 v[40:43], v31 offset:55952
	v_lshrrev_b32_e32 v1, 16, v1
	v_and_or_b32 v17, v17, s11, v1
	s_waitcnt lgkmcnt(2)
	v_lshlrev_b32_e32 v44, 16, v26
	v_and_b32_e32 v45, 0xffff0000, v26
	v_lshlrev_b32_e32 v26, 16, v27
	v_and_b32_e32 v27, 0xffff0000, v27
	s_waitcnt lgkmcnt(1)
	v_pk_fma_f32 v[38:39], v[38:39], v[26:27], v[20:21]
	v_pk_fma_f32 v[36:37], v[36:37], v[44:45], v[18:19]
	v_lshlrev_b32_e32 v18, 16, v28
	v_and_b32_e32 v19, 0xffff0000, v28
	v_lshlrev_b32_e32 v20, 16, v29
	v_and_b32_e32 v21, 0xffff0000, v29
	s_waitcnt lgkmcnt(0)
	v_pk_fma_f32 v[42:43], v[42:43], v[20:21], v[24:25]
	v_pk_fma_f32 v[40:41], v[40:41], v[18:19], v[22:23]
	ds_read_b128 v[18:21], v198 offset:144
	ds_read_b128 v[22:25], v31 offset:56192
	ds_read_b128 v[26:29], v31 offset:56208
	s_waitcnt lgkmcnt(2)
	v_lshlrev_b32_e32 v44, 16, v18
	v_and_b32_e32 v45, 0xffff0000, v18
	v_lshlrev_b32_e32 v18, 16, v19
	v_and_b32_e32 v19, 0xffff0000, v19
	s_waitcnt lgkmcnt(1)
	v_pk_fma_f32 v[38:39], v[24:25], v[18:19], v[38:39]
	v_lshlrev_b32_e32 v18, 16, v20
	v_and_b32_e32 v19, 0xffff0000, v20
	v_lshlrev_b32_e32 v20, 16, v21
	v_and_b32_e32 v21, 0xffff0000, v21
	v_pk_fma_f32 v[36:37], v[22:23], v[44:45], v[36:37]
	s_waitcnt lgkmcnt(0)
	v_pk_fma_f32 v[42:43], v[28:29], v[20:21], v[42:43]
	v_pk_fma_f32 v[40:41], v[26:27], v[18:19], v[40:41]
	ds_read_b128 v[18:21], v198 offset:288
	ds_read_b128 v[22:25], v31 offset:56448
	ds_read_b128 v[26:29], v31 offset:56464
	s_waitcnt lgkmcnt(2)
	v_lshlrev_b32_e32 v44, 16, v18
	v_and_b32_e32 v45, 0xffff0000, v18
	v_lshlrev_b32_e32 v18, 16, v19
	v_and_b32_e32 v19, 0xffff0000, v19
	s_waitcnt lgkmcnt(1)
	v_pk_fma_f32 v[38:39], v[24:25], v[18:19], v[38:39]
	v_lshlrev_b32_e32 v18, 16, v20
	v_and_b32_e32 v19, 0xffff0000, v20
	v_lshlrev_b32_e32 v20, 16, v21
	v_and_b32_e32 v21, 0xffff0000, v21
	v_pk_fma_f32 v[36:37], v[22:23], v[44:45], v[36:37]
	s_waitcnt lgkmcnt(0)
; #define LAS __attribute__((address_space(3)))
; template <bool PHASE_B>
; __device__ __forceinline__ void lru_item(const Params& p, LAS unsigned char* lds, int ci, int ci_next, int jb, const int tid, v4u (&xvn)[3]) {
;     ...
;     float xc[4][4];
; #pragma unroll
;     for (int ct = 0; ct < 4; ++ct) { const int ch = 16 * ct + fr; float xr7[7];
; #pragma unroll
;         for (int j = 0; j < 7; ++j) xr7[j] = __builtin_bit_cast(float, (unsigned)(*(const LAS bf16*)(lds + LR_XR + (16 * rt + 4 * fq + j) * 144 + ch * 2)) << 16);
;         const float w0 = CW[ch], w1 = CW[64 + ch], w2 = CW[128 + ch], w3 = CW[192 + ch], b = CB[ch];
; #pragma unroll
;         for (int e = 0; e < 4; ++e) xc[ct][e] = b + xr7[e] * w0 + xr7[e + 1] * w1 + xr7[e + 2] * w2 + xr7[e + 3] * w3; }
	v_pk_fma_f32 v[42:43], v[28:29], v[20:21], v[42:43]
	v_pk_fma_f32 v[40:41], v[26:27], v[18:19], v[40:41]
	ds_read_b128 v[18:21], v198 offset:432
	ds_read_b128 v[22:25], v31 offset:56704
	ds_read_b128 v[26:29], v31 offset:56720
	s_waitcnt lgkmcnt(2)
	v_lshlrev_b32_e32 v44, 16, v18
	v_and_b32_e32 v45, 0xffff0000, v18
	v_lshlrev_b32_e32 v18, 16, v19
	v_and_b32_e32 v19, 0xffff0000, v19
	s_waitcnt lgkmcnt(1)
	v_pk_fma_f32 v[24:25], v[24:25], v[18:19], v[38:39]
	v_pk_fma_f32 v[18:19], v[22:23], v[44:45], v[36:37]
	v_lshlrev_b32_e32 v22, 16, v20
	v_bfe_u32 v1, v18, 16, 1
	v_add3_u32 v1, v18, v1, s33
	v_bfe_u32 v18, v19, 16, 1
	v_lshrrev_b32_e32 v1, 16, v1
	v_add3_u32 v18, v19, v18, s33
	v_and_or_b32 v18, v18, s11, v1
	v_and_b32_e32 v23, 0xffff0000, v20
	v_lshlrev_b32_e32 v20, 16, v21
	v_and_b32_e32 v21, 0xffff0000, v21
	s_waitcnt lgkmcnt(0)
	v_pk_fma_f32 v[28:29], v[28:29], v[20:21], v[42:43]
	v_pk_fma_f32 v[20:21], v[26:27], v[22:23], v[40:41]
	v_cvt_pk_bf16_f32 v19, v24, v25
	v_bfe_u32 v1, v20, 16, 1
	v_add3_u32 v1, v20, v1, s33
	v_bfe_u32 v20, v21, 16, 1
	v_lshrrev_b32_e32 v1, 16, v1
	v_add3_u32 v20, v21, v20, s33
	v_and_or_b32 v20, v20, s11, v1
	v_cvt_pk_bf16_f32 v21, v28, v29
	v_add_u32_e32 v1, v168, v169
	ds_read_u16 v22, v1
	s_waitcnt lgkmcnt(0)
	v_lshlrev_b32_e32 v23, 16, v22
	ds_read_u16 v22, v1 offset:144
	ds_read_u16 v31, v1 offset:288
	ds_read_u16 v38, v1 offset:432
	ds_read_u16 v39, v1 offset:576
	ds_read_u16 v46, v1 offset:720
	ds_read_u16 v1, v1 offset:864
	ds_read2_b32 v[24:25], v50 offset0:128 offset1:144
	ds_read2_b32 v[26:27], v50 offset0:192 offset1:208
	ds_read2_b32 v[28:29], v51 offset1:16
	ds_read2_b32 v[36:37], v51 offset0:64 offset1:80
	ds_read2_b32 v[40:41], v51 offset0:128 offset1:144
	s_waitcnt lgkmcnt(10)
	v_lshlrev_b32_e32 v45, 16, v22
	s_waitcnt lgkmcnt(8)
	v_lshlrev_b32_e32 v43, 16, v38
	s_waitcnt lgkmcnt(7)
	v_lshlrev_b32_e32 v42, 16, v39
	s_waitcnt lgkmcnt(3)
	v_mov_b32_e32 v38, v26
	v_mov_b32_e32 v39, v24
	v_mov_b32_e32 v22, v45
	v_pk_mul_f32 v[22:23], v[38:39], v[22:23]
	v_lshlrev_b32_e32 v44, 16, v31
	s_waitcnt lgkmcnt(0)
	v_add_f32_e32 v23, v23, v40
	v_add_f32_e32 v24, v22, v23
	v_pk_mul_f32 v[22:23], v[38:39], v[44:45]
	v_mov_b32_e32 v47, v28
	v_add_f32_e32 v23, v23, v40
	v_add_f32_e32 v26, v22, v23
	v_pk_mov_b32 v[22:23], v[42:43], v[44:45] op_sel:[1,0]
	s_nop 0
	v_pk_mul_f32 v[44:45], v[38:39], v[22:23]
	v_pk_mul_f32 v[38:39], v[38:39], v[42:43]
	v_add_f32_e32 v31, v45, v40
	v_lshlrev_b32_e32 v45, 16, v46
	v_mov_b32_e32 v46, v36
	v_pk_mul_f32 v[48:49], v[46:47], v[22:23]
	v_pk_mul_f32 v[22:23], v[46:47], v[42:43]
	v_add_f32_e32 v31, v44, v31
	v_lshlrev_b32_e32 v44, 16, v1
	v_add_f32_e32 v1, v23, v26
	v_add_f32_e32 v108, v22, v1
	v_pk_mov_b32 v[22:23], v[44:45], v[42:43] op_sel:[1,0]
	v_add_f32_e32 v39, v39, v40
	v_pk_mul_f32 v[22:23], v[46:47], v[22:23]
	v_add_f32_e32 v38, v38, v39
	v_add_f32_e32 v1, v23, v31
	v_add_f32_e32 v106, v22, v1
	v_pk_mul_f32 v[22:23], v[46:47], v[44:45]
	v_add_f32_e32 v39, v49, v24
	v_add_f32_e32 v1, v23, v38
	v_add_f32_e32 v101, v22, v1
	ds_read_u16 v1, v199
	v_add_f32_e32 v110, v48, v39
	s_waitcnt lgkmcnt(0)
	v_lshlrev_b32_e32 v23, 16, v1
	ds_read_u16 v1, v199 offset:144
	ds_read_u16 v22, v199 offset:288
	ds_read_u16 v24, v199 offset:432
	ds_read_u16 v26, v199 offset:576
	ds_read_u16 v28, v199 offset:720
	ds_read_u16 v31, v199 offset:864
	s_waitcnt lgkmcnt(3)
	v_lshlrev_b32_e32 v43, 16, v24
	v_mov_b32_e32 v24, v27
	v_lshlrev_b32_e32 v27, 16, v1
	s_waitcnt lgkmcnt(2)
	v_lshlrev_b32_e32 v42, 16, v26
	v_lshlrev_b32_e32 v26, 16, v22
	v_mov_b32_e32 v22, v27
	v_pk_mul_f32 v[22:23], v[24:25], v[22:23]
	s_nop 0
	v_add_f32_e32 v1, v23, v41
	v_add_f32_e32 v1, v22, v1
	v_pk_mul_f32 v[22:23], v[24:25], v[26:27]
	s_nop 0
	v_add_f32_e32 v23, v23, v41
	v_add_f32_e32 v36, v22, v23
	v_pk_mov_b32 v[22:23], v[42:43], v[26:27] op_sel:[1,0]
	s_nop 0
	v_pk_mul_f32 v[26:27], v[24:25], v[22:23]
	v_pk_mul_f32 v[24:25], v[24:25], v[42:43]
	v_add_f32_e32 v27, v27, v41
	v_add_f32_e32 v25, v25, v41
	v_add_f32_e32 v26, v26, v27
	v_add_f32_e32 v27, v24, v25
	s_waitcnt lgkmcnt(1)
	v_lshlrev_b32_e32 v25, 16, v28
	v_mov_b32_e32 v28, v37
	v_pk_mul_f32 v[64:65], v[28:29], v[22:23]
	v_pk_mul_f32 v[22:23], v[28:29], v[42:43]
	s_waitcnt lgkmcnt(0)
	v_lshlrev_b32_e32 v24, 16, v31
	v_add_f32_e32 v57, v65, v1
	v_add_f32_e32 v1, v23, v36
	v_add_f32_e32 v120, v22, v1
	v_pk_mov_b32 v[22:23], v[24:25], v[42:43] op_sel:[1,0]
	v_add_f32_e32 v122, v64, v57
	v_pk_mul_f32 v[22:23], v[28:29], v[22:23]
	s_nop 0
	v_add_f32_e32 v1, v23, v26
	v_add_f32_e32 v118, v22, v1
	v_pk_mul_f32 v[22:23], v[28:29], v[24:25]
	s_nop 0
	v_add_f32_e32 v1, v23, v27
	v_add_f32_e32 v113, v22, v1
	ds_read_u16 v1, v200
	s_waitcnt lgkmcnt(0)
	v_lshlrev_b32_e32 v23, 16, v1
	ds_read_u16 v1, v200 offset:144
	ds_read_u16 v22, v200 offset:288
	ds_read_u16 v31, v200 offset:432
	ds_read_u16 v38, v200 offset:576
	ds_read_u16 v49, v200 offset:720
	ds_read_u16 v52, v200 offset:864
	ds_read2_b32 v[24:25], v50 offset0:160 offset1:176
	ds_read2_b32 v[26:27], v50 offset0:224 offset1:240
	ds_read2_b32 v[28:29], v51 offset0:32 offset1:48
	ds_read2_b32 v[36:37], v51 offset0:96 offset1:112
	ds_read2_b32 v[40:41], v51 offset0:160 offset1:176
	s_waitcnt lgkmcnt(10)
	v_lshlrev_b32_e32 v47, 16, v1
	s_waitcnt lgkmcnt(3)
	v_mov_b32_e32 v44, v26
	v_mov_b32_e32 v45, v24
	v_lshlrev_b32_e32 v46, 16, v22
	v_mov_b32_e32 v22, v47
	v_pk_mul_f32 v[22:23], v[44:45], v[22:23]
	v_lshlrev_b32_e32 v43, 16, v31
	s_waitcnt lgkmcnt(0)
; #define LAS __attribute__((address_space(3)))
; #define MFMA16(a, b, c) __builtin_amdgcn_mfma_f32_16x16x32_bf16(a, b, c, 0, 0, 0)
; template <bool PHASE_B>
; __device__ __forceinline__ void lru_item(const Params& p, LAS unsigned char* lds, int ci, int ci_next, int jb, const int tid, v4u (&xvn)[3]) {
;     ...
;     for (int ct = 0; ct < 4; ++ct) { const int ch = 16 * ct + fr; float xr7[7];
; #pragma unroll
;         for (int j = 0; j < 7; ++j) xr7[j] = __builtin_bit_cast(float, (unsigned)(*(const LAS bf16*)(lds + LR_XR + (16 * rt + 4 * fq + j) * 144 + ch * 2)) << 16);
;         const float w0 = CW[ch], w1 = CW[64 + ch], w2 = CW[128 + ch], w3 = CW[192 + ch], b = CB[ch];
; #pragma unroll
;         for (int e = 0; e < 4; ++e) xc[ct][e] = b + xr7[e] * w0 + xr7[e + 1] * w1 + xr7[e + 2] * w2 + xr7[e + 3] * w3; }
;     float av[2][4][4], uv[2][4][4], pA[2][4], pH[2][4];
; #pragma unroll
;     for (int dir = 0; dir < 2; ++dir) {
; #pragma unroll
;         for (int ct = 0; ct < 4; ++ct) {
;             f32x4 ga = (f32x4){0.f, 0.f, 0.f, 0.f}, gx = (f32x4){0.f, 0.f, 0.f, 0.f};
; #pragma unroll
;             for (int ks = 0; ks < 2; ++ks) {
;                 const bf16x8 wa = *(const LAS bf16x8*)(lds + LR_WG + ((dir * 2 + 0) * 64 + 16 * ct + fr) * 144 + (32 * ks + 8 * fq) * 2);
;                 const bf16x8 wx = *(const LAS bf16x8*)(lds + LR_WG + ((dir * 2 + 1) * 64 + 16 * ct + fr) * 144 + (32 * ks + 8 * fq) * 2);
;                 ga = MFMA16(af[ks], wa, ga); gx = MFMA16(af[ks], wx, gx); }
;             const int ch = 16 * ct + fr; const float bav = GC[(dir * 3 + 0) * 64 + ch], bxv = GC[(dir * 3 + 1) * 64 + ch], c8 = GC[(dir * 3 + 2) * 64 + ch];
;             float Al = 1.f, Hl = 0.f;
; #pragma unroll
;             for (int ee = 0; ee < 4; ++ee) { const int e = dir ? 3 - ee : ee;
;                 const float r = __builtin_amdgcn_rcpf(1.f + __expf(-(ga[e] + bav))), ig = __builtin_amdgcn_rcpf(1.f + __expf(-(gx[e] + bxv)));
;                 const float la = -c8 * r; const float a = __expf(la); const float u = __builtin_amdgcn_sqrtf((1.f - a) * (1.f + a)) * (ig * xc[ct][e]);
;                 av[dir][ct][e] = a; uv[dir][ct][e] = u; Hl = a * Hl + u; Al *= a; }
	v_add_f32_e32 v1, v23, v40
	v_add_f32_e32 v1, v22, v1
	v_pk_mul_f32 v[22:23], v[44:45], v[46:47]
	v_lshlrev_b32_e32 v42, 16, v38
	v_add_f32_e32 v23, v23, v40
	v_add_f32_e32 v24, v22, v23
	v_pk_mov_b32 v[22:23], v[42:43], v[46:47] op_sel:[1,0]
	v_mov_b32_e32 v50, v36
	v_pk_mul_f32 v[46:47], v[44:45], v[22:23]
	v_pk_mul_f32 v[44:45], v[44:45], v[42:43]
	v_mov_b32_e32 v51, v28
	v_add_f32_e32 v31, v45, v40
	v_add_f32_e32 v26, v47, v40
	v_add_f32_e32 v31, v44, v31
	v_pk_mul_f32 v[44:45], v[50:51], v[22:23]
	v_pk_mul_f32 v[22:23], v[50:51], v[42:43]
	v_add_f32_e32 v26, v46, v26
	v_lshlrev_b32_e32 v47, 16, v49
	v_lshlrev_b32_e32 v46, 16, v52
	v_add_f32_e32 v45, v45, v1
	v_add_f32_e32 v1, v23, v24
	v_add_f32_e32 v130, v22, v1
	v_pk_mov_b32 v[22:23], v[46:47], v[42:43] op_sel:[1,0]
	s_nop 0
	v_pk_mul_f32 v[22:23], v[50:51], v[22:23]
	s_nop 0
	v_add_f32_e32 v1, v23, v26
	v_add_f32_e32 v128, v22, v1
	v_pk_mul_f32 v[22:23], v[50:51], v[46:47]
	s_nop 0
	v_add_f32_e32 v1, v23, v31
	v_add_f32_e32 v125, v22, v1
	ds_read_u16 v1, v201
	s_waitcnt lgkmcnt(0)
	v_lshlrev_b32_e32 v23, 16, v1
	ds_read_u16 v1, v201 offset:144
	ds_read_u16 v22, v201 offset:288
	ds_read_u16 v24, v201 offset:432
	ds_read_u16 v26, v201 offset:576
	ds_read_u16 v28, v201 offset:720
	ds_read_u16 v31, v201 offset:864
	s_waitcnt lgkmcnt(3)
	v_lshlrev_b32_e32 v43, 16, v24
	v_mov_b32_e32 v24, v27
	v_lshlrev_b32_e32 v27, 16, v1
	s_waitcnt lgkmcnt(2)
	v_lshlrev_b32_e32 v42, 16, v26
	v_lshlrev_b32_e32 v26, 16, v22
	v_mov_b32_e32 v22, v27
	v_pk_mul_f32 v[22:23], v[24:25], v[22:23]
	s_nop 0
	v_add_f32_e32 v1, v23, v41
	v_add_f32_e32 v1, v22, v1
	v_pk_mul_f32 v[22:23], v[24:25], v[26:27]
	s_nop 0
	v_add_f32_e32 v23, v23, v41
	v_add_f32_e32 v38, v22, v23
	v_pk_mov_b32 v[22:23], v[42:43], v[26:27] op_sel:[1,0]
	s_nop 0
	v_pk_mul_f32 v[26:27], v[24:25], v[22:23]
	v_pk_mul_f32 v[24:25], v[24:25], v[42:43]
	v_add_f32_e32 v27, v27, v41
	v_add_f32_e32 v25, v25, v41
	v_add_f32_e32 v26, v26, v27
	v_add_f32_e32 v27, v24, v25
	s_waitcnt lgkmcnt(1)
	v_lshlrev_b32_e32 v25, 16, v28
	v_mov_b32_e32 v28, v37
	v_pk_mul_f32 v[36:37], v[28:29], v[22:23]
	v_pk_mul_f32 v[22:23], v[28:29], v[42:43]
	s_waitcnt lgkmcnt(0)
	v_lshlrev_b32_e32 v24, 16, v31
	v_add_f32_e32 v37, v37, v1
	v_add_f32_e32 v1, v23, v38
	v_add_f32_e32 v31, v22, v1
	v_pk_mov_b32 v[22:23], v[24:25], v[42:43] op_sel:[1,0]
	s_nop 0
	v_pk_mul_f32 v[22:23], v[28:29], v[22:23]
	s_nop 0
	v_add_f32_e32 v1, v23, v26
	v_add_f32_e32 v136, v22, v1
	v_pk_mul_f32 v[22:23], v[28:29], v[24:25]
	s_nop 0
	v_add_f32_e32 v1, v23, v27
	v_add_f32_e32 v133, v22, v1
	ds_read_b128 v[22:25], v132 offset:18944
	ds_read_b128 v[26:29], v132 offset:28160
	s_waitcnt lgkmcnt(1)
	v_mfma_f32_16x16x32_bf16 v[22:25], v[14:17], v[22:25], 0
	s_waitcnt lgkmcnt(0)
	v_mfma_f32_16x16x32_bf16 v[40:43], v[14:17], v[26:29], 0
	ds_read_b128 v[26:29], v132 offset:19008
	ds_read_b128 v[50:53], v132 offset:28224
	ds_read_b32 v49, v174 offset:57088
	ds_read_b32 v47, v174 offset:57344
	ds_read_b32 v46, v174 offset:57600
	s_waitcnt lgkmcnt(4)
	v_mfma_f32_16x16x32_bf16 v[26:29], v[18:21], v[26:29], v[22:25]
	s_waitcnt lgkmcnt(3)
	v_mfma_f32_16x16x32_bf16 v[22:25], v[18:21], v[50:53], v[40:43]
	ds_read_b32 v227, v174 offset:57152
	ds_read_b32 v228, v174 offset:57408
	ds_read_b32 v229, v174 offset:57664
	ds_read_b128 v[208:211], v132 offset:21248
	ds_read_b128 v[212:215], v132 offset:30464
	ds_read_b128 v[216:219], v132 offset:21312
	ds_read_b128 v[220:223], v132 offset:30528
	s_waitcnt lgkmcnt(2)
	s_nop 4
	v_add_f32_e32 v1, v26, v49
	v_mul_f32_e32 v1, 0xbfb8aa3b, v1
	v_exp_f32_e32 v1, v1
	s_nop 0
	v_add_f32_e32 v1, 1.0, v1
	v_rcp_f32_e32 v1, v1
	s_waitcnt lgkmcnt(1)
	v_add_f32_e32 v22, v22, v47
	v_mul_f32_e32 v22, 0xbfb8aa3b, v22
	v_exp_f32_e32 v22, v22
	s_waitcnt lgkmcnt(0)
	v_mul_f32_e32 v1, v1, v46
	v_mul_f32_e32 v1, 0xbfb8aa3b, v1
	v_exp_f32_e32 v38, v1
	v_add_f32_e32 v22, 1.0, v22
	v_rcp_f32_e32 v50, v22
	v_add_f32_e32 v23, v23, v47
	v_sub_f32_e32 v1, 1.0, v38
	v_add_f32_e32 v22, 1.0, v38
	v_mul_f32_e32 v1, v1, v22
	v_add_f32_e32 v22, v27, v49
	v_mul_f32_e32 v22, 0xbfb8aa3b, v22
	v_exp_f32_e32 v22, v22
	v_mul_f32_e32 v23, 0xbfb8aa3b, v23
	v_exp_f32_e32 v23, v23
	v_add_f32_e32 v24, v24, v47
	v_add_f32_e32 v22, 1.0, v22
	v_rcp_f32_e32 v22, v22
	v_add_f32_e32 v23, 1.0, v23
	v_rcp_f32_e32 v23, v23
	v_add_f32_e32 v25, v25, v47
	v_mul_f32_e32 v22, v22, v46
	v_mul_f32_e32 v22, 0xbfb8aa3b, v22
	v_exp_f32_e32 v41, v22
	v_mul_f32_e32 v24, 0xbfb8aa3b, v24
	v_mul_f32_e32 v25, 0xbfb8aa3b, v25
	v_sqrt_f32_e32 v1, v1
	v_sub_f32_e32 v22, 1.0, v41
	v_add_f32_e32 v26, 1.0, v41
	v_mul_f32_e32 v22, v22, v26
	v_add_f32_e32 v26, v28, v49
	v_mul_f32_e32 v26, 0xbfb8aa3b, v26
	v_exp_f32_e32 v26, v26
	v_sqrt_f32_e32 v40, v22
	v_mul_f32_e32 v22, v108, v23
	v_mul_f32_e32 v23, v38, v41
	v_add_f32_e32 v26, 1.0, v26
	v_rcp_f32_e32 v26, v26
	v_exp_f32_e32 v24, v24
	v_exp_f32_e32 v25, v25
	v_mul_f32_e32 v39, v110, v50
	v_mul_f32_e32 v26, v26, v46
	v_mul_f32_e32 v26, 0xbfb8aa3b, v26
	v_exp_f32_e32 v43, v26
	v_add_f32_e32 v24, 1.0, v24
	v_add_f32_e32 v25, 1.0, v25
	v_rcp_f32_e32 v24, v24
	v_sub_f32_e32 v26, 1.0, v43
	v_add_f32_e32 v27, 1.0, v43
	v_mul_f32_e32 v26, v26, v27
	v_sqrt_f32_e32 v42, v26
	v_add_f32_e32 v26, v29, v49
	v_mul_f32_e32 v26, 0xbfb8aa3b, v26
	v_exp_f32_e32 v26, v26
	v_mul_f32_e32 v23, v43, v23
	v_pk_mul_f32 v[48:49], v[38:39], v[0:1]
	v_rcp_f32_e32 v25, v25
	v_add_f32_e32 v26, 1.0, v26
	v_rcp_f32_e32 v26, v26
	v_pk_fma_f32 v[50:51], v[38:39], v[0:1], v[48:49] op_sel_hi:[1,1,0]
	v_mul_f32_e32 v24, v106, v24
	v_mul_f32_e32 v26, v26, v46
	v_mul_f32_e32 v26, 0xbfb8aa3b, v26
	v_exp_f32_e32 v47, v26
	s_nop 0
	v_mul_f32_e32 v29, v47, v23
	v_sub_f32_e32 v26, 1.0, v47
	v_add_f32_e32 v27, 1.0, v47
	v_mul_f32_e32 v26, v26, v27
	v_sqrt_f32_e32 v46, v26
	s_waitcnt lgkmcnt(0)
; #define LAS __attribute__((address_space(3)))
; #define MFMA16(a, b, c) __builtin_amdgcn_mfma_f32_16x16x32_bf16(a, b, c, 0, 0, 0)
; template <bool PHASE_B>
; __device__ __forceinline__ void lru_item(const Params& p, LAS unsigned char* lds, int ci, int ci_next, int jb, const int tid, v4u (&xvn)[3]) {
;     ...
; #pragma unroll
;         for (int ct = 0; ct < 4; ++ct) {
;             f32x4 ga = (f32x4){0.f, 0.f, 0.f, 0.f}, gx = (f32x4){0.f, 0.f, 0.f, 0.f};
; #pragma unroll
;             for (int ks = 0; ks < 2; ++ks) {
;                 const bf16x8 wa = *(const LAS bf16x8*)(lds + LR_WG + ((dir * 2 + 0) * 64 + 16 * ct + fr) * 144 + (32 * ks + 8 * fq) * 2);
;                 const bf16x8 wx = *(const LAS bf16x8*)(lds + LR_WG + ((dir * 2 + 1) * 64 + 16 * ct + fr) * 144 + (32 * ks + 8 * fq) * 2);
;                 ga = MFMA16(af[ks], wa, ga); gx = MFMA16(af[ks], wx, gx); }
;             const int ch = 16 * ct + fr; const float bav = GC[(dir * 3 + 0) * 64 + ch], bxv = GC[(dir * 3 + 1) * 64 + ch], c8 = GC[(dir * 3 + 2) * 64 + ch];
;             float Al = 1.f, Hl = 0.f;
; #pragma unroll
;             for (int ee = 0; ee < 4; ++ee) { const int e = dir ? 3 - ee : ee;
;                 const float r = __builtin_amdgcn_rcpf(1.f + __expf(-(ga[e] + bav))), ig = __builtin_amdgcn_rcpf(1.f + __expf(-(gx[e] + bxv)));
;                 const float la = -c8 * r; const float a = __expf(la); const float u = __builtin_amdgcn_sqrtf((1.f - a) * (1.f + a)) * (ig * xc[ct][e]);
;                 av[dir][ct][e] = a; uv[dir][ct][e] = u; Hl = a * Hl + u; Al *= a; }
;             const int o = dir ? 3 - fq : fq; const bool odd = (o & 1) != 0, hi2 = (o & 2) != 0;
;             const float A1 = __shfl_xor(Al, 16), H1 = __shfl_xor(Hl, 16);
;             const float pxA = odd ? A1 : 1.f, pxH = odd ? H1 : 0.f;
;             const float gA = Al * A1, gH = odd ? (Al * H1 + Hl) : (A1 * Hl + H1);
;             const float A2 = __shfl_xor(gA, 32), H2 = __shfl_xor(gH, 32);
;             const float PA = hi2 ? pxA * A2 : pxA, PH = hi2 ? (pxA * H2 + pxH) : pxH;
;             const float TA = gA * A2, TH = hi2 ? (gA * H2 + gH) : (A2 * gH + H2);
;             pA[dir][ct] = PA; pH[dir][ct] = PH;
;             ((LAS f32x2*)(lds + LR_SEG))[(dir * 8 + rt) * 64 + ch] = (f32x2){TA, TH};
	v_mov_b32_e32 v249, v29
	v_mov_b32_e32 v56, v29
	s_nop 1
	v_permlane16_swap_b32_e32 v56, v249
	v_cndmask_b32_e64 v56, v249, v56, s[98:99]
	v_mul_f32_e32 v59, v29, v56
	v_cndmask_b32_e64 v58, v56, 1.0, s[50:51]
	v_mul_f32_e32 v26, v101, v25
	s_waitcnt lgkmcnt(0)
	v_mov_b32_e32 v249, v59
	v_mov_b32_e32 v60, v59
	s_nop 1
	v_permlane32_swap_b32_e32 v60, v249
	v_cndmask_b32_e64 v60, v249, v60, s[100:101]
	v_mul_f32_e32 v23, v58, v60
	v_cndmask_b32_e64 v206, v23, v58, s[52:53]
	v_mov_b32_e32 v23, v51
	v_pk_mul_f32 v[50:51], v[22:23], v[40:41]
	v_mul_f32_e32 v28, v59, v60
	v_pk_fma_f32 v[22:23], v[22:23], v[40:41], v[50:51] op_sel_hi:[1,1,0]
	s_nop 0
	v_mov_b32_e32 v25, v23
	v_pk_mul_f32 v[52:53], v[24:25], v[42:43]
	s_nop 0
	v_pk_fma_f32 v[22:23], v[24:25], v[42:43], v[52:53] op_sel_hi:[1,1,0]
	s_nop 0
	v_mov_b32_e32 v27, v23
	v_pk_mul_f32 v[54:55], v[26:27], v[46:47]
	s_nop 0
	v_add_f32_e32 v1, v54, v55
	s_waitcnt lgkmcnt(0)
	v_mov_b32_e32 v249, v1
	v_mov_b32_e32 v22, v1
	s_nop 1
	v_permlane16_swap_b32_e32 v22, v249
	v_cndmask_b32_e64 v22, v249, v22, s[98:99]
	v_cndmask_b32_e64 v23, v22, 0, s[50:51]
	v_fma_f32 v24, v29, v22, v1
	v_fmac_f32_e32 v22, v1, v56
	v_cndmask_b32_e64 v1, v24, v22, s[50:51]
	s_waitcnt lgkmcnt(0)
	v_mov_b32_e32 v249, v1
	v_mov_b32_e32 v22, v1
	s_nop 1
	v_permlane32_swap_b32_e32 v22, v249
	v_cndmask_b32_e64 v22, v249, v22, s[100:101]
	v_fma_f32 v24, v58, v22, v23
	v_cndmask_b32_e64 v39, v24, v23, s[52:53]
	v_fma_f32 v23, v59, v22, v1
	v_fmac_f32_e32 v22, v1, v60
	v_cndmask_b32_e64 v29, v23, v22, s[52:53]
	ds_write_b64 v175, v[28:29] offset:58624
	s_waitcnt lgkmcnt(1)
	v_mfma_f32_16x16x32_bf16 v[22:25], v[14:17], v[208:211], 0
	s_waitcnt lgkmcnt(0)
	v_mfma_f32_16x16x32_bf16 v[58:61], v[14:17], v[212:215], 0
	s_waitcnt lgkmcnt(1)
	v_mfma_f32_16x16x32_bf16 v[26:29], v[18:21], v[216:219], v[22:25]
	s_waitcnt lgkmcnt(1)
	v_mfma_f32_16x16x32_bf16 v[22:25], v[18:21], v[220:223], v[58:61]
	ds_read_b128 v[208:211], v132 offset:23552
	ds_read_b128 v[212:215], v132 offset:32768
	ds_read_b128 v[216:219], v132 offset:23616
	ds_read_b128 v[220:223], v132 offset:32832
	s_waitcnt lgkmcnt(2)
	s_nop 4
	v_add_f32_e32 v1, v26, v227
	v_mul_f32_e32 v1, 0xbfb8aa3b, v1
	v_exp_f32_e32 v1, v1
	s_nop 0
	v_add_f32_e32 v1, 1.0, v1
	v_rcp_f32_e32 v1, v1
	s_waitcnt lgkmcnt(1)
	v_add_f32_e32 v22, v22, v228
	v_mul_f32_e32 v22, 0xbfb8aa3b, v22
	v_exp_f32_e32 v22, v22
	s_waitcnt lgkmcnt(0)
	v_mul_f32_e32 v1, v1, v229
	v_mul_f32_e32 v1, 0xbfb8aa3b, v1
	v_exp_f32_e32 v56, v1
	v_add_f32_e32 v22, 1.0, v22
	v_rcp_f32_e32 v48, v22
	v_add_f32_e32 v23, v23, v228
	v_sub_f32_e32 v1, 1.0, v56
	v_add_f32_e32 v22, 1.0, v56
	v_mul_f32_e32 v1, v1, v22
	v_add_f32_e32 v22, v27, v227
	v_mul_f32_e32 v22, 0xbfb8aa3b, v22
	v_exp_f32_e32 v22, v22
	v_mul_f32_e32 v23, 0xbfb8aa3b, v23
	v_exp_f32_e32 v23, v23
	v_add_f32_e32 v24, v24, v228
	v_add_f32_e32 v22, 1.0, v22
	v_rcp_f32_e32 v22, v22
	v_add_f32_e32 v23, 1.0, v23
	v_rcp_f32_e32 v23, v23
	v_add_f32_e32 v25, v25, v228
	v_mul_f32_e32 v22, v22, v229
	v_mul_f32_e32 v22, 0xbfb8aa3b, v22
	v_exp_f32_e32 v59, v22
	v_mul_f32_e32 v24, 0xbfb8aa3b, v24
	v_mul_f32_e32 v25, 0xbfb8aa3b, v25
	v_sqrt_f32_e32 v1, v1
	v_sub_f32_e32 v22, 1.0, v59
	v_add_f32_e32 v26, 1.0, v59
	v_mul_f32_e32 v22, v22, v26
	v_add_f32_e32 v26, v28, v227
	v_mul_f32_e32 v26, 0xbfb8aa3b, v26
	v_exp_f32_e32 v26, v26
	v_sqrt_f32_e32 v58, v22
	v_mul_f32_e32 v22, v120, v23
	v_mul_f32_e32 v23, v56, v59
	v_add_f32_e32 v26, 1.0, v26
	v_rcp_f32_e32 v26, v26
	v_exp_f32_e32 v24, v24
	v_exp_f32_e32 v25, v25
	v_mul_f32_e32 v57, v122, v48
	v_mul_f32_e32 v26, v26, v229
	v_mul_f32_e32 v26, 0xbfb8aa3b, v26
	v_exp_f32_e32 v61, v26
	v_add_f32_e32 v24, 1.0, v24
	v_add_f32_e32 v25, 1.0, v25
	v_pk_mul_f32 v[64:65], v[56:57], v[0:1]
	v_sub_f32_e32 v26, 1.0, v61
	v_add_f32_e32 v27, 1.0, v61
	v_mul_f32_e32 v26, v26, v27
	v_sqrt_f32_e32 v60, v26
	v_add_f32_e32 v26, v29, v227
	v_mul_f32_e32 v26, 0xbfb8aa3b, v26
	v_exp_f32_e32 v26, v26
	v_mul_f32_e32 v23, v61, v23
	v_rcp_f32_e32 v24, v24
	v_rcp_f32_e32 v25, v25
	v_add_f32_e32 v26, 1.0, v26
	v_rcp_f32_e32 v26, v26
	v_pk_fma_f32 v[66:67], v[56:57], v[0:1], v[64:65] op_sel_hi:[1,1,0]
	v_mul_f32_e32 v24, v118, v24
	v_mul_f32_e32 v26, v26, v229
	v_mul_f32_e32 v26, 0xbfb8aa3b, v26
	v_exp_f32_e32 v63, v26
	s_nop 0
	v_mul_f32_e32 v29, v63, v23
	v_sub_f32_e32 v26, 1.0, v63
	v_add_f32_e32 v27, 1.0, v63
	v_mul_f32_e32 v26, v26, v27
	v_sqrt_f32_e32 v62, v26
	s_waitcnt lgkmcnt(0)
	v_mov_b32_e32 v249, v29
	v_mov_b32_e32 v42, v29
	s_nop 1
	v_permlane16_swap_b32_e32 v42, v249
	v_cndmask_b32_e64 v42, v249, v42, s[98:99]
	v_mul_f32_e32 v51, v29, v42
	v_cndmask_b32_e64 v46, v42, 1.0, s[50:51]
	v_mul_f32_e32 v26, v113, v25
	s_waitcnt lgkmcnt(0)
	v_mov_b32_e32 v249, v51
	v_mov_b32_e32 v53, v51
	s_nop 1
	v_permlane32_swap_b32_e32 v53, v249
	v_cndmask_b32_e64 v53, v249, v53, s[100:101]
	v_mul_f32_e32 v23, v46, v53
	v_cndmask_b32_e64 v40, v23, v46, s[52:53]
	v_mov_b32_e32 v23, v67
	v_pk_mul_f32 v[66:67], v[22:23], v[58:59]
	v_mul_f32_e32 v28, v51, v53
	v_pk_fma_f32 v[22:23], v[22:23], v[58:59], v[66:67] op_sel_hi:[1,1,0]
	s_nop 0
	v_mov_b32_e32 v25, v23
	v_pk_mul_f32 v[68:69], v[24:25], v[60:61]
	s_nop 0
	v_pk_fma_f32 v[22:23], v[24:25], v[60:61], v[68:69] op_sel_hi:[1,1,0]
	v_add_f32_e32 v69, v44, v45
	v_mov_b32_e32 v27, v23
	v_pk_mul_f32 v[70:71], v[26:27], v[62:63]
	s_nop 0
	v_add_f32_e32 v1, v70, v71
	v_add_f32_e32 v71, v36, v37
	s_waitcnt lgkmcnt(0)
	v_mov_b32_e32 v249, v1
	v_mov_b32_e32 v22, v1
	s_nop 1
	v_permlane16_swap_b32_e32 v22, v249
	v_cndmask_b32_e64 v22, v249, v22, s[98:99]
	v_cndmask_b32_e64 v23, v22, 0, s[50:51]
	v_fma_f32 v24, v29, v22, v1
	v_fmac_f32_e32 v22, v1, v42
	v_cndmask_b32_e64 v1, v24, v22, s[50:51]
	s_waitcnt lgkmcnt(0)
; #define LAS __attribute__((address_space(3)))
; #define MFMA16(a, b, c) __builtin_amdgcn_mfma_f32_16x16x32_bf16(a, b, c, 0, 0, 0)
; template <bool PHASE_B>
; __device__ __forceinline__ void lru_item(const Params& p, LAS unsigned char* lds, int ci, int ci_next, int jb, const int tid, v4u (&xvn)[3]) {
;     ...
; #pragma unroll
;         for (int ct = 0; ct < 4; ++ct) {
;             f32x4 ga = (f32x4){0.f, 0.f, 0.f, 0.f}, gx = (f32x4){0.f, 0.f, 0.f, 0.f};
; #pragma unroll
;             for (int ks = 0; ks < 2; ++ks) {
;                 const bf16x8 wa = *(const LAS bf16x8*)(lds + LR_WG + ((dir * 2 + 0) * 64 + 16 * ct + fr) * 144 + (32 * ks + 8 * fq) * 2);
;                 const bf16x8 wx = *(const LAS bf16x8*)(lds + LR_WG + ((dir * 2 + 1) * 64 + 16 * ct + fr) * 144 + (32 * ks + 8 * fq) * 2);
;                 ga = MFMA16(af[ks], wa, ga); gx = MFMA16(af[ks], wx, gx); }
;             const int ch = 16 * ct + fr; const float bav = GC[(dir * 3 + 0) * 64 + ch], bxv = GC[(dir * 3 + 1) * 64 + ch], c8 = GC[(dir * 3 + 2) * 64 + ch];
;             float Al = 1.f, Hl = 0.f;
; #pragma unroll
;             for (int ee = 0; ee < 4; ++ee) { const int e = dir ? 3 - ee : ee;
;                 const float r = __builtin_amdgcn_rcpf(1.f + __expf(-(ga[e] + bav))), ig = __builtin_amdgcn_rcpf(1.f + __expf(-(gx[e] + bxv)));
;                 const float la = -c8 * r; const float a = __expf(la); const float u = __builtin_amdgcn_sqrtf((1.f - a) * (1.f + a)) * (ig * xc[ct][e]);
;                 av[dir][ct][e] = a; uv[dir][ct][e] = u; Hl = a * Hl + u; Al *= a; }
;             const int o = dir ? 3 - fq : fq; const bool odd = (o & 1) != 0, hi2 = (o & 2) != 0;
;             const float A1 = __shfl_xor(Al, 16), H1 = __shfl_xor(Hl, 16);
;             const float pxA = odd ? A1 : 1.f, pxH = odd ? H1 : 0.f;
;             const float gA = Al * A1, gH = odd ? (Al * H1 + Hl) : (A1 * Hl + H1);
;             const float A2 = __shfl_xor(gA, 32), H2 = __shfl_xor(gH, 32);
;             const float PA = hi2 ? pxA * A2 : pxA, PH = hi2 ? (pxA * H2 + pxH) : pxH;
;             const float TA = gA * A2, TH = hi2 ? (gA * H2 + gH) : (A2 * gH + H2);
;             pA[dir][ct] = PA; pH[dir][ct] = PH;
;             ((LAS f32x2*)(lds + LR_SEG))[(dir * 8 + rt) * 64 + ch] = (f32x2){TA, TH};
	v_mov_b32_e32 v249, v1
	v_mov_b32_e32 v22, v1
	s_nop 1
	v_permlane32_swap_b32_e32 v22, v249
	v_cndmask_b32_e64 v22, v249, v22, s[100:101]
	v_fma_f32 v24, v46, v22, v23
	v_cndmask_b32_e64 v42, v24, v23, s[52:53]
	v_fma_f32 v23, v51, v22, v1
	v_fmac_f32_e32 v22, v1, v53
	v_cndmask_b32_e64 v29, v23, v22, s[52:53]
	ds_write_b64 v175, v[28:29] offset:58752
	s_waitcnt lgkmcnt(1)
	v_mfma_f32_16x16x32_bf16 v[22:25], v[14:17], v[208:211], 0
	s_waitcnt lgkmcnt(1)
	v_mfma_f32_16x16x32_bf16 v[26:29], v[14:17], v[212:215], 0
	s_waitcnt lgkmcnt(1)
	v_mfma_f32_16x16x32_bf16 v[80:83], v[18:21], v[216:219], v[22:25]
	s_waitcnt lgkmcnt(0)
	v_mfma_f32_16x16x32_bf16 v[22:25], v[18:21], v[220:223], v[26:29]
	ds_read_b32 v224, v174 offset:57216
	ds_read_b32 v225, v174 offset:57472
	ds_read_b32 v226, v174 offset:57728
	ds_read_b128 v[208:211], v132 offset:25856
	ds_read_b128 v[212:215], v132 offset:35072
	ds_read_b128 v[216:219], v132 offset:25920
	ds_read_b128 v[220:223], v132 offset:35136
	s_nop 3
	s_waitcnt lgkmcnt(2)
	v_add_f32_e32 v1, v80, v224
	v_mul_f32_e32 v1, 0xbfb8aa3b, v1
	v_exp_f32_e32 v1, v1
	s_waitcnt lgkmcnt(1)
	v_add_f32_e32 v22, v22, v225
	v_mul_f32_e32 v22, 0xbfb8aa3b, v22
	v_exp_f32_e32 v22, v22
	v_add_f32_e32 v1, 1.0, v1
	v_rcp_f32_e32 v1, v1
	v_add_f32_e32 v23, v23, v225
	v_add_f32_e32 v22, 1.0, v22
	v_rcp_f32_e32 v29, v22
	s_waitcnt lgkmcnt(0)
	v_mul_f32_e32 v1, v1, v226
	v_mul_f32_e32 v1, 0xbfb8aa3b, v1
	v_exp_f32_e32 v72, v1
	v_mul_f32_e32 v23, 0xbfb8aa3b, v23
	v_exp_f32_e32 v23, v23
	v_add_f32_e32 v24, v24, v225
	v_sub_f32_e32 v1, 1.0, v72
	v_add_f32_e32 v22, 1.0, v72
	v_mul_f32_e32 v1, v1, v22
	v_add_f32_e32 v22, v81, v224
	v_mul_f32_e32 v22, 0xbfb8aa3b, v22
	v_exp_f32_e32 v22, v22
	v_add_f32_e32 v23, 1.0, v23
	v_rcp_f32_e32 v23, v23
	v_add_f32_e32 v25, v25, v225
	v_add_f32_e32 v22, 1.0, v22
	v_rcp_f32_e32 v22, v22
	v_mul_f32_e32 v24, 0xbfb8aa3b, v24
	v_mul_f32_e32 v25, 0xbfb8aa3b, v25
	v_sqrt_f32_e32 v1, v1
	v_mul_f32_e32 v22, v22, v226
	v_mul_f32_e32 v22, 0xbfb8aa3b, v22
	v_exp_f32_e32 v75, v22
	v_exp_f32_e32 v24, v24
	v_exp_f32_e32 v25, v25
	v_mul_f32_e32 v73, v69, v29
	v_sub_f32_e32 v22, 1.0, v75
	v_add_f32_e32 v46, 1.0, v75
	v_mul_f32_e32 v22, v22, v46
	v_add_f32_e32 v46, v82, v224
	v_mul_f32_e32 v46, 0xbfb8aa3b, v46
	v_add_f32_e32 v26, v83, v224
	v_exp_f32_e32 v46, v46
	v_mul_f32_e32 v26, 0xbfb8aa3b, v26
	v_exp_f32_e32 v26, v26
	v_sqrt_f32_e32 v74, v22
	v_add_f32_e32 v46, 1.0, v46
	v_rcp_f32_e32 v46, v46
	v_add_f32_e32 v26, 1.0, v26
	v_rcp_f32_e32 v26, v26
	v_mul_f32_e32 v22, v130, v23
	v_mul_f32_e32 v46, v46, v226
	v_mul_f32_e32 v46, 0xbfb8aa3b, v46
	v_mul_f32_e32 v26, v26, v226
	v_exp_f32_e32 v77, v46
	v_mul_f32_e32 v26, 0xbfb8aa3b, v26
	v_exp_f32_e32 v79, v26
	v_mul_f32_e32 v23, v72, v75
	v_sub_f32_e32 v46, 1.0, v77
	v_add_f32_e32 v48, 1.0, v77
	v_mul_f32_e32 v23, v77, v23
	v_mul_f32_e32 v46, v46, v48
	v_mul_f32_e32 v48, v79, v23
	v_add_f32_e32 v24, 1.0, v24
	v_add_f32_e32 v25, 1.0, v25
	v_pk_mul_f32 v[44:45], v[72:73], v[0:1]
	v_rcp_f32_e32 v24, v24
	s_waitcnt lgkmcnt(0)
	v_mov_b32_e32 v249, v48
	v_mov_b32_e32 v51, v48
	s_nop 1
	v_permlane16_swap_b32_e32 v51, v249
	v_cndmask_b32_e64 v51, v249, v51, s[98:99]
	v_mul_f32_e32 v55, v48, v51
	v_cndmask_b32_e64 v53, v51, 1.0, s[50:51]
	v_rcp_f32_e32 v25, v25
	v_pk_fma_f32 v[80:81], v[72:73], v[0:1], v[44:45] op_sel_hi:[1,1,0]
	v_sqrt_f32_e32 v76, v46
	s_waitcnt lgkmcnt(0)
	v_mov_b32_e32 v249, v55
	v_mov_b32_e32 v57, v55
	s_nop 1
	v_permlane32_swap_b32_e32 v57, v249
	v_cndmask_b32_e64 v57, v249, v57, s[100:101]
	v_mul_f32_e32 v23, v53, v57
	v_cndmask_b32_e64 v46, v23, v53, s[52:53]
	v_mov_b32_e32 v23, v81
	v_sub_f32_e32 v26, 1.0, v79
	v_add_f32_e32 v27, 1.0, v79
	v_pk_mul_f32 v[80:81], v[22:23], v[74:75]
	v_mul_f32_e32 v26, v26, v27
	v_pk_fma_f32 v[22:23], v[22:23], v[74:75], v[80:81] op_sel_hi:[1,1,0]
	v_mul_f32_e32 v24, v128, v24
	v_sqrt_f32_e32 v78, v26
	v_mul_f32_e32 v26, v125, v25
	v_mov_b32_e32 v25, v23
	v_pk_mul_f32 v[82:83], v[24:25], v[76:77]
	v_mul_f32_e32 v28, v55, v57
	v_pk_fma_f32 v[22:23], v[24:25], v[76:77], v[82:83] op_sel_hi:[1,1,0]
	s_nop 0
	v_mov_b32_e32 v27, v23
	v_pk_mul_f32 v[84:85], v[26:27], v[78:79]
	s_nop 0
	v_add_f32_e32 v1, v84, v85
	s_waitcnt lgkmcnt(0)
	v_mov_b32_e32 v249, v1
	v_mov_b32_e32 v22, v1
	s_nop 1
	v_permlane16_swap_b32_e32 v22, v249
	v_cndmask_b32_e64 v22, v249, v22, s[98:99]
	v_cndmask_b32_e64 v23, v22, 0, s[50:51]
	v_fma_f32 v24, v48, v22, v1
	v_fmac_f32_e32 v22, v1, v51
	v_cndmask_b32_e64 v1, v24, v22, s[50:51]
	s_waitcnt lgkmcnt(0)
	v_mov_b32_e32 v249, v1
	v_mov_b32_e32 v22, v1
	s_nop 1
	v_permlane32_swap_b32_e32 v22, v249
	v_cndmask_b32_e64 v22, v249, v22, s[100:101]
	v_fma_f32 v24, v53, v22, v23
	v_cndmask_b32_e64 v44, v24, v23, s[52:53]
	v_fma_f32 v23, v55, v22, v1
	v_fmac_f32_e32 v22, v1, v57
	v_cndmask_b32_e64 v29, v23, v22, s[52:53]
	ds_write_b64 v175, v[28:29] offset:58880
	s_waitcnt lgkmcnt(1)
	v_mfma_f32_16x16x32_bf16 v[22:25], v[14:17], v[208:211], 0
	s_waitcnt lgkmcnt(1)
	v_mfma_f32_16x16x32_bf16 v[26:29], v[14:17], v[212:215], 0
	s_waitcnt lgkmcnt(1)
	v_mfma_f32_16x16x32_bf16 v[94:97], v[18:21], v[216:219], v[22:25]
	s_waitcnt lgkmcnt(0)
	v_mfma_f32_16x16x32_bf16 v[22:25], v[18:21], v[220:223], v[26:29]
	ds_read_b32 v227, v174 offset:57280
	ds_read_b32 v228, v174 offset:57536
	ds_read_b32 v229, v174 offset:57792
	ds_read_b128 v[208:211], v132 offset:37376
	ds_read_b128 v[212:215], v132 offset:46592
	ds_read_b128 v[216:219], v132 offset:37440
	ds_read_b128 v[220:223], v132 offset:46656
	s_nop 3
	s_waitcnt lgkmcnt(2)
	v_add_f32_e32 v1, v94, v227
	v_mul_f32_e32 v1, 0xbfb8aa3b, v1
	v_exp_f32_e32 v1, v1
	s_waitcnt lgkmcnt(1)
; #define LAS __attribute__((address_space(3)))
; #define MFMA16(a, b, c) __builtin_amdgcn_mfma_f32_16x16x32_bf16(a, b, c, 0, 0, 0)
; template <bool PHASE_B>
; __device__ __forceinline__ void lru_item(const Params& p, LAS unsigned char* lds, int ci, int ci_next, int jb, const int tid, v4u (&xvn)[3]) {
;     ...
; #pragma unroll
;         for (int ct = 0; ct < 4; ++ct) {
;             f32x4 ga = (f32x4){0.f, 0.f, 0.f, 0.f}, gx = (f32x4){0.f, 0.f, 0.f, 0.f};
; #pragma unroll
;             for (int ks = 0; ks < 2; ++ks) {
;                 const bf16x8 wa = *(const LAS bf16x8*)(lds + LR_WG + ((dir * 2 + 0) * 64 + 16 * ct + fr) * 144 + (32 * ks + 8 * fq) * 2);
;                 const bf16x8 wx = *(const LAS bf16x8*)(lds + LR_WG + ((dir * 2 + 1) * 64 + 16 * ct + fr) * 144 + (32 * ks + 8 * fq) * 2);
;                 ga = MFMA16(af[ks], wa, ga); gx = MFMA16(af[ks], wx, gx); }
;             const int ch = 16 * ct + fr; const float bav = GC[(dir * 3 + 0) * 64 + ch], bxv = GC[(dir * 3 + 1) * 64 + ch], c8 = GC[(dir * 3 + 2) * 64 + ch];
;             float Al = 1.f, Hl = 0.f;
; #pragma unroll
;             for (int ee = 0; ee < 4; ++ee) { const int e = dir ? 3 - ee : ee;
;                 const float r = __builtin_amdgcn_rcpf(1.f + __expf(-(ga[e] + bav))), ig = __builtin_amdgcn_rcpf(1.f + __expf(-(gx[e] + bxv)));
;                 const float la = -c8 * r; const float a = __expf(la); const float u = __builtin_amdgcn_sqrtf((1.f - a) * (1.f + a)) * (ig * xc[ct][e]);
;                 av[dir][ct][e] = a; uv[dir][ct][e] = u; Hl = a * Hl + u; Al *= a; }
;             const int o = dir ? 3 - fq : fq; const bool odd = (o & 1) != 0, hi2 = (o & 2) != 0;
;             const float A1 = __shfl_xor(Al, 16), H1 = __shfl_xor(Hl, 16);
;             const float pxA = odd ? A1 : 1.f, pxH = odd ? H1 : 0.f;
;             const float gA = Al * A1, gH = odd ? (Al * H1 + Hl) : (A1 * Hl + H1);
;             const float A2 = __shfl_xor(gA, 32), H2 = __shfl_xor(gH, 32);
;             const float PA = hi2 ? pxA * A2 : pxA, PH = hi2 ? (pxA * H2 + pxH) : pxH;
;             const float TA = gA * A2, TH = hi2 ? (gA * H2 + gH) : (A2 * gH + H2);
;             pA[dir][ct] = PA; pH[dir][ct] = PH;
;             ((LAS f32x2*)(lds + LR_SEG))[(dir * 8 + rt) * 64 + ch] = (f32x2){TA, TH};
	v_add_f32_e32 v22, v22, v228
	v_mul_f32_e32 v22, 0xbfb8aa3b, v22
	v_exp_f32_e32 v22, v22
	v_add_f32_e32 v1, 1.0, v1
	v_rcp_f32_e32 v1, v1
	v_add_f32_e32 v23, v23, v228
	v_add_f32_e32 v22, 1.0, v22
	v_rcp_f32_e32 v29, v22
	s_waitcnt lgkmcnt(0)
	v_mul_f32_e32 v1, v1, v229
	v_mul_f32_e32 v1, 0xbfb8aa3b, v1
	v_exp_f32_e32 v86, v1
	v_mul_f32_e32 v23, 0xbfb8aa3b, v23
	v_exp_f32_e32 v23, v23
	v_add_f32_e32 v24, v24, v228
	v_sub_f32_e32 v1, 1.0, v86
	v_add_f32_e32 v22, 1.0, v86
	v_mul_f32_e32 v1, v1, v22
	v_add_f32_e32 v22, v95, v227
	v_mul_f32_e32 v22, 0xbfb8aa3b, v22
	v_exp_f32_e32 v22, v22
	v_add_f32_e32 v23, 1.0, v23
	v_rcp_f32_e32 v23, v23
	v_add_f32_e32 v25, v25, v228
	v_add_f32_e32 v22, 1.0, v22
	v_rcp_f32_e32 v22, v22
	v_mul_f32_e32 v24, 0xbfb8aa3b, v24
	v_mul_f32_e32 v25, 0xbfb8aa3b, v25
	v_sqrt_f32_e32 v1, v1
	v_mul_f32_e32 v22, v22, v229
	v_mul_f32_e32 v22, 0xbfb8aa3b, v22
	v_exp_f32_e32 v89, v22
	v_exp_f32_e32 v24, v24
	v_exp_f32_e32 v25, v25
	v_mul_f32_e32 v87, v71, v29
	v_sub_f32_e32 v22, 1.0, v89
	v_add_f32_e32 v48, 1.0, v89
	v_mul_f32_e32 v22, v22, v48
	v_add_f32_e32 v48, v96, v227
	v_mul_f32_e32 v48, 0xbfb8aa3b, v48
	v_add_f32_e32 v26, v97, v227
	v_exp_f32_e32 v48, v48
	v_mul_f32_e32 v26, 0xbfb8aa3b, v26
	v_exp_f32_e32 v26, v26
	v_sqrt_f32_e32 v88, v22
	v_add_f32_e32 v48, 1.0, v48
	v_rcp_f32_e32 v48, v48
	v_add_f32_e32 v26, 1.0, v26
	v_rcp_f32_e32 v26, v26
	v_mul_f32_e32 v22, v31, v23
	v_mul_f32_e32 v48, v48, v229
	v_mul_f32_e32 v48, 0xbfb8aa3b, v48
	v_mul_f32_e32 v26, v26, v229
	v_exp_f32_e32 v91, v48
	v_mul_f32_e32 v26, 0xbfb8aa3b, v26
	v_exp_f32_e32 v93, v26
	v_mul_f32_e32 v23, v86, v89
	v_sub_f32_e32 v48, 1.0, v91
	v_add_f32_e32 v51, 1.0, v91
	v_mul_f32_e32 v23, v91, v23
	v_mul_f32_e32 v48, v48, v51
	v_mul_f32_e32 v51, v93, v23
	v_add_f32_e32 v24, 1.0, v24
	v_add_f32_e32 v25, 1.0, v25
	v_pk_mul_f32 v[36:37], v[86:87], v[0:1]
	v_rcp_f32_e32 v24, v24
	s_waitcnt lgkmcnt(0)
	v_mov_b32_e32 v249, v51
	v_mov_b32_e32 v53, v51
	s_nop 1
	v_permlane16_swap_b32_e32 v53, v249
	v_cndmask_b32_e64 v53, v249, v53, s[98:99]
	v_mul_f32_e32 v57, v51, v53
	v_cndmask_b32_e64 v55, v53, 1.0, s[50:51]
	v_rcp_f32_e32 v25, v25
	v_pk_fma_f32 v[94:95], v[86:87], v[0:1], v[36:37] op_sel_hi:[1,1,0]
	v_sqrt_f32_e32 v90, v48
	s_waitcnt lgkmcnt(0)
	v_mov_b32_e32 v249, v57
	v_mov_b32_e32 v58, v57
	s_nop 1
	v_permlane32_swap_b32_e32 v58, v249
	v_cndmask_b32_e64 v58, v249, v58, s[100:101]
	v_mul_f32_e32 v23, v55, v58
	v_cndmask_b32_e64 v48, v23, v55, s[52:53]
	v_mov_b32_e32 v23, v95
	v_sub_f32_e32 v26, 1.0, v93
	v_add_f32_e32 v27, 1.0, v93
	v_pk_mul_f32 v[94:95], v[22:23], v[88:89]
	v_mul_f32_e32 v26, v26, v27
	v_pk_fma_f32 v[22:23], v[22:23], v[88:89], v[94:95] op_sel_hi:[1,1,0]
	v_mul_f32_e32 v24, v136, v24
	v_sqrt_f32_e32 v92, v26
	v_mul_f32_e32 v26, v133, v25
	v_mov_b32_e32 v25, v23
	v_pk_mul_f32 v[96:97], v[24:25], v[90:91]
	v_mul_f32_e32 v28, v57, v58
	v_pk_fma_f32 v[22:23], v[24:25], v[90:91], v[96:97] op_sel_hi:[1,1,0]
	s_nop 0
	v_mov_b32_e32 v27, v23
	v_pk_mul_f32 v[98:99], v[26:27], v[92:93]
	s_nop 0
	v_add_f32_e32 v1, v98, v99
	s_waitcnt lgkmcnt(0)
	v_mov_b32_e32 v249, v1
	v_mov_b32_e32 v22, v1
	s_nop 1
	v_permlane16_swap_b32_e32 v22, v249
	v_cndmask_b32_e64 v22, v249, v22, s[98:99]
	v_cndmask_b32_e64 v23, v22, 0, s[50:51]
	v_fma_f32 v24, v51, v22, v1
	v_fmac_f32_e32 v22, v1, v53
	v_cndmask_b32_e64 v1, v24, v22, s[50:51]
	s_waitcnt lgkmcnt(0)
	v_mov_b32_e32 v249, v1
	v_mov_b32_e32 v22, v1
	s_nop 1
	v_permlane32_swap_b32_e32 v22, v249
	v_cndmask_b32_e64 v22, v249, v22, s[100:101]
	v_fma_f32 v24, v55, v22, v23
	v_cndmask_b32_e64 v36, v24, v23, s[52:53]
	v_fma_f32 v23, v57, v22, v1
	v_fmac_f32_e32 v22, v1, v58
	v_cndmask_b32_e64 v29, v23, v22, s[52:53]
	ds_write_b64 v175, v[28:29] offset:59008
	s_waitcnt lgkmcnt(1)
	v_mfma_f32_16x16x32_bf16 v[22:25], v[14:17], v[208:211], 0
	s_waitcnt lgkmcnt(0)
	v_mfma_f32_16x16x32_bf16 v[102:105], v[14:17], v[212:215], 0
	ds_read_b32 v55, v174 offset:57856
	ds_read_b32 v57, v174 offset:58112
	ds_read_b32 v58, v174 offset:58368
	s_waitcnt lgkmcnt(4)
	v_mfma_f32_16x16x32_bf16 v[26:29], v[18:21], v[216:219], v[22:25]
	s_waitcnt lgkmcnt(3)
	v_mfma_f32_16x16x32_bf16 v[22:25], v[18:21], v[220:223], v[102:105]
	ds_read_b32 v246, v174 offset:57920
	ds_read_b32 v247, v174 offset:58176
	ds_read_b32 v248, v174 offset:58432
	ds_read_b128 v[208:211], v132 offset:39680
	ds_read_b128 v[212:215], v132 offset:48896
	ds_read_b128 v[216:219], v132 offset:39744
	ds_read_b128 v[220:223], v132 offset:48960
	s_waitcnt lgkmcnt(2)
	s_nop 4
	v_add_f32_e32 v1, v29, v55
	v_mul_f32_e32 v1, 0xbfb8aa3b, v1
	v_exp_f32_e32 v1, v1
	s_nop 0
	v_add_f32_e32 v1, 1.0, v1
	v_rcp_f32_e32 v1, v1
	s_waitcnt lgkmcnt(1)
	v_add_f32_e32 v25, v25, v57
	v_mul_f32_e32 v25, 0xbfb8aa3b, v25
	v_exp_f32_e32 v25, v25
	s_waitcnt lgkmcnt(0)
; #define LAS __attribute__((address_space(3)))
; #define MFMA16(a, b, c) __builtin_amdgcn_mfma_f32_16x16x32_bf16(a, b, c, 0, 0, 0)
; template <bool PHASE_B>
; __device__ __forceinline__ void lru_item(const Params& p, LAS unsigned char* lds, int ci, int ci_next, int jb, const int tid, v4u (&xvn)[3]) {
;     ...
; #pragma unroll
;         for (int ct = 0; ct < 4; ++ct) {
;             f32x4 ga = (f32x4){0.f, 0.f, 0.f, 0.f}, gx = (f32x4){0.f, 0.f, 0.f, 0.f};
; #pragma unroll
;             for (int ks = 0; ks < 2; ++ks) {
;                 const bf16x8 wa = *(const LAS bf16x8*)(lds + LR_WG + ((dir * 2 + 0) * 64 + 16 * ct + fr) * 144 + (32 * ks + 8 * fq) * 2);
;                 const bf16x8 wx = *(const LAS bf16x8*)(lds + LR_WG + ((dir * 2 + 1) * 64 + 16 * ct + fr) * 144 + (32 * ks + 8 * fq) * 2);
;                 ga = MFMA16(af[ks], wa, ga); gx = MFMA16(af[ks], wx, gx); }
;             const int ch = 16 * ct + fr; const float bav = GC[(dir * 3 + 0) * 64 + ch], bxv = GC[(dir * 3 + 1) * 64 + ch], c8 = GC[(dir * 3 + 2) * 64 + ch];
;             float Al = 1.f, Hl = 0.f;
; #pragma unroll
;             for (int ee = 0; ee < 4; ++ee) { const int e = dir ? 3 - ee : ee;
;                 const float r = __builtin_amdgcn_rcpf(1.f + __expf(-(ga[e] + bav))), ig = __builtin_amdgcn_rcpf(1.f + __expf(-(gx[e] + bxv)));
;                 const float la = -c8 * r; const float a = __expf(la); const float u = __builtin_amdgcn_sqrtf((1.f - a) * (1.f + a)) * (ig * xc[ct][e]);
;                 av[dir][ct][e] = a; uv[dir][ct][e] = u; Hl = a * Hl + u; Al *= a; }
;             const int o = dir ? 3 - fq : fq; const bool odd = (o & 1) != 0, hi2 = (o & 2) != 0;
;             const float A1 = __shfl_xor(Al, 16), H1 = __shfl_xor(Hl, 16);
;             const float pxA = odd ? A1 : 1.f, pxH = odd ? H1 : 0.f;
;             const float gA = Al * A1, gH = odd ? (Al * H1 + Hl) : (A1 * Hl + H1);
;             const float A2 = __shfl_xor(gA, 32), H2 = __shfl_xor(gH, 32);
;             const float PA = hi2 ? pxA * A2 : pxA, PH = hi2 ? (pxA * H2 + pxH) : pxH;
;             const float TA = gA * A2, TH = hi2 ? (gA * H2 + gH) : (A2 * gH + H2);
;             pA[dir][ct] = PA; pH[dir][ct] = PH;
;             ((LAS f32x2*)(lds + LR_SEG))[(dir * 8 + rt) * 64 + ch] = (f32x2){TA, TH};
	v_mul_f32_e32 v1, v1, v58
	v_mul_f32_e32 v1, 0xbfb8aa3b, v1
	v_exp_f32_e32 v100, v1
	v_add_f32_e32 v25, 1.0, v25
	v_rcp_f32_e32 v25, v25
	v_add_f32_e32 v23, v23, v57
	v_sub_f32_e32 v1, 1.0, v100
	v_add_f32_e32 v29, 1.0, v100
	v_mul_f32_e32 v1, v1, v29
	v_sqrt_f32_e32 v1, v1
	v_mul_f32_e32 v101, v101, v25
	v_mul_f32_e32 v23, 0xbfb8aa3b, v23
	v_exp_f32_e32 v23, v23
	v_pk_mul_f32 v[102:103], v[100:101], v[0:1]
	v_add_f32_e32 v24, v24, v57
	v_pk_fma_f32 v[114:115], v[100:101], v[0:1], v[102:103] op_sel_hi:[1,1,0]
	v_add_f32_e32 v1, v28, v55
	v_mul_f32_e32 v1, 0xbfb8aa3b, v1
	v_exp_f32_e32 v1, v1
	v_add_f32_e32 v23, 1.0, v23
	v_rcp_f32_e32 v23, v23
	v_mul_f32_e32 v24, 0xbfb8aa3b, v24
	v_add_f32_e32 v1, 1.0, v1
	v_rcp_f32_e32 v1, v1
	v_mul_f32_e32 v23, v108, v23
	v_exp_f32_e32 v24, v24
	v_add_f32_e32 v22, v22, v57
	v_mul_f32_e32 v1, v1, v58
	v_mul_f32_e32 v1, 0xbfb8aa3b, v1
	v_exp_f32_e32 v105, v1
	v_mul_f32_e32 v22, 0xbfb8aa3b, v22
	v_add_f32_e32 v24, 1.0, v24
	v_exp_f32_e32 v22, v22
	v_sub_f32_e32 v1, 1.0, v105
	v_add_f32_e32 v25, 1.0, v105
	v_mul_f32_e32 v1, v1, v25
	v_add_f32_e32 v25, v27, v55
	v_mul_f32_e32 v25, 0xbfb8aa3b, v25
	v_exp_f32_e32 v25, v25
	v_rcp_f32_e32 v24, v24
	v_sqrt_f32_e32 v104, v1
	v_add_f32_e32 v22, 1.0, v22
	v_add_f32_e32 v25, 1.0, v25
	v_rcp_f32_e32 v25, v25
	v_mul_f32_e32 v114, v106, v24
	v_rcp_f32_e32 v22, v22
	v_pk_mul_f32 v[106:107], v[114:115], v[104:105]
	v_mul_f32_e32 v25, v25, v58
	v_mul_f32_e32 v25, 0xbfb8aa3b, v25
	v_exp_f32_e32 v51, v25
	v_add_f32_e32 v1, v106, v107
	v_mul_f32_e32 v24, v100, v105
	v_mul_f32_e32 v22, v110, v22
	v_sub_f32_e32 v25, 1.0, v51
	v_add_f32_e32 v27, 1.0, v51
	v_mul_f32_e32 v25, v25, v27
	v_sqrt_f32_e32 v25, v25
	v_mul_f32_e32 v1, v51, v1
	v_mul_f32_e32 v24, v51, v24
	v_mul_f32_e32 v53, v23, v25
	v_add_f32_e32 v23, v26, v55
	v_mul_f32_e32 v23, 0xbfb8aa3b, v23
	v_exp_f32_e32 v23, v23
	s_nop 0
	v_add_f32_e32 v23, 1.0, v23
	v_rcp_f32_e32 v23, v23
	s_nop 0
	v_mul_f32_e32 v23, v23, v58
	v_mul_f32_e32 v23, 0xbfb8aa3b, v23
	v_exp_f32_e32 v109, v23
	s_nop 0
	v_sub_f32_e32 v23, 1.0, v109
	v_add_f32_e32 v25, 1.0, v109
	v_mul_f32_e32 v23, v23, v25
	v_sqrt_f32_e32 v108, v23
	v_add_f32_e32 v23, v1, v53
	v_pk_mul_f32 v[110:111], v[22:23], v[108:109]
	s_nop 0
	v_add_f32_e32 v1, v110, v111
	v_mul_f32_e32 v22, v109, v24
	s_waitcnt lgkmcnt(0)
	v_mov_b32_e32 v249, v22
	v_mov_b32_e32 v23, v22
	s_nop 1
	v_permlane16_swap_b32_e32 v23, v249
	v_cndmask_b32_e64 v23, v249, v23, s[98:99]
	v_mul_f32_e32 v27, v22, v23
	s_waitcnt lgkmcnt(0)
	v_mov_b32_e32 v249, v1
	v_mov_b32_e32 v24, v1
	s_nop 1
	v_permlane16_swap_b32_e32 v24, v249
	v_cndmask_b32_e64 v24, v249, v24, s[98:99]
	v_cndmask_b32_e64 v26, v24, 0, s[54:55]
	v_fma_f32 v22, v22, v24, v1
	v_fmac_f32_e32 v24, v1, v23
	v_cndmask_b32_e64 v25, v23, 1.0, s[54:55]
	v_cndmask_b32_e64 v1, v22, v24, s[54:55]
	s_waitcnt lgkmcnt(0)
	v_mov_b32_e32 v249, v27
	v_mov_b32_e32 v23, v27
	s_nop 1
	v_permlane32_swap_b32_e32 v23, v249
	v_cndmask_b32_e64 v23, v249, v23, s[100:101]
	v_mul_f32_e32 v22, v25, v23
	v_cndmask_b32_e64 v55, v22, v25, s[56:57]
	s_waitcnt lgkmcnt(0)
	v_mov_b32_e32 v249, v1
	v_mov_b32_e32 v24, v1
	s_nop 1
	v_permlane32_swap_b32_e32 v24, v249
	v_cndmask_b32_e64 v24, v249, v24, s[100:101]
	v_fma_f32 v22, v25, v24, v26
	v_fma_f32 v25, v27, v24, v1
	v_fmac_f32_e32 v24, v1, v23
	v_cndmask_b32_e64 v57, v22, v26, s[56:57]
	v_mul_f32_e32 v22, v27, v23
	v_cndmask_b32_e64 v23, v25, v24, s[56:57]
	ds_write_b64 v175, v[22:23] offset:62720
	s_waitcnt lgkmcnt(1)
	v_mfma_f32_16x16x32_bf16 v[22:25], v[14:17], v[208:211], 0
	s_waitcnt lgkmcnt(0)
	v_mfma_f32_16x16x32_bf16 v[114:117], v[14:17], v[212:215], 0
	s_waitcnt lgkmcnt(1)
	v_mfma_f32_16x16x32_bf16 v[26:29], v[18:21], v[216:219], v[22:25]
	s_waitcnt lgkmcnt(1)
	v_mfma_f32_16x16x32_bf16 v[22:25], v[18:21], v[220:223], v[114:117]
	ds_read_b32 v224, v174 offset:57984
	ds_read_b32 v225, v174 offset:58240
	ds_read_b32 v226, v174 offset:58496
	ds_read_b128 v[208:211], v132 offset:41984
	ds_read_b128 v[212:215], v132 offset:51200
	ds_read_b128 v[216:219], v132 offset:42048
	ds_read_b128 v[220:223], v132 offset:51264
	s_waitcnt lgkmcnt(2)
	s_nop 4
	v_add_f32_e32 v1, v29, v246
	v_mul_f32_e32 v1, 0xbfb8aa3b, v1
	v_exp_f32_e32 v1, v1
	s_nop 0
	v_add_f32_e32 v1, 1.0, v1
	v_rcp_f32_e32 v1, v1
	s_waitcnt lgkmcnt(1)
	v_add_f32_e32 v25, v25, v247
	v_mul_f32_e32 v25, 0xbfb8aa3b, v25
	v_exp_f32_e32 v25, v25
	s_waitcnt lgkmcnt(0)
	v_mul_f32_e32 v1, v1, v248
	v_mul_f32_e32 v1, 0xbfb8aa3b, v1
	v_exp_f32_e32 v112, v1
	v_add_f32_e32 v25, 1.0, v25
	v_rcp_f32_e32 v25, v25
	v_add_f32_e32 v23, v23, v247
	v_sub_f32_e32 v1, 1.0, v112
	v_add_f32_e32 v29, 1.0, v112
	v_mul_f32_e32 v1, v1, v29
	v_sqrt_f32_e32 v1, v1
	v_mul_f32_e32 v113, v113, v25
	v_mul_f32_e32 v23, 0xbfb8aa3b, v23
	v_exp_f32_e32 v23, v23
	v_pk_mul_f32 v[114:115], v[112:113], v[0:1]
	v_add_f32_e32 v24, v24, v247
	v_pk_fma_f32 v[126:127], v[112:113], v[0:1], v[114:115] op_sel_hi:[1,1,0]
	v_add_f32_e32 v1, v28, v246
	v_mul_f32_e32 v1, 0xbfb8aa3b, v1
	v_exp_f32_e32 v1, v1
	v_add_f32_e32 v23, 1.0, v23
	v_rcp_f32_e32 v23, v23
	v_mul_f32_e32 v24, 0xbfb8aa3b, v24
	v_add_f32_e32 v1, 1.0, v1
	v_rcp_f32_e32 v1, v1
	v_mul_f32_e32 v23, v120, v23
	v_exp_f32_e32 v24, v24
	v_add_f32_e32 v22, v22, v247
	v_mul_f32_e32 v1, v1, v248
	v_mul_f32_e32 v1, 0xbfb8aa3b, v1
	v_exp_f32_e32 v117, v1
	v_mul_f32_e32 v22, 0xbfb8aa3b, v22
	v_add_f32_e32 v24, 1.0, v24
	v_exp_f32_e32 v22, v22
	v_sub_f32_e32 v1, 1.0, v117
	v_add_f32_e32 v25, 1.0, v117
	v_mul_f32_e32 v1, v1, v25
	v_add_f32_e32 v25, v27, v246
	v_mul_f32_e32 v25, 0xbfb8aa3b, v25
	v_exp_f32_e32 v25, v25
	v_rcp_f32_e32 v24, v24
	v_sqrt_f32_e32 v116, v1
	v_add_f32_e32 v22, 1.0, v22
	v_add_f32_e32 v25, 1.0, v25
	v_rcp_f32_e32 v25, v25
	v_mul_f32_e32 v126, v118, v24
	v_rcp_f32_e32 v22, v22
	v_pk_mul_f32 v[118:119], v[126:127], v[116:117]
	v_mul_f32_e32 v25, v25, v248
	v_mul_f32_e32 v25, 0xbfb8aa3b, v25
	v_exp_f32_e32 v58, v25
	v_add_f32_e32 v1, v118, v119
	v_mul_f32_e32 v24, v112, v117
	v_mul_f32_e32 v22, v122, v22
	v_sub_f32_e32 v25, 1.0, v58
	v_add_f32_e32 v27, 1.0, v58
	v_mul_f32_e32 v25, v25, v27
	v_sqrt_f32_e32 v25, v25
	v_mul_f32_e32 v1, v58, v1
	v_mul_f32_e32 v24, v58, v24
	v_mul_f32_e32 v60, v23, v25
	v_add_f32_e32 v23, v26, v246
	v_mul_f32_e32 v23, 0xbfb8aa3b, v23
	v_exp_f32_e32 v23, v23
	s_nop 0
	v_add_f32_e32 v23, 1.0, v23
	v_rcp_f32_e32 v23, v23
	s_nop 0
	v_mul_f32_e32 v23, v23, v248
	v_mul_f32_e32 v23, 0xbfb8aa3b, v23
	v_exp_f32_e32 v121, v23
	s_nop 0
	v_sub_f32_e32 v23, 1.0, v121
	v_add_f32_e32 v25, 1.0, v121
	v_mul_f32_e32 v23, v23, v25
	v_sqrt_f32_e32 v120, v23
	v_add_f32_e32 v23, v1, v60
	v_pk_mul_f32 v[122:123], v[22:23], v[120:121]
	s_nop 0
	v_add_f32_e32 v1, v122, v123
	v_mul_f32_e32 v22, v121, v24
	s_waitcnt lgkmcnt(0)
; #define LAS __attribute__((address_space(3)))
; #define MFMA16(a, b, c) __builtin_amdgcn_mfma_f32_16x16x32_bf16(a, b, c, 0, 0, 0)
; template <bool PHASE_B>
; __device__ __forceinline__ void lru_item(const Params& p, LAS unsigned char* lds, int ci, int ci_next, int jb, const int tid, v4u (&xvn)[3]) {
;     ...
; #pragma unroll
;         for (int ct = 0; ct < 4; ++ct) {
;             f32x4 ga = (f32x4){0.f, 0.f, 0.f, 0.f}, gx = (f32x4){0.f, 0.f, 0.f, 0.f};
; #pragma unroll
;             for (int ks = 0; ks < 2; ++ks) {
;                 const bf16x8 wa = *(const LAS bf16x8*)(lds + LR_WG + ((dir * 2 + 0) * 64 + 16 * ct + fr) * 144 + (32 * ks + 8 * fq) * 2);
;                 const bf16x8 wx = *(const LAS bf16x8*)(lds + LR_WG + ((dir * 2 + 1) * 64 + 16 * ct + fr) * 144 + (32 * ks + 8 * fq) * 2);
;                 ga = MFMA16(af[ks], wa, ga); gx = MFMA16(af[ks], wx, gx); }
;             const int ch = 16 * ct + fr; const float bav = GC[(dir * 3 + 0) * 64 + ch], bxv = GC[(dir * 3 + 1) * 64 + ch], c8 = GC[(dir * 3 + 2) * 64 + ch];
;             float Al = 1.f, Hl = 0.f;
; #pragma unroll
;             for (int ee = 0; ee < 4; ++ee) { const int e = dir ? 3 - ee : ee;
;                 const float r = __builtin_amdgcn_rcpf(1.f + __expf(-(ga[e] + bav))), ig = __builtin_amdgcn_rcpf(1.f + __expf(-(gx[e] + bxv)));
;                 const float la = -c8 * r; const float a = __expf(la); const float u = __builtin_amdgcn_sqrtf((1.f - a) * (1.f + a)) * (ig * xc[ct][e]);
;                 av[dir][ct][e] = a; uv[dir][ct][e] = u; Hl = a * Hl + u; Al *= a; }
;             const int o = dir ? 3 - fq : fq; const bool odd = (o & 1) != 0, hi2 = (o & 2) != 0;
;             const float A1 = __shfl_xor(Al, 16), H1 = __shfl_xor(Hl, 16);
;             const float pxA = odd ? A1 : 1.f, pxH = odd ? H1 : 0.f;
;             const float gA = Al * A1, gH = odd ? (Al * H1 + Hl) : (A1 * Hl + H1);
;             const float A2 = __shfl_xor(gA, 32), H2 = __shfl_xor(gH, 32);
;             const float PA = hi2 ? pxA * A2 : pxA, PH = hi2 ? (pxA * H2 + pxH) : pxH;
;             const float TA = gA * A2, TH = hi2 ? (gA * H2 + gH) : (A2 * gH + H2);
;             pA[dir][ct] = PA; pH[dir][ct] = PH;
;             ((LAS f32x2*)(lds + LR_SEG))[(dir * 8 + rt) * 64 + ch] = (f32x2){TA, TH};
	v_mov_b32_e32 v249, v22
	v_mov_b32_e32 v23, v22
	s_nop 1
	v_permlane16_swap_b32_e32 v23, v249
	v_cndmask_b32_e64 v23, v249, v23, s[98:99]
	v_mul_f32_e32 v27, v22, v23
	s_waitcnt lgkmcnt(0)
	v_mov_b32_e32 v249, v1
	v_mov_b32_e32 v24, v1
	s_nop 1
	v_permlane16_swap_b32_e32 v24, v249
	v_cndmask_b32_e64 v24, v249, v24, s[98:99]
	v_cndmask_b32_e64 v26, v24, 0, s[54:55]
	v_fma_f32 v22, v22, v24, v1
	v_fmac_f32_e32 v24, v1, v23
	v_cndmask_b32_e64 v25, v23, 1.0, s[54:55]
	v_cndmask_b32_e64 v1, v22, v24, s[54:55]
	s_waitcnt lgkmcnt(0)
	v_mov_b32_e32 v249, v27
	v_mov_b32_e32 v23, v27
	s_nop 1
	v_permlane32_swap_b32_e32 v23, v249
	v_cndmask_b32_e64 v23, v249, v23, s[100:101]
	v_mul_f32_e32 v22, v25, v23
	v_cndmask_b32_e64 v62, v22, v25, s[56:57]
	s_waitcnt lgkmcnt(0)
	v_mov_b32_e32 v249, v1
	v_mov_b32_e32 v24, v1
	s_nop 1
	v_permlane32_swap_b32_e32 v24, v249
	v_cndmask_b32_e64 v24, v249, v24, s[100:101]
	v_fma_f32 v22, v25, v24, v26
	v_fma_f32 v25, v27, v24, v1
	v_fmac_f32_e32 v24, v1, v23
	v_cndmask_b32_e64 v64, v22, v26, s[56:57]
	v_mul_f32_e32 v22, v27, v23
	v_cndmask_b32_e64 v23, v25, v24, s[56:57]
	ds_write_b64 v175, v[22:23] offset:62848
	s_waitcnt lgkmcnt(1)
	v_mfma_f32_16x16x32_bf16 v[22:25], v[14:17], v[208:211], 0
	s_waitcnt lgkmcnt(0)
	v_mfma_f32_16x16x32_bf16 v[138:141], v[14:17], v[212:215], 0
	s_waitcnt lgkmcnt(1)
	v_mfma_f32_16x16x32_bf16 v[26:29], v[18:21], v[216:219], v[22:25]
	s_waitcnt lgkmcnt(1)
	v_mfma_f32_16x16x32_bf16 v[22:25], v[18:21], v[220:223], v[138:141]
	ds_read_b32 v227, v174 offset:58048
	ds_read_b32 v228, v174 offset:58304
	ds_read_b32 v229, v174 offset:58560
	ds_read_b128 v[208:211], v132 offset:44288
	ds_read_b128 v[212:215], v132 offset:53504
	ds_read_b128 v[216:219], v132 offset:44352
	ds_read_b128 v[220:223], v132 offset:53568
	s_waitcnt lgkmcnt(2)
	s_nop 4
	v_add_f32_e32 v1, v29, v224
	v_mul_f32_e32 v1, 0xbfb8aa3b, v1
	v_exp_f32_e32 v1, v1
	s_nop 0
	v_add_f32_e32 v1, 1.0, v1
	v_rcp_f32_e32 v1, v1
	s_waitcnt lgkmcnt(1)
	v_add_f32_e32 v25, v25, v225
	v_mul_f32_e32 v25, 0xbfb8aa3b, v25
	v_exp_f32_e32 v25, v25
	s_waitcnt lgkmcnt(0)
	v_mul_f32_e32 v1, v1, v226
	v_mul_f32_e32 v1, 0xbfb8aa3b, v1
	v_exp_f32_e32 v124, v1
	v_add_f32_e32 v25, 1.0, v25
	v_rcp_f32_e32 v25, v25
	v_add_f32_e32 v24, v24, v225
	v_sub_f32_e32 v1, 1.0, v124
	v_add_f32_e32 v29, 1.0, v124
	v_mul_f32_e32 v1, v1, v29
	v_sqrt_f32_e32 v1, v1
	v_mul_f32_e32 v125, v125, v25
	v_mul_f32_e32 v24, 0xbfb8aa3b, v24
	v_exp_f32_e32 v24, v24
	v_pk_mul_f32 v[126:127], v[124:125], v[0:1]
	v_add_f32_e32 v23, v23, v225
	v_pk_fma_f32 v[134:135], v[124:125], v[0:1], v[126:127] op_sel_hi:[1,1,0]
	v_add_f32_e32 v1, v28, v224
	v_mul_f32_e32 v1, 0xbfb8aa3b, v1
	v_exp_f32_e32 v1, v1
	v_add_f32_e32 v24, 1.0, v24
	v_rcp_f32_e32 v24, v24
	v_mul_f32_e32 v23, 0xbfb8aa3b, v23
	v_add_f32_e32 v1, 1.0, v1
	v_rcp_f32_e32 v1, v1
	v_mul_f32_e32 v134, v128, v24
	v_exp_f32_e32 v23, v23
	v_add_f32_e32 v22, v22, v225
	v_mul_f32_e32 v1, v1, v226
	v_mul_f32_e32 v1, 0xbfb8aa3b, v1
	v_exp_f32_e32 v29, v1
	v_add_f32_e32 v23, 1.0, v23
	v_rcp_f32_e32 v23, v23
	v_mul_f32_e32 v22, 0xbfb8aa3b, v22
	v_sub_f32_e32 v1, 1.0, v29
	v_add_f32_e32 v25, 1.0, v29
	v_mul_f32_e32 v1, v1, v25
	v_add_f32_e32 v25, v27, v224
	v_mul_f32_e32 v25, 0xbfb8aa3b, v25
	v_exp_f32_e32 v25, v25
	v_sqrt_f32_e32 v28, v1
	v_mul_f32_e32 v23, v130, v23
	v_exp_f32_e32 v22, v22
	v_add_f32_e32 v25, 1.0, v25
	v_rcp_f32_e32 v25, v25
	v_pk_mul_f32 v[128:129], v[134:135], v[28:29]
	v_add_f32_e32 v22, 1.0, v22
	v_rcp_f32_e32 v22, v22
	v_mul_f32_e32 v25, v25, v226
	v_mul_f32_e32 v25, 0xbfb8aa3b, v25
	v_exp_f32_e32 v28, v25
	v_add_f32_e32 v1, v128, v129
	v_mul_f32_e32 v24, v124, v29
	v_mul_f32_e32 v22, v69, v22
	v_sub_f32_e32 v25, 1.0, v28
	v_add_f32_e32 v27, 1.0, v28
	v_mul_f32_e32 v25, v25, v27
	v_sqrt_f32_e32 v25, v25
	v_mul_f32_e32 v1, v28, v1
	v_mul_f32_e32 v24, v28, v24
	v_mul_f32_e32 v67, v23, v25
	v_add_f32_e32 v23, v26, v224
	v_mul_f32_e32 v23, 0xbfb8aa3b, v23
	v_exp_f32_e32 v23, v23
	s_nop 0
	v_add_f32_e32 v23, 1.0, v23
	v_rcp_f32_e32 v23, v23
	s_nop 0
	v_mul_f32_e32 v23, v23, v226
	v_mul_f32_e32 v23, 0xbfb8aa3b, v23
	v_exp_f32_e32 v27, v23
	s_nop 0
	v_sub_f32_e32 v23, 1.0, v27
	v_add_f32_e32 v25, 1.0, v27
	v_mul_f32_e32 v23, v23, v25
	v_sqrt_f32_e32 v26, v23
	v_add_f32_e32 v23, v1, v67
	v_pk_mul_f32 v[130:131], v[22:23], v[26:27]
	s_nop 0
	v_add_f32_e32 v1, v130, v131
	v_mul_f32_e32 v22, v27, v24
	s_waitcnt lgkmcnt(0)
	v_mov_b32_e32 v249, v22
	v_mov_b32_e32 v23, v22
	s_nop 1
	v_permlane16_swap_b32_e32 v23, v249
	v_cndmask_b32_e64 v23, v249, v23, s[98:99]
	v_mul_f32_e32 v73, v22, v23
	s_waitcnt lgkmcnt(0)
	v_mov_b32_e32 v249, v1
	v_mov_b32_e32 v24, v1
	s_nop 1
	v_permlane16_swap_b32_e32 v24, v249
	v_cndmask_b32_e64 v24, v249, v24, s[98:99]
	v_cndmask_b32_e64 v69, v24, 0, s[54:55]
	v_fma_f32 v22, v22, v24, v1
	v_fmac_f32_e32 v24, v1, v23
	v_cndmask_b32_e64 v25, v23, 1.0, s[54:55]
	v_cndmask_b32_e64 v1, v22, v24, s[54:55]
	s_waitcnt lgkmcnt(0)
	v_mov_b32_e32 v249, v73
	v_mov_b32_e32 v23, v73
	s_nop 1
	v_permlane32_swap_b32_e32 v23, v249
	v_cndmask_b32_e64 v23, v249, v23, s[100:101]
	v_mul_f32_e32 v22, v25, v23
	v_cndmask_b32_e64 v26, v22, v25, s[56:57]
	s_waitcnt lgkmcnt(0)
	v_mov_b32_e32 v249, v1
	v_mov_b32_e32 v24, v1
	s_nop 1
	v_permlane32_swap_b32_e32 v24, v249
	v_cndmask_b32_e64 v24, v249, v24, s[100:101]
	v_fma_f32 v22, v25, v24, v69
	v_fma_f32 v25, v73, v24, v1
	v_fmac_f32_e32 v24, v1, v23
	v_cndmask_b32_e64 v69, v22, v69, s[56:57]
	v_mul_f32_e32 v22, v73, v23
	v_cndmask_b32_e64 v23, v25, v24, s[56:57]
	ds_write_b64 v175, v[22:23] offset:62976
	s_waitcnt lgkmcnt(1)
	v_mfma_f32_16x16x32_bf16 v[22:25], v[14:17], v[208:211], 0
	s_waitcnt lgkmcnt(0)
; #define LAS __attribute__((address_space(3)))
; template <bool PHASE_B>
; __device__ __forceinline__ void lru_item(const Params& p, LAS unsigned char* lds, int ci, int ci_next, int jb, const int tid, v4u (&xvn)[3]) {
;     ...
;             const int ch = 16 * ct + fr; const float bav = GC[(dir * 3 + 0) * 64 + ch], bxv = GC[(dir * 3 + 1) * 64 + ch], c8 = GC[(dir * 3 + 2) * 64 + ch];
;             float Al = 1.f, Hl = 0.f;
; #pragma unroll
;             for (int ee = 0; ee < 4; ++ee) { const int e = dir ? 3 - ee : ee;
;                 const float r = __builtin_amdgcn_rcpf(1.f + __expf(-(ga[e] + bav))), ig = __builtin_amdgcn_rcpf(1.f + __expf(-(gx[e] + bxv)));
;                 const float la = -c8 * r; const float a = __expf(la); const float u = __builtin_amdgcn_sqrtf((1.f - a) * (1.f + a)) * (ig * xc[ct][e]);
;                 av[dir][ct][e] = a; uv[dir][ct][e] = u; Hl = a * Hl + u; Al *= a; }
;             const int o = dir ? 3 - fq : fq; const bool odd = (o & 1) != 0, hi2 = (o & 2) != 0;
;             const float A1 = __shfl_xor(Al, 16), H1 = __shfl_xor(Hl, 16);
;             const float pxA = odd ? A1 : 1.f, pxH = odd ? H1 : 0.f;
;             const float gA = Al * A1, gH = odd ? (Al * H1 + Hl) : (A1 * Hl + H1);
;             const float A2 = __shfl_xor(gA, 32), H2 = __shfl_xor(gH, 32);
;             const float PA = hi2 ? pxA * A2 : pxA, PH = hi2 ? (pxA * H2 + pxH) : pxH;
;             const float TA = gA * A2, TH = hi2 ? (gA * H2 + gH) : (A2 * gH + H2);
;             pA[dir][ct] = PA; pH[dir][ct] = PH;
;             ((LAS f32x2*)(lds + LR_SEG))[(dir * 8 + rt) * 64 + ch] = (f32x2){TA, TH};
;         }
;     }
;     if constexpr (PHASE_B) {
; #pragma unroll
;         for (int dir = 0; dir < 2; ++dir)
; #pragma unroll
;             for (int ct = 0; ct < 4; ++ct) cin[dir][ct] = ((const float*)(p.ws + WS_CIN))[(size_t)(ci * 2 + dir) * 768 + jb * 64 + 16 * ct + fr];
;         const bf16* gp = (const bf16*)(p.ws + WS_GR) + (size_t)(t0 + (tid >> 2)) * 768 + jb * 64 + (tid & 3) * 16;
;         gv[0] = *(const v4u*)gp; gv[1] = *(const v4u*)(gp + 8);
;     }
	v_mfma_f32_16x16x32_bf16 v[14:17], v[14:17], v[212:215], 0
	s_waitcnt lgkmcnt(1)
	v_mfma_f32_16x16x32_bf16 v[22:25], v[18:21], v[216:219], v[22:25]
	s_waitcnt lgkmcnt(0)
	v_mfma_f32_16x16x32_bf16 v[14:17], v[18:21], v[220:223], v[14:17]
	s_waitcnt lgkmcnt(1)
	s_nop 1
	s_nop 2
	v_add_f32_e32 v1, v25, v227
	v_mul_f32_e32 v1, 0xbfb8aa3b, v1
	v_exp_f32_e32 v1, v1
	s_waitcnt lgkmcnt(1)
	s_nop 0
	v_add_f32_e32 v17, v17, v228
	v_mul_f32_e32 v17, 0xbfb8aa3b, v17
	v_exp_f32_e32 v17, v17
	v_add_f32_e32 v1, 1.0, v1
	v_rcp_f32_e32 v1, v1
	v_add_f32_e32 v16, v16, v228
	v_add_f32_e32 v17, 1.0, v17
	v_rcp_f32_e32 v17, v17
	s_waitcnt lgkmcnt(0)
	v_mul_f32_e32 v1, v1, v229
	v_mul_f32_e32 v1, 0xbfb8aa3b, v1
	v_exp_f32_e32 v132, v1
	v_mul_f32_e32 v133, v133, v17
	v_mul_f32_e32 v16, 0xbfb8aa3b, v16
	v_exp_f32_e32 v16, v16
	v_sub_f32_e32 v1, 1.0, v132
	v_add_f32_e32 v18, 1.0, v132
	v_mul_f32_e32 v1, v1, v18
	v_sqrt_f32_e32 v1, v1
	v_add_f32_e32 v16, 1.0, v16
	v_add_f32_e32 v15, v15, v228
	v_rcp_f32_e32 v16, v16
	v_pk_mul_f32 v[134:135], v[132:133], v[0:1]
	v_mul_f32_e32 v15, 0xbfb8aa3b, v15
	v_pk_fma_f32 v[18:19], v[132:133], v[0:1], v[134:135] op_sel_hi:[1,1,0]
	v_add_f32_e32 v1, v24, v227
	v_mul_f32_e32 v1, 0xbfb8aa3b, v1
	v_exp_f32_e32 v1, v1
	v_exp_f32_e32 v15, v15
	v_mul_f32_e32 v18, v136, v16
	v_add_f32_e32 v14, v14, v228
	v_add_f32_e32 v1, 1.0, v1
	v_rcp_f32_e32 v1, v1
	v_add_f32_e32 v15, 1.0, v15
	v_rcp_f32_e32 v15, v15
	v_mul_f32_e32 v14, 0xbfb8aa3b, v14
	v_mul_f32_e32 v1, v1, v229
	v_mul_f32_e32 v1, 0xbfb8aa3b, v1
	v_exp_f32_e32 v25, v1
	v_mul_f32_e32 v15, v31, v15
	v_exp_f32_e32 v14, v14
	v_sub_f32_e32 v1, 1.0, v25
	v_add_f32_e32 v17, 1.0, v25
	v_mul_f32_e32 v1, v1, v17
	v_sqrt_f32_e32 v24, v1
	v_add_f32_e32 v1, v23, v227
	v_mul_f32_e32 v1, 0xbfb8aa3b, v1
	v_exp_f32_e32 v1, v1
	v_pk_mul_f32 v[136:137], v[18:19], v[24:25]
	v_mul_f32_e32 v17, v132, v25
	v_add_f32_e32 v16, v136, v137
	v_add_f32_e32 v1, 1.0, v1
	v_rcp_f32_e32 v1, v1
	v_add_f32_e32 v14, 1.0, v14
	v_rcp_f32_e32 v14, v14
	v_mul_f32_e32 v1, v1, v229
	v_mul_f32_e32 v1, 0xbfb8aa3b, v1
	v_exp_f32_e32 v1, v1
	v_mul_f32_e32 v14, v71, v14
	v_sub_f32_e32 v18, 1.0, v1
	v_add_f32_e32 v19, 1.0, v1
	v_mul_f32_e32 v18, v18, v19
	v_sqrt_f32_e32 v18, v18
	s_nop 0
	v_mul_f32_e32 v24, v15, v18
	v_mul_f32_e32 v15, v1, v16
	v_mul_f32_e32 v16, v1, v17
	v_add_f32_e32 v17, v22, v227
	v_mul_f32_e32 v17, 0xbfb8aa3b, v17
	v_exp_f32_e32 v17, v17
	v_add_f32_e32 v15, v15, v24
	v_add_f32_e32 v17, 1.0, v17
	v_rcp_f32_e32 v17, v17
	s_nop 0
	v_mul_f32_e32 v17, v17, v229
	v_mul_f32_e32 v17, 0xbfb8aa3b, v17
	v_exp_f32_e32 v23, v17
	s_nop 0
	v_sub_f32_e32 v17, 1.0, v23
	v_add_f32_e32 v18, 1.0, v23
	v_mul_f32_e32 v17, v17, v18
	v_sqrt_f32_e32 v22, v17
	s_nop 0
	v_pk_mul_f32 v[138:139], v[14:15], v[22:23]
	s_nop 0
	v_add_f32_e32 v14, v138, v139
	v_mul_f32_e32 v15, v23, v16
	s_waitcnt lgkmcnt(0)
	v_mov_b32_e32 v249, v15
	v_mov_b32_e32 v16, v15
	s_nop 1
	v_permlane16_swap_b32_e32 v16, v249
	v_cndmask_b32_e64 v16, v249, v16, s[98:99]
	v_mul_f32_e32 v20, v15, v16
	s_waitcnt lgkmcnt(0)
	v_mov_b32_e32 v249, v14
	v_mov_b32_e32 v17, v14
	s_nop 1
	v_permlane16_swap_b32_e32 v17, v249
	v_cndmask_b32_e64 v17, v249, v17, s[98:99]
	v_cndmask_b32_e64 v19, v17, 0, s[54:55]
	v_fma_f32 v15, v15, v17, v14
	v_fmac_f32_e32 v17, v14, v16
	v_cndmask_b32_e64 v18, v16, 1.0, s[54:55]
	v_cndmask_b32_e64 v15, v15, v17, s[54:55]
	s_waitcnt lgkmcnt(0)
	v_mov_b32_e32 v249, v20
	v_mov_b32_e32 v16, v20
	s_nop 1
	v_permlane32_swap_b32_e32 v16, v249
	v_cndmask_b32_e64 v16, v249, v16, s[100:101]
	v_mul_f32_e32 v14, v18, v16
	v_cndmask_b32_e64 v22, v14, v18, s[56:57]
	s_waitcnt lgkmcnt(0)
	v_mov_b32_e32 v249, v15
	v_mov_b32_e32 v17, v15
	s_nop 1
	v_permlane32_swap_b32_e32 v17, v249
	v_cndmask_b32_e64 v17, v249, v17, s[100:101]
	v_fma_f32 v14, v18, v17, v19
	v_fma_f32 v18, v20, v17, v15
	v_fmac_f32_e32 v17, v15, v16
	v_cndmask_b32_e64 v31, v14, v19, s[56:57]
	v_mul_f32_e32 v14, v20, v16
	v_cndmask_b32_e64 v15, v18, v17, s[56:57]
	ds_write_b64 v175, v[14:15] offset:63104
	v_mad_i64_i32 v[14:15], s[0:1], s13, v232, v[32:33]
	global_load_dword v78, v[14:15], off
	global_load_dword v81, v[14:15], off offset:64
	global_load_dword v83, v[14:15], off offset:128
	global_load_dword v85, v[14:15], off offset:192
	s_add_i32 s0, s13, 1
	v_mad_i64_i32 v[14:15], s[0:1], s0, v232, v[32:33]
	s_movk_i32 s0, 0x600
	s_nop 0
	v_mad_i64_i32 v[140:141], s[0:1], v196, s0, v[34:35]
	global_load_dword v76, v[14:15], off
	global_load_dword v74, v[14:15], off offset:64
	global_load_dword v73, v[14:15], off offset:128
	global_load_dword v71, v[14:15], off offset:192
	s_nop 0
	global_load_dwordx4 v[14:17], v[140:141], off offset:16
	global_load_dwordx4 v[18:21], v[140:141], off
	s_waitcnt lgkmcnt(0)
	s_barrier
; #define LAS __attribute__((address_space(3)))
; template <bool PHASE_B>
; __device__ __forceinline__ void lru_item(const Params& p, LAS unsigned char* lds, int ci, int ci_next, int jb, const int tid, v4u (&xvn)[3]) {
;     ...
; #pragma unroll
;         for (int dir = 0; dir < 2; ++dir) { const int ot = dir ? 7 - rt : rt;
; #pragma unroll
;             for (int ct = 0; ct < 4; ++ct) { const int ch = 16 * ct + fr; float h = cin[dir][ct];
; #pragma unroll
;                 for (int q = 0; q < 7; ++q) { const f32x2 sh = ((const LAS f32x2*)(lds + LR_SEG))[(dir * 8 + (dir ? 7 - q : q)) * 64 + ch]; const float nh = sh.x * h + sh.y; h = (q < ot) ? nh : h; }
;                 h = pA[dir][ct] * h + pH[dir][ct];
; #pragma unroll
;                 for (int ee = 0; ee < 4; ++ee) { const int e = dir ? 3 - ee : ee; h = av[dir][ct][e] * h + uv[dir][ct][e];
;                     ((LAS float*)(lds + LR_HB))[(dir * LCH + 16 * rt + 4 * fq + e) * 68 + ch] = h; } } }
	ds_read_b64 v[208:209], v176 offset:58624
	ds_read_b64 v[210:211], v176 offset:59136
	ds_read_b64 v[212:213], v176 offset:59648
	ds_read_b64 v[214:215], v176 offset:60160
	ds_read_b64 v[216:217], v176 offset:60672
	ds_read_b64 v[218:219], v176 offset:61184
	ds_read_b64 v[220:221], v176 offset:61696
	v_add_u32_e32 v196, s12, v196
	s_add_i32 s13, s13, s86
	s_waitcnt vmcnt(9) lgkmcnt(0)
	v_fmac_f32_e32 v209, v78, v208
	v_cndmask_b32_e64 v78, v78, v209, s[58:59]
	v_fmac_f32_e32 v211, v210, v78
	v_cndmask_b32_e64 v78, v78, v211, s[60:61]
	v_fmac_f32_e32 v213, v212, v78
	v_cndmask_b32_e64 v78, v78, v213, s[62:63]
	v_fmac_f32_e32 v215, v214, v78
	v_cndmask_b32_e64 v78, v78, v215, s[64:65]
	v_fmac_f32_e32 v217, v216, v78
	v_cndmask_b32_e64 v78, v78, v217, s[66:67]
	v_fmac_f32_e32 v219, v218, v78
	v_cndmask_b32_e64 v78, v78, v219, s[68:69]
	v_fmac_f32_e32 v221, v220, v78
	v_cndmask_b32_e64 v78, v78, v221, s[70:71]
	v_fmac_f32_e32 v39, v206, v78
	v_fmac_f32_e32 v49, v38, v39
	v_fmac_f32_e32 v50, v41, v49
	v_fmac_f32_e32 v52, v43, v50
	v_fmac_f32_e32 v54, v47, v52
	ds_write2_b32 v202, v49, v50 offset1:68
	ds_write2_b32 v202, v52, v54 offset0:136 offset1:204
	ds_read_b64 v[222:223], v176 offset:58752
	ds_read_b64 v[224:225], v176 offset:59264
	ds_read_b64 v[226:227], v176 offset:59776
	ds_read_b64 v[228:229], v176 offset:60288
	ds_read_b64 v[234:235], v176 offset:60800
	ds_read_b64 v[236:237], v176 offset:61312
	ds_read_b64 v[238:239], v176 offset:61824
	s_waitcnt vmcnt(0)
	v_lshlrev_b32_e32 v52, 16, v18
	v_and_b32_e32 v18, 0xffff0000, v18
	s_waitcnt lgkmcnt(0)
	v_fmac_f32_e32 v223, v81, v222
	v_cndmask_b32_e64 v41, v81, v223, s[58:59]
	v_fmac_f32_e32 v225, v224, v41
	v_cndmask_b32_e64 v41, v41, v225, s[60:61]
	v_fmac_f32_e32 v227, v226, v41
	v_cndmask_b32_e64 v41, v41, v227, s[62:63]
	v_fmac_f32_e32 v229, v228, v41
	v_cndmask_b32_e64 v41, v41, v229, s[64:65]
	v_fmac_f32_e32 v235, v234, v41
	v_cndmask_b32_e64 v41, v41, v235, s[66:67]
	v_fmac_f32_e32 v237, v236, v41
	v_cndmask_b32_e64 v41, v41, v237, s[68:69]
	v_fmac_f32_e32 v239, v238, v41
	v_cndmask_b32_e64 v38, v41, v239, s[70:71]
	v_fmac_f32_e32 v42, v40, v38
	v_fmac_f32_e32 v65, v56, v42
	v_fmac_f32_e32 v66, v59, v65
	v_fmac_f32_e32 v68, v61, v66
	v_fmac_f32_e32 v70, v63, v68
	ds_write_b32 v177, v65
	ds_write_b32 v178, v66
	ds_write_b32 v179, v68
	ds_write_b32 v180, v70
	ds_read_b64 v[208:209], v176 offset:58880
	ds_read_b64 v[210:211], v176 offset:59392
	ds_read_b64 v[212:213], v176 offset:59904
	ds_read_b64 v[214:215], v176 offset:60416
	ds_read_b64 v[216:217], v176 offset:60928
	ds_read_b64 v[218:219], v176 offset:61440
	ds_read_b64 v[220:221], v176 offset:61952
	s_waitcnt lgkmcnt(0)
	v_fmac_f32_e32 v209, v83, v208
	v_cndmask_b32_e64 v40, v83, v209, s[58:59]
	v_fmac_f32_e32 v211, v210, v40
	v_cndmask_b32_e64 v40, v40, v211, s[60:61]
	v_fmac_f32_e32 v213, v212, v40
	v_cndmask_b32_e64 v40, v40, v213, s[62:63]
	v_fmac_f32_e32 v215, v214, v40
	v_cndmask_b32_e64 v40, v40, v215, s[64:65]
	v_fmac_f32_e32 v217, v216, v40
	v_cndmask_b32_e64 v40, v40, v217, s[66:67]
	v_fmac_f32_e32 v219, v218, v40
	v_cndmask_b32_e64 v40, v40, v219, s[68:69]
	v_fmac_f32_e32 v221, v220, v40
	v_cndmask_b32_e64 v38, v40, v221, s[70:71]
	v_fmac_f32_e32 v44, v46, v38
	v_fmac_f32_e32 v45, v72, v44
	v_fmac_f32_e32 v80, v75, v45
	v_fmac_f32_e32 v82, v77, v80
	v_fmac_f32_e32 v84, v79, v82
	ds_write_b32 v181, v45
	ds_write_b32 v182, v80
	ds_write_b32 v183, v82
	ds_write_b32 v184, v84
	ds_read_b64 v[222:223], v176 offset:59008
	ds_read_b64 v[224:225], v176 offset:59520
	ds_read_b64 v[226:227], v176 offset:60032
	ds_read_b64 v[228:229], v176 offset:60544
	ds_read_b64 v[234:235], v176 offset:61056
	ds_read_b64 v[236:237], v176 offset:61568
	ds_read_b64 v[238:239], v176 offset:62080
	s_waitcnt lgkmcnt(0)
	v_fmac_f32_e32 v223, v85, v222
	v_cndmask_b32_e64 v40, v85, v223, s[58:59]
	v_fmac_f32_e32 v225, v224, v40
	v_cndmask_b32_e64 v40, v40, v225, s[60:61]
	v_fmac_f32_e32 v227, v226, v40
	v_cndmask_b32_e64 v40, v40, v227, s[62:63]
	v_fmac_f32_e32 v229, v228, v40
	v_cndmask_b32_e64 v40, v40, v229, s[64:65]
	v_fmac_f32_e32 v235, v234, v40
	v_cndmask_b32_e64 v40, v40, v235, s[66:67]
	v_fmac_f32_e32 v237, v236, v40
	v_cndmask_b32_e64 v40, v40, v237, s[68:69]
	v_fmac_f32_e32 v239, v238, v40
	v_cndmask_b32_e64 v38, v40, v239, s[70:71]
	v_fmac_f32_e32 v36, v48, v38
	v_fmac_f32_e32 v37, v86, v36
	v_fmac_f32_e32 v94, v89, v37
	v_fmac_f32_e32 v96, v91, v94
	v_fmac_f32_e32 v98, v93, v96
	ds_write_b32 v185, v37
	ds_write_b32 v186, v94
	ds_write_b32 v187, v96
	ds_write_b32 v188, v98
	ds_read2st64_b64 v[36:39], v190 offset0:6 offset1:7
	s_waitcnt lgkmcnt(0)
	v_fma_f32 v38, v76, v38, v39
	v_cndmask_b32_e64 v38, v76, v38, s[72:73]
	v_fmac_f32_e32 v37, v36, v38
	v_cndmask_b32_e64 v38, v38, v37, s[74:75]
	ds_read_b64 v[208:209], v176 offset:65280
	ds_read_b64 v[210:211], v176 offset:64768
	ds_read_b64 v[212:213], v176 offset:64256
	ds_read_b64 v[214:215], v176 offset:63744
	ds_read_b64 v[216:217], v176 offset:63232
	s_waitcnt lgkmcnt(0)
	v_fmac_f32_e32 v209, v208, v38
	v_cndmask_b32_e64 v38, v38, v209, s[76:77]
	v_fmac_f32_e32 v211, v210, v38
	v_cndmask_b32_e64 v38, v38, v211, s[78:79]
	v_fmac_f32_e32 v213, v212, v38
	v_cndmask_b32_e64 v38, v38, v213, s[80:81]
	v_fmac_f32_e32 v215, v214, v38
	v_cndmask_b32_e64 v38, v38, v215, s[82:83]
	v_fmac_f32_e32 v217, v216, v38
	v_cndmask_b32_e64 v36, v38, v217, s[84:85]
	v_fmac_f32_e32 v57, v55, v36
	v_fmac_f32_e32 v103, v100, v57
	v_fmac_f32_e32 v106, v105, v103
	v_fmac_f32_e32 v53, v51, v106
	v_add_u32_e32 v36, 0x8800, v202
	v_fmac_f32_e32 v110, v109, v53
	ds_write2_b32 v36, v106, v103 offset0:136 offset1:204
	ds_write2_b32 v36, v110, v53 offset1:68
	ds_read2st64_b64 v[36:39], v191 offset0:6 offset1:7
	v_lshlrev_b32_e32 v53, 16, v19
	v_and_b32_e32 v19, 0xffff0000, v19
	s_waitcnt lgkmcnt(0)
; #define LAS __attribute__((address_space(3)))
; __device__ __forceinline__ unsigned pk2(float lo, float hi) { return f2bf(lo) | (f2bf(hi) << 16); }
; template <bool PHASE_B>
; __device__ __forceinline__ void lru_item(const Params& p, LAS unsigned char* lds, int ci, int ci_next, int jb, const int tid, v4u (&xvn)[3]) {
;     ...
; #pragma unroll
;         for (int dir = 0; dir < 2; ++dir) { const int ot = dir ? 7 - rt : rt;
; #pragma unroll
;             for (int ct = 0; ct < 4; ++ct) { const int ch = 16 * ct + fr; float h = cin[dir][ct];
; #pragma unroll
;                 for (int q = 0; q < 7; ++q) { const f32x2 sh = ((const LAS f32x2*)(lds + LR_SEG))[(dir * 8 + (dir ? 7 - q : q)) * 64 + ch]; const float nh = sh.x * h + sh.y; h = (q < ot) ? nh : h; }
;                 h = pA[dir][ct] * h + pH[dir][ct];
; #pragma unroll
;                 for (int ee = 0; ee < 4; ++ee) { const int e = dir ? 3 - ee : ee; h = av[dir][ct][e] * h + uv[dir][ct][e];
;                     ((LAS float*)(lds + LR_HB))[(dir * LCH + 16 * rt + 4 * fq + e) * 68 + ch] = h; } } }
;         __syncthreads();
;         { const int t = tid >> 2, c0 = (tid & 3) * 16; bf16* gp = (bf16*)(p.ws + WS_GR) + (size_t)(t0 + t) * 768 + jb * 64 + c0;
;           const LAS float* H0 = (const LAS float*)(lds + LR_HB) + t * 68 + c0; const LAS float* H1 = H0 + LCH * 68;
; #pragma unroll
;           for (int hf = 0; hf < 2; ++hf) { const f32x4 a0 = *(const LAS f32x4*)(H0 + 8 * hf), a1 = *(const LAS f32x4*)(H0 + 8 * hf + 4), b0 = *(const LAS f32x4*)(H1 + 8 * hf), b1 = *(const LAS f32x4*)(H1 + 8 * hf + 4);
;               const v4u g = gv[hf]; v4u o;
;               o.x = pk2(bflo(g.x) * (a0[0] + b0[0]), bfhi(g.x) * (a0[1] + b0[1])); o.y = pk2(bflo(g.y) * (a0[2] + b0[2]), bfhi(g.y) * (a0[3] + b0[3]));
;               o.z = pk2(bflo(g.z) * (a1[0] + b1[0]), bfhi(g.z) * (a1[1] + b1[1])); o.w = pk2(bflo(g.w) * (a1[2] + b1[2]), bfhi(g.w) * (a1[3] + b1[3]));
;               *(v4u*)(gp + 8 * hf) = o; } }
	v_fma_f32 v38, v74, v38, v39
	v_cndmask_b32_e64 v38, v74, v38, s[72:73]
	v_fmac_f32_e32 v37, v36, v38
	v_cndmask_b32_e64 v38, v38, v37, s[74:75]
	ds_read_b64 v[222:223], v176 offset:65408
	ds_read_b64 v[224:225], v176 offset:64896
	ds_read_b64 v[226:227], v176 offset:64384
	ds_read_b64 v[228:229], v176 offset:63872
	ds_read_b64 v[234:235], v176 offset:63360
	s_waitcnt lgkmcnt(0)
	v_fmac_f32_e32 v223, v222, v38
	v_cndmask_b32_e64 v38, v38, v223, s[76:77]
	v_fmac_f32_e32 v225, v224, v38
	v_cndmask_b32_e64 v38, v38, v225, s[78:79]
	v_fmac_f32_e32 v227, v226, v38
	v_cndmask_b32_e64 v38, v38, v227, s[80:81]
	v_fmac_f32_e32 v229, v228, v38
	v_cndmask_b32_e64 v38, v38, v229, s[82:83]
	v_fmac_f32_e32 v235, v234, v38
	v_cndmask_b32_e64 v36, v38, v235, s[84:85]
	v_fmac_f32_e32 v64, v62, v36
	v_fmac_f32_e32 v115, v112, v64
	v_fmac_f32_e32 v118, v117, v115
	v_fmac_f32_e32 v60, v58, v118
	v_add_u32_e32 v36, 0x8800, v203
	v_fmac_f32_e32 v122, v121, v60
	ds_write2_b32 v36, v118, v115 offset0:136 offset1:204
	ds_write2_b32 v36, v122, v60 offset1:68
	ds_read_b64 v[36:37], v192 offset:3584
	s_waitcnt lgkmcnt(0)
	v_fmac_f32_e32 v37, v73, v36
	v_cndmask_b32_e64 v40, v73, v37, s[72:73]
	ds_read2st64_b64 v[36:39], v192 offset0:5 offset1:6
	s_waitcnt lgkmcnt(0)
	v_fma_f32 v38, v38, v40, v39
	v_cndmask_b32_e64 v38, v40, v38, s[74:75]
	v_fmac_f32_e32 v37, v36, v38
	v_cndmask_b32_e64 v38, v38, v37, s[76:77]
	ds_read_b64 v[208:209], v176 offset:65024
	ds_read_b64 v[210:211], v176 offset:64512
	ds_read_b64 v[212:213], v176 offset:64000
	ds_read_b64 v[214:215], v176 offset:63488
	s_waitcnt lgkmcnt(0)
	v_fmac_f32_e32 v209, v208, v38
	v_cndmask_b32_e64 v38, v38, v209, s[78:79]
	v_fmac_f32_e32 v211, v210, v38
	v_cndmask_b32_e64 v38, v38, v211, s[80:81]
	v_fmac_f32_e32 v213, v212, v38
	v_cndmask_b32_e64 v38, v38, v213, s[82:83]
	v_fmac_f32_e32 v215, v214, v38
	v_cndmask_b32_e64 v36, v38, v215, s[84:85]
	v_fmac_f32_e32 v69, v26, v36
	v_fmac_f32_e32 v127, v124, v69
	v_fmac_f32_e32 v128, v29, v127
	v_fmac_f32_e32 v67, v28, v128
	v_add_u32_e32 v26, 0x8800, v204
	v_fmac_f32_e32 v130, v27, v67
	ds_write2_b32 v26, v128, v127 offset0:136 offset1:204
	ds_write2_b32 v26, v130, v67 offset1:68
	ds_read_b64 v[26:27], v194 offset:3584
	s_waitcnt lgkmcnt(0)
	v_fmac_f32_e32 v27, v71, v26
	v_cndmask_b32_e64 v36, v71, v27, s[72:73]
	ds_read2st64_b64 v[26:29], v194 offset0:5 offset1:6
	s_waitcnt lgkmcnt(0)
	v_fma_f32 v28, v28, v36, v29
	v_cndmask_b32_e64 v28, v36, v28, s[74:75]
	v_fmac_f32_e32 v27, v26, v28
	v_cndmask_b32_e64 v28, v28, v27, s[76:77]
	ds_read_b64 v[222:223], v176 offset:65152
	ds_read_b64 v[224:225], v176 offset:64640
	ds_read_b64 v[226:227], v176 offset:64128
	ds_read_b64 v[228:229], v176 offset:63616
	s_waitcnt lgkmcnt(0)
	v_fmac_f32_e32 v223, v222, v28
	v_cndmask_b32_e64 v28, v28, v223, s[78:79]
	v_fmac_f32_e32 v225, v224, v28
	v_cndmask_b32_e64 v28, v28, v225, s[80:81]
	v_fmac_f32_e32 v227, v226, v28
	v_cndmask_b32_e64 v28, v28, v227, s[82:83]
	v_fmac_f32_e32 v229, v228, v28
	v_cndmask_b32_e64 v26, v28, v229, s[84:85]
	v_fmac_f32_e32 v31, v22, v26
	v_fmac_f32_e32 v135, v132, v31
	v_fmac_f32_e32 v136, v25, v135
	v_fmac_f32_e32 v24, v1, v136
	v_add_u32_e32 v22, 0x8800, v205
	v_fmac_f32_e32 v138, v23, v24
	ds_write2_b32 v22, v136, v135 offset0:136 offset1:204
	ds_write2_b32 v22, v138, v24 offset1:68
	s_waitcnt lgkmcnt(0)
	s_barrier
	ds_read_b128 v[22:25], v195
	ds_read_b128 v[26:29], v195 offset:16
	ds_read_b128 v[36:39], v195 offset:32
	ds_read_b128 v[40:43], v195 offset:48
	ds_read_b128 v[44:47], v195 offset:34816
	ds_read_b128 v[48:51], v195 offset:34832
	s_waitcnt lgkmcnt(1)
	v_pk_add_f32 v[24:25], v[24:25], v[46:47]
	v_pk_add_f32 v[22:23], v[22:23], v[44:45]
	v_mov_b32_e32 v45, v24
	v_mov_b32_e32 v24, v23
	v_pk_mul_f32 v[18:19], v[24:25], v[18:19]
	s_waitcnt lgkmcnt(0)
	v_pk_add_f32 v[24:25], v[28:29], v[50:51]
	v_pk_add_f32 v[26:27], v[26:27], v[48:49]
	v_mov_b32_e32 v44, v22
	v_lshlrev_b32_e32 v23, 16, v21
	v_lshlrev_b32_e32 v22, 16, v20
	v_mov_b32_e32 v29, v24
	v_and_b32_e32 v21, 0xffff0000, v21
	v_and_b32_e32 v20, 0xffff0000, v20
	v_mov_b32_e32 v24, v27
	v_mov_b32_e32 v28, v26
	v_pk_mul_f32 v[20:21], v[24:25], v[20:21]
	v_pk_mul_f32 v[44:45], v[44:45], v[52:53]
	v_pk_mul_f32 v[22:23], v[28:29], v[22:23]
	v_bfe_u32 v1, v21, 16, 1
	v_add3_u32 v1, v21, v1, s33
	v_bfe_u32 v26, v23, 16, 1
	v_add3_u32 v23, v23, v26, s33
	v_lshrrev_b32_e32 v21, 16, v23
	v_and_or_b32 v21, v1, s11, v21
	v_cvt_pk_bf16_f32 v20, v22, v20
	v_cvt_pk_bf16_f32 v19, v45, v19
	v_cvt_pk_bf16_f32 v18, v44, v18
	global_store_dwordx4 v[140:141], v[18:21], off
	ds_read_b128 v[18:21], v195 offset:34848
	ds_read_b128 v[22:25], v195 offset:34864
	v_lshlrev_b32_e32 v27, 16, v15
	v_lshlrev_b32_e32 v26, 16, v14
	v_and_b32_e32 v15, 0xffff0000, v15
	s_waitcnt lgkmcnt(1)
	v_pk_add_f32 v[20:21], v[38:39], v[20:21]
	v_pk_add_f32 v[18:19], v[36:37], v[18:19]
	v_mov_b32_e32 v29, v20
	v_and_b32_e32 v14, 0xffff0000, v14
	v_mov_b32_e32 v20, v19
	v_pk_mul_f32 v[14:15], v[20:21], v[14:15]
	s_waitcnt lgkmcnt(0)
	v_pk_add_f32 v[20:21], v[42:43], v[24:25]
	v_pk_add_f32 v[22:23], v[40:41], v[22:23]
	v_mov_b32_e32 v28, v18
	v_lshlrev_b32_e32 v19, 16, v17
	v_lshlrev_b32_e32 v18, 16, v16
	v_mov_b32_e32 v25, v20
	v_and_b32_e32 v17, 0xffff0000, v17
	v_and_b32_e32 v16, 0xffff0000, v16
	v_mov_b32_e32 v20, v23
	v_mov_b32_e32 v24, v22
	v_pk_mul_f32 v[16:17], v[20:21], v[16:17]
	v_pk_mul_f32 v[26:27], v[28:29], v[26:27]
	v_pk_mul_f32 v[18:19], v[24:25], v[18:19]
	v_bfe_u32 v1, v17, 16, 1
	v_bfe_u32 v20, v16, 16, 1
	v_add3_u32 v16, v16, v20, s33
	v_add3_u32 v1, v17, v1, s33
	v_bfe_u32 v21, v18, 16, 1
	v_bfe_u32 v22, v19, 16, 1
	v_add3_u32 v19, v19, v22, s33
	v_add3_u32 v18, v18, v21, s33
	v_lshrrev_b32_e32 v21, 16, v17
	v_lshrrev_b32_e32 v20, 16, v20
	v_lshrrev_b32_e32 v18, 16, v18
	v_lshrrev_b32_e32 v17, 16, v19
	v_and_or_b32 v17, v1, s11, v17
	v_and_or_b32 v16, v16, s11, v18
	v_cvt_pk_bf16_f32 v15, v27, v15
	v_cvt_pk_bf16_f32 v14, v26, v14
	global_store_dwordx4 v[140:141], v[14:17], off offset:16
	s_cbranch_vccnz .LBB0_353

; #define LAS __attribute__((address_space(3)))
; template <bool PHASE_B>
; __device__ __forceinline__ void lru_item(const Params& p, LAS unsigned char* lds, int ci, int ci_next, int jb, const int tid, v4u (&xvn)[3]) {
;     ...
; #pragma unroll
;     for (int k = 0; k < 3; ++k) { const int c = k * NTHR + tid, rr = c >> 3, d8 = c & 7; if (c < 131 * 8) *(LAS v4u*)(lds + LR_XR + rr * 144 + d8 * 16) = xvn[k]; }
;     float cin[2][4]; v4u gv[2];
.LBB0_529:
	s_mov_b32 s98, 0xffff0000
	s_mov_b32 s99, 0xffff0000
	s_mov_b32 s100, 0
	s_mov_b32 s101, -1
	s_and_saveexec_b64 s[12:13], s[8:9]
	s_cbranch_execz .LBB0_543
	s_waitcnt vmcnt(1)
	ds_write_b128 v73, v[6:9]
	s_or_b64 exec, exec, s[12:13]
	s_and_saveexec_b64 s[12:13], s[38:39]
	s_cbranch_execnz .LBB0_544

; #define LAS __attribute__((address_space(3)))
; __device__ __forceinline__ unsigned pk2(float lo, float hi) { return f2bf(lo) | (f2bf(hi) << 16); }
; template <bool PHASE_B>
; __device__ __forceinline__ void lru_item(const Params& p, LAS unsigned char* lds, int ci, int ci_next, int jb, const int tid, v4u (&xvn)[3]) {
;     ...
;     bf16x8 af[2];
; #pragma unroll
;     for (int ks = 0; ks < 2; ++ks) { const int cb0 = 32 * ks + 8 * fq;
;         f32x4 s0 = *(const LAS f32x4*)(CB + cb0), s1 = *(const LAS f32x4*)(CB + cb0 + 4);
; #pragma unroll
;         for (int tap = 0; tap < 4; ++tap) { const v4u v = *(const LAS v4u*)(lds + LR_XR + (16 * rt + fr + tap) * 144 + cb0 * 2);
;             const f32x4 w0 = *(const LAS f32x4*)(CW + tap * 64 + cb0), w1 = *(const LAS f32x4*)(CW + tap * 64 + cb0 + 4);
;             s0 += (f32x4){bflo(v.x), bfhi(v.x), bflo(v.y), bfhi(v.y)} * w0; s1 += (f32x4){bflo(v.z), bfhi(v.z), bflo(v.w), bfhi(v.w)} * w1; }
;         v4u o; o.x = pk2(s0[0], s0[1]); o.y = pk2(s0[2], s0[3]); o.z = pk2(s1[0], s1[1]); o.w = pk2(s1[2], s1[3]);
;         af[ks] = __builtin_bit_cast(bf16x8, o); }
.LBB0_541:
	ds_read_b128 v[14:17], v88
	ds_read_b128 v[18:21], v78 offset:56832
	ds_read_b128 v[26:29], v78 offset:56848
	ds_read_b128 v[30:33], v78 offset:55808
	ds_read_b128 v[34:37], v78 offset:55824
	ds_read_b128 v[38:41], v88 offset:144
	s_waitcnt lgkmcnt(5)
	v_lshlrev_b32_e32 v42, 16, v14
	v_and_b32_e32 v43, 0xffff0000, v14
	v_lshlrev_b32_e32 v14, 16, v15
	v_and_b32_e32 v15, 0xffff0000, v15
	s_waitcnt lgkmcnt(2)
	v_pk_fma_f32 v[32:33], v[32:33], v[14:15], v[20:21]
	v_lshlrev_b32_e32 v14, 16, v16
	v_and_b32_e32 v15, 0xffff0000, v16
	v_lshlrev_b32_e32 v16, 16, v17
	v_and_b32_e32 v17, 0xffff0000, v17
	v_pk_fma_f32 v[30:31], v[30:31], v[42:43], v[18:19]
	s_waitcnt lgkmcnt(1)
	v_pk_fma_f32 v[26:27], v[34:35], v[14:15], v[26:27]
	v_pk_fma_f32 v[28:29], v[36:37], v[16:17], v[28:29]
	ds_read_b128 v[14:17], v78 offset:56064
	ds_read_b128 v[18:21], v78 offset:56080
	s_waitcnt lgkmcnt(2)
	v_lshlrev_b32_e32 v34, 16, v38
	v_and_b32_e32 v35, 0xffff0000, v38
	v_lshlrev_b32_e32 v36, 16, v39
	v_and_b32_e32 v37, 0xffff0000, v39
	s_waitcnt lgkmcnt(1)
	v_pk_fma_f32 v[34:35], v[14:15], v[34:35], v[30:31]
	v_lshlrev_b32_e32 v14, 16, v41
	v_and_b32_e32 v15, 0xffff0000, v41
	v_pk_fma_f32 v[36:37], v[16:17], v[36:37], v[32:33]
	s_waitcnt lgkmcnt(0)
	v_pk_fma_f32 v[38:39], v[20:21], v[14:15], v[28:29]
	ds_read_b128 v[14:17], v88 offset:288
	v_lshlrev_b32_e32 v30, 16, v40
	v_and_b32_e32 v31, 0xffff0000, v40
	v_pk_fma_f32 v[40:41], v[18:19], v[30:31], v[26:27]
	ds_read_b128 v[18:21], v78 offset:56320
	ds_read_b128 v[26:29], v78 offset:56336
	ds_read_b128 v[30:33], v88 offset:432
	s_waitcnt lgkmcnt(3)
	v_lshlrev_b32_e32 v42, 16, v14
	v_and_b32_e32 v43, 0xffff0000, v14
	v_lshlrev_b32_e32 v14, 16, v15
	v_and_b32_e32 v15, 0xffff0000, v15
	s_waitcnt lgkmcnt(2)
	v_pk_fma_f32 v[36:37], v[20:21], v[14:15], v[36:37]
	v_lshlrev_b32_e32 v14, 16, v16
	v_and_b32_e32 v15, 0xffff0000, v16
	v_lshlrev_b32_e32 v16, 16, v17
	v_and_b32_e32 v17, 0xffff0000, v17
	v_pk_fma_f32 v[34:35], v[18:19], v[42:43], v[34:35]
	s_waitcnt lgkmcnt(1)
	v_pk_fma_f32 v[26:27], v[26:27], v[14:15], v[40:41]
	v_pk_fma_f32 v[28:29], v[28:29], v[16:17], v[38:39]
	ds_read_b128 v[14:17], v78 offset:56576
	ds_read_b128 v[18:21], v78 offset:56592
	s_waitcnt lgkmcnt(2)
	v_lshlrev_b32_e32 v38, 16, v30
	v_and_b32_e32 v39, 0xffff0000, v30
	v_lshlrev_b32_e32 v30, 16, v31
	s_waitcnt lgkmcnt(1)
	v_pk_fma_f32 v[14:15], v[14:15], v[38:39], v[34:35]
	v_and_b32_e32 v31, 0xffff0000, v31
	v_bfe_u32 v1, v14, 16, 1
	v_add3_u32 v1, v14, v1, s33
	v_bfe_u32 v14, v15, 16, 1
	v_pk_fma_f32 v[16:17], v[16:17], v[30:31], v[36:37]
	v_lshrrev_b32_e32 v1, 16, v1
	v_add3_u32 v14, v15, v14, s33
	v_and_or_b32 v14, v14, s11, v1
	v_lshlrev_b32_e32 v30, 16, v32
	v_and_b32_e32 v31, 0xffff0000, v32
	s_waitcnt lgkmcnt(0)
	v_pk_fma_f32 v[18:19], v[18:19], v[30:31], v[26:27]
	v_cvt_pk_bf16_f32 v15, v16, v17
	v_lshlrev_b32_e32 v32, 16, v33
	v_and_b32_e32 v33, 0xffff0000, v33
	v_pk_fma_f32 v[20:21], v[20:21], v[32:33], v[28:29]
	v_cvt_pk_bf16_f32 v16, v18, v19
	v_bfe_u32 v1, v20, 16, 1
	v_bfe_u32 v17, v21, 16, 1
	v_add3_u32 v1, v20, v1, s33
	v_add3_u32 v17, v21, v17, s33
	ds_read_b128 v[18:21], v89
	ds_read_b128 v[26:29], v78 offset:56960
	ds_read_b128 v[30:33], v78 offset:56976
	ds_read_b128 v[34:37], v78 offset:55936
	ds_read_b128 v[38:41], v78 offset:55952
	ds_read_b128 v[42:45], v89 offset:144
	s_waitcnt lgkmcnt(5)
	v_lshlrev_b32_e32 v46, 16, v18
	v_and_b32_e32 v47, 0xffff0000, v18
	v_lshlrev_b32_e32 v18, 16, v19
	v_and_b32_e32 v19, 0xffff0000, v19
	s_waitcnt lgkmcnt(2)
	v_pk_fma_f32 v[36:37], v[36:37], v[18:19], v[28:29]
	v_lshlrev_b32_e32 v18, 16, v20
	v_and_b32_e32 v19, 0xffff0000, v20
	v_lshlrev_b32_e32 v20, 16, v21
	v_and_b32_e32 v21, 0xffff0000, v21
	v_pk_fma_f32 v[34:35], v[34:35], v[46:47], v[26:27]
	s_waitcnt lgkmcnt(1)
	v_pk_fma_f32 v[30:31], v[38:39], v[18:19], v[30:31]
	v_pk_fma_f32 v[32:33], v[40:41], v[20:21], v[32:33]
	ds_read_b128 v[18:21], v78 offset:56192
	ds_read_b128 v[26:29], v78 offset:56208
	s_waitcnt lgkmcnt(2)
	v_lshlrev_b32_e32 v38, 16, v42
	v_and_b32_e32 v39, 0xffff0000, v42
	v_lshlrev_b32_e32 v40, 16, v43
	v_and_b32_e32 v41, 0xffff0000, v43
	s_waitcnt lgkmcnt(1)
	v_pk_fma_f32 v[38:39], v[18:19], v[38:39], v[34:35]
	v_lshlrev_b32_e32 v18, 16, v45
	v_and_b32_e32 v19, 0xffff0000, v45
	v_pk_fma_f32 v[40:41], v[20:21], v[40:41], v[36:37]
	s_waitcnt lgkmcnt(0)
	v_pk_fma_f32 v[42:43], v[28:29], v[18:19], v[32:33]
	ds_read_b128 v[18:21], v89 offset:288
	v_lshlrev_b32_e32 v34, 16, v44
	v_and_b32_e32 v35, 0xffff0000, v44
	v_pk_fma_f32 v[44:45], v[26:27], v[34:35], v[30:31]
	ds_read_b128 v[26:29], v78 offset:56448
	ds_read_b128 v[30:33], v78 offset:56464
	ds_read_b128 v[34:37], v89 offset:432
	s_waitcnt lgkmcnt(3)
	v_lshlrev_b32_e32 v46, 16, v18
	v_and_b32_e32 v47, 0xffff0000, v18
	v_lshlrev_b32_e32 v18, 16, v19
	v_and_b32_e32 v19, 0xffff0000, v19
	s_waitcnt lgkmcnt(2)
	v_pk_fma_f32 v[40:41], v[28:29], v[18:19], v[40:41]
	v_lshlrev_b32_e32 v18, 16, v20
	v_and_b32_e32 v19, 0xffff0000, v20
	v_lshlrev_b32_e32 v20, 16, v21
	v_and_b32_e32 v21, 0xffff0000, v21
	v_pk_fma_f32 v[38:39], v[26:27], v[46:47], v[38:39]
	s_waitcnt lgkmcnt(1)
	v_pk_fma_f32 v[30:31], v[30:31], v[18:19], v[44:45]
	v_pk_fma_f32 v[32:33], v[32:33], v[20:21], v[42:43]
	ds_read_b128 v[18:21], v78 offset:56704
	ds_read_b128 v[26:29], v78 offset:56720
	s_waitcnt lgkmcnt(2)
	v_lshlrev_b32_e32 v42, 16, v34
	v_and_b32_e32 v43, 0xffff0000, v34
	v_lshlrev_b32_e32 v34, 16, v35
	s_waitcnt lgkmcnt(1)
; #define LAS __attribute__((address_space(3)))
; #define MFMA16(a, b, c) __builtin_amdgcn_mfma_f32_16x16x32_bf16(a, b, c, 0, 0, 0)
; template <bool PHASE_B>
; __device__ __forceinline__ void lru_item(const Params& p, LAS unsigned char* lds, int ci, int ci_next, int jb, const int tid, v4u (&xvn)[3]) {
;     ...
;     float xc[4][4];
; #pragma unroll
;     for (int ct = 0; ct < 4; ++ct) { const int ch = 16 * ct + fr; float xr7[7];
; #pragma unroll
;         for (int j = 0; j < 7; ++j) xr7[j] = __builtin_bit_cast(float, (unsigned)(*(const LAS bf16*)(lds + LR_XR + (16 * rt + 4 * fq + j) * 144 + ch * 2)) << 16);
;         const float w0 = CW[ch], w1 = CW[64 + ch], w2 = CW[128 + ch], w3 = CW[192 + ch], b = CB[ch];
; #pragma unroll
;         for (int e = 0; e < 4; ++e) xc[ct][e] = b + xr7[e] * w0 + xr7[e + 1] * w1 + xr7[e + 2] * w2 + xr7[e + 3] * w3; }
;     float av[2][4][4], uv[2][4][4], pA[2][4], pH[2][4];
; #pragma unroll
;     for (int dir = 0; dir < 2; ++dir) {
; #pragma unroll
;         for (int ct = 0; ct < 4; ++ct) {
;             f32x4 ga = (f32x4){0.f, 0.f, 0.f, 0.f}, gx = (f32x4){0.f, 0.f, 0.f, 0.f};
; #pragma unroll
;             for (int ks = 0; ks < 2; ++ks) {
;                 const bf16x8 wa = *(const LAS bf16x8*)(lds + LR_WG + ((dir * 2 + 0) * 64 + 16 * ct + fr) * 144 + (32 * ks + 8 * fq) * 2);
;                 const bf16x8 wx = *(const LAS bf16x8*)(lds + LR_WG + ((dir * 2 + 1) * 64 + 16 * ct + fr) * 144 + (32 * ks + 8 * fq) * 2);
;                 ga = MFMA16(af[ks], wa, ga); gx = MFMA16(af[ks], wx, gx); }
;             const int ch = 16 * ct + fr; const float bav = GC[(dir * 3 + 0) * 64 + ch], bxv = GC[(dir * 3 + 1) * 64 + ch], c8 = GC[(dir * 3 + 2) * 64 + ch];
;             float Al = 1.f, Hl = 0.f;
; #pragma unroll
;             for (int ee = 0; ee < 4; ++ee) { const int e = dir ? 3 - ee : ee;
;                 const float r = __builtin_amdgcn_rcpf(1.f + __expf(-(ga[e] + bav))), ig = __builtin_amdgcn_rcpf(1.f + __expf(-(gx[e] + bxv)));
;                 const float la = -c8 * r; const float a = __expf(la); const float u = __builtin_amdgcn_sqrtf((1.f - a) * (1.f + a)) * (ig * xc[ct][e]);
;                 av[dir][ct][e] = a; uv[dir][ct][e] = u; Hl = a * Hl + u; Al *= a; }
	v_pk_fma_f32 v[18:19], v[18:19], v[42:43], v[38:39]
	v_and_b32_e32 v35, 0xffff0000, v35
	v_pk_fma_f32 v[20:21], v[20:21], v[34:35], v[40:41]
	v_cvt_pk_bf16_f32 v18, v18, v19
	v_bfe_u32 v19, v20, 16, 1
	v_lshlrev_b32_e32 v34, 16, v36
	v_and_b32_e32 v35, 0xffff0000, v36
	v_lshlrev_b32_e32 v36, 16, v37
	v_and_b32_e32 v37, 0xffff0000, v37
	v_add3_u32 v19, v20, v19, s33
	v_bfe_u32 v20, v21, 16, 1
	s_waitcnt lgkmcnt(0)
	v_pk_fma_f32 v[28:29], v[28:29], v[36:37], v[32:33]
	v_pk_fma_f32 v[26:27], v[26:27], v[34:35], v[30:31]
	v_lshrrev_b32_e32 v19, 16, v19
	v_add3_u32 v20, v21, v20, s33
	v_and_or_b32 v19, v20, s11, v19
	v_bfe_u32 v20, v26, 16, 1
	v_bfe_u32 v23, v29, 16, 1
	v_add3_u32 v20, v26, v20, s33
	v_bfe_u32 v21, v27, 16, 1
	v_add3_u32 v32, v29, v23, s33
	v_add_u32_e32 v23, v80, v81
	v_add_u32_e32 v30, 0xd800, v82
	v_add_u32_e32 v58, 0xdc00, v82
	v_lshrrev_b32_e32 v20, 16, v20
	v_add3_u32 v21, v27, v21, s33
	ds_read_u16 v49, v23
	ds_read_u16 v51, v23 offset:144
	ds_read_u16 v60, v23 offset:288
	ds_read_u16 v26, v23 offset:864
	ds_read_u16 v70, v23 offset:432
	ds_read_u16 v109, v23 offset:576
	ds_read_u16 v116, v90
	ds_read_u16 v110, v23 offset:720
	ds_read2_b32 v[46:47], v30 offset0:128 offset1:144
	ds_read2_b32 v[40:41], v30 offset0:192 offset1:208
	ds_read2_b32 v[52:53], v58 offset1:16
	ds_read2_b32 v[44:45], v58 offset0:64 offset1:80
	ds_read2_b32 v[34:35], v58 offset0:128 offset1:144
	ds_read_u16 v117, v90 offset:144
	ds_read_u16 v118, v90 offset:288
	ds_read_u16 v119, v90 offset:432
	ds_read_u16 v23, v90 offset:864
	ds_read_u16 v120, v90 offset:576
	ds_read_u16 v123, v91
	ds_read_u16 v122, v91 offset:144
	ds_read_u16 v121, v90 offset:720
	v_and_or_b32 v20, v21, s11, v20
	v_bfe_u32 v21, v28, 16, 1
	s_waitcnt lgkmcnt(4)
	v_lshlrev_b32_e32 v50, 16, v23
	v_add_u32_e32 v23, v85, v79
	v_add3_u32 v21, v28, v21, s33
	v_lshlrev_b32_e32 v48, 16, v26
	ds_read_u16 v124, v91 offset:288
	ds_read_u16 v125, v91 offset:432
	ds_read_u16 v126, v91 offset:576
	ds_read_u16 v127, v91 offset:720
	ds_read_u16 v31, v91 offset:864
	ds_read_u16 v43, v92
	ds_read_u16 v61, v92 offset:144
	ds_read_u16 v103, v92 offset:288
	ds_read_b128 v[26:29], v23 offset:18944
	v_perm_b32 v17, v17, v1, s65
	ds_read2_b32 v[38:39], v30 offset0:160 offset1:176
	ds_read_b128 v[54:57], v23 offset:28160
	ds_read_b128 v[62:65], v23 offset:19008
	v_perm_b32 v21, v32, v21, s65
	s_waitcnt lgkmcnt(3)
	v_mfma_f32_16x16x32_bf16 v[66:69], v[14:17], v[26:29], 0
	v_lshlrev_b32_e32 v42, 16, v31
	ds_read2_b32 v[30:31], v30 offset0:224 offset1:240
	ds_read_b128 v[104:107], v23 offset:28224
	ds_read2_b32 v[36:37], v58 offset0:32 offset1:48
	ds_read2_b32 v[32:33], v58 offset0:96 offset1:112
	ds_read2_b32 v[26:27], v58 offset0:160 offset1:176
	s_waitcnt lgkmcnt(6)
	v_mfma_f32_16x16x32_bf16 v[54:57], v[14:17], v[54:57], 0
	v_lshlrev_b32_e32 v71, 16, v49
	v_lshlrev_b32_e32 v122, 16, v122
	v_lshlrev_b32_e32 v123, 16, v123
	s_waitcnt lgkmcnt(5)
	v_mfma_f32_16x16x32_bf16 v[62:65], v[18:21], v[62:65], v[66:69]
	s_nop 2
	ds_read_b32 v66, v93 offset:57088
	ds_read_u16 v128, v92 offset:432
	ds_read_u16 v102, v92 offset:576
	ds_read_u16 v29, v92 offset:720
	ds_read_u16 v1, v92 offset:864
	v_mov_b32_e32 v67, v46
	s_waitcnt lgkmcnt(4)
	v_add_f32_e32 v28, v62, v66
	v_mfma_f32_16x16x32_bf16 v[56:59], v[18:21], v[104:107], v[54:57]
	ds_read_b32 v217, v93 offset:57344
	ds_read_b32 v218, v93 offset:57600
	ds_read_b32 v219, v93 offset:57152
	ds_read_b128 v[198:201], v23 offset:21248
	ds_read_b128 v[202:205], v23 offset:21312
	ds_read_b128 v[206:209], v23 offset:30464
	ds_read_b128 v[210:213], v23 offset:30528
	s_nop 2
	v_mul_f32_e32 v28, 0xbfb8aa3b, v28
	v_exp_f32_e32 v28, v28
	s_waitcnt lgkmcnt(1)
	v_add_f32_e32 v56, v56, v217
	v_mul_f32_e32 v56, 0xbfb8aa3b, v56
	v_exp_f32_e32 v56, v56
	v_add_f32_e32 v28, 1.0, v28
	v_rcp_f32_e32 v62, v28
	v_lshlrev_b32_e32 v28, 16, v1
	v_add_f32_e32 v1, 1.0, v56
	v_rcp_f32_e32 v129, v1
	s_waitcnt lgkmcnt(0)
	v_mul_f32_e32 v1, v62, v218
	v_mul_f32_e32 v1, 0xbfb8aa3b, v1
	v_exp_f32_e32 v56, v1
	v_add_f32_e32 v1, v63, v66
	v_mul_f32_e32 v1, 0xbfb8aa3b, v1
	v_exp_f32_e32 v1, v1
	v_add_f32_e32 v57, v57, v217
	v_sub_f32_e32 v62, 1.0, v56
	v_add_f32_e32 v63, 1.0, v56
	v_add_f32_e32 v1, 1.0, v1
	v_rcp_f32_e32 v1, v1
	v_mul_f32_e32 v57, 0xbfb8aa3b, v57
	v_mul_f32_e32 v62, v62, v63
	v_exp_f32_e32 v57, v57
	v_mul_f32_e32 v1, v1, v218
	v_mul_f32_e32 v1, 0xbfb8aa3b, v1
	v_exp_f32_e32 v130, v1
	v_sqrt_f32_e32 v1, v62
	v_add_f32_e32 v62, v64, v66
	v_mul_f32_e32 v62, 0xbfb8aa3b, v62
	v_exp_f32_e32 v62, v62
	v_add_f32_e32 v57, 1.0, v57
	v_rcp_f32_e32 v131, v57
	v_sub_f32_e32 v57, 1.0, v130
	v_add_f32_e32 v63, 1.0, v130
	v_mul_f32_e32 v57, v57, v63
	v_sqrt_f32_e32 v63, v57
	v_add_f32_e32 v57, 1.0, v62
	v_rcp_f32_e32 v57, v57
	v_add_f32_e32 v58, v58, v217
	v_mul_f32_e32 v58, 0xbfb8aa3b, v58
	v_exp_f32_e32 v58, v58
	v_mul_f32_e32 v57, v57, v218
	v_mul_f32_e32 v57, 0xbfb8aa3b, v57
	v_exp_f32_e32 v105, v57
	v_add_f32_e32 v62, v65, v66
	v_mul_f32_e32 v62, 0xbfb8aa3b, v62
	v_exp_f32_e32 v62, v62
	v_add_f32_e32 v58, 1.0, v58
	v_rcp_f32_e32 v132, v58
	v_sub_f32_e32 v58, 1.0, v105
	v_add_f32_e32 v64, 1.0, v105
	v_mul_f32_e32 v58, v58, v64
	v_sqrt_f32_e32 v65, v58
	v_add_f32_e32 v58, 1.0, v62
	v_rcp_f32_e32 v58, v58
	v_add_f32_e32 v54, v59, v217
	v_mul_f32_e32 v54, 0xbfb8aa3b, v54
	v_exp_f32_e32 v54, v54
	v_mul_f32_e32 v55, v58, v218
	v_mul_f32_e32 v55, 0xbfb8aa3b, v55
	v_exp_f32_e32 v59, v55
	v_add_f32_e32 v54, 1.0, v54
	v_rcp_f32_e32 v58, v54
	v_mov_b32_e32 v66, v40
	v_sub_f32_e32 v54, 1.0, v59
	v_add_f32_e32 v55, 1.0, v59
	v_mul_f32_e32 v54, v54, v55
	v_sqrt_f32_e32 v133, v54
	v_lshlrev_b32_e32 v55, 16, v60
; template <bool PHASE_B>
; __device__ __forceinline__ void lru_item(const Params& p, LAS unsigned char* lds, int ci, int ci_next, int jb, const int tid, v4u (&xvn)[3]) {
;     ...
;     for (int ct = 0; ct < 4; ++ct) { const int ch = 16 * ct + fr; float xr7[7];
; #pragma unroll
;         for (int j = 0; j < 7; ++j) xr7[j] = __builtin_bit_cast(float, (unsigned)(*(const LAS bf16*)(lds + LR_XR + (16 * rt + 4 * fq + j) * 144 + ch * 2)) << 16);
;         const float w0 = CW[ch], w1 = CW[64 + ch], w2 = CW[128 + ch], w3 = CW[192 + ch], b = CB[ch];
; #pragma unroll
;         for (int e = 0; e < 4; ++e) xc[ct][e] = b + xr7[e] * w0 + xr7[e + 1] * w1 + xr7[e + 2] * w2 + xr7[e + 3] * w3; }
;     float av[2][4][4], uv[2][4][4], pA[2][4], pH[2][4];
; #pragma unroll
;     for (int dir = 0; dir < 2; ++dir) {
; #pragma unroll
;         for (int ct = 0; ct < 4; ++ct) {
;             f32x4 ga = (f32x4){0.f, 0.f, 0.f, 0.f}, gx = (f32x4){0.f, 0.f, 0.f, 0.f};
; #pragma unroll
;             for (int ks = 0; ks < 2; ++ks) {
;                 const bf16x8 wa = *(const LAS bf16x8*)(lds + LR_WG + ((dir * 2 + 0) * 64 + 16 * ct + fr) * 144 + (32 * ks + 8 * fq) * 2);
;                 const bf16x8 wx = *(const LAS bf16x8*)(lds + LR_WG + ((dir * 2 + 1) * 64 + 16 * ct + fr) * 144 + (32 * ks + 8 * fq) * 2);
;                 ga = MFMA16(af[ks], wa, ga); gx = MFMA16(af[ks], wx, gx); }
;             const int ch = 16 * ct + fr; const float bav = GC[(dir * 3 + 0) * 64 + ch], bxv = GC[(dir * 3 + 1) * 64 + ch], c8 = GC[(dir * 3 + 2) * 64 + ch];
;             float Al = 1.f, Hl = 0.f;
; #pragma unroll
;             for (int ee = 0; ee < 4; ++ee) { const int e = dir ? 3 - ee : ee;
;                 const float r = __builtin_amdgcn_rcpf(1.f + __expf(-(ga[e] + bav))), ig = __builtin_amdgcn_rcpf(1.f + __expf(-(gx[e] + bxv)));
;                 const float la = -c8 * r; const float a = __expf(la); const float u = __builtin_amdgcn_sqrtf((1.f - a) * (1.f + a)) * (ig * xc[ct][e]);
;                 av[dir][ct][e] = a; uv[dir][ct][e] = u; Hl = a * Hl + u; Al *= a; }
;             const int o = dir ? 3 - fq : fq; const bool odd = (o & 1) != 0, hi2 = (o & 2) != 0;
;             const float A1 = __shfl_xor(Al, 16), H1 = __shfl_xor(Hl, 16);
;             const float pxA = odd ? A1 : 1.f, pxH = odd ? H1 : 0.f;
;             const float gA = Al * A1, gH = odd ? (Al * H1 + Hl) : (A1 * Hl + H1);
	v_lshlrev_b32_e32 v54, 16, v70
	v_lshlrev_b32_e32 v70, 16, v51
	v_pk_mul_f32 v[106:107], v[66:67], v[70:71]
	v_pk_mov_b32 v[70:71], v[54:55], v[70:71] op_sel:[1,0]
	v_pk_mul_f32 v[68:69], v[66:67], v[54:55]
	v_pk_mul_f32 v[66:67], v[66:67], v[70:71]
	v_add_f32_e32 v49, v107, v34
	v_add_f32_e32 v51, v67, v34
	v_mov_b32_e32 v62, v40
	v_add_f32_e32 v40, v69, v34
	v_fma_f32 v108, v46, v54, v34
	v_add_f32_e32 v34, v106, v49
	v_add_f32_e32 v46, v66, v51
	v_lshlrev_b32_e32 v107, 16, v109
	v_lshlrev_b32_e32 v106, 16, v110
	v_mov_b32_e32 v66, v44
	v_mov_b32_e32 v67, v52
	v_pk_mul_f32 v[110:111], v[66:67], v[54:55]
	v_pk_mov_b32 v[54:55], v[106:107], v[54:55] op_sel:[1,0]
	v_add_f32_e32 v40, v68, v40
	v_pk_mul_f32 v[112:113], v[66:67], v[54:55]
	v_pk_mul_f32 v[114:115], v[66:67], v[106:107]
	v_add_f32_e32 v49, v113, v46
	v_lshlrev_b32_e32 v67, 16, v118
	v_lshlrev_b32_e32 v66, 16, v119
	v_mov_b32_e32 v46, v41
	v_lshlrev_b32_e32 v68, 16, v117
	v_lshlrev_b32_e32 v69, 16, v116
	v_pk_mul_f32 v[70:71], v[46:47], v[68:69]
	v_pk_mov_b32 v[68:69], v[66:67], v[68:69] op_sel:[1,0]
	v_mul_f32_e32 v57, v56, v130
	v_pk_mul_f32 v[68:69], v[46:47], v[68:69]
	v_mul_f32_e32 v57, v105, v57
	v_mul_f32_e32 v104, v52, v106
	v_pk_mul_f32 v[54:55], v[46:47], v[66:67]
	v_add_f32_e32 v52, v71, v35
	v_add_f32_e32 v46, v69, v35
	v_mov_b32_e32 v64, v44
	v_mul_f32_e32 v44, v59, v57
	v_add_f32_e32 v113, v115, v40
	v_add_f32_e32 v40, v55, v35
	v_fmac_f32_e32 v35, v47, v66
	v_add_f32_e32 v55, v70, v52
	v_add_f32_e32 v57, v68, v46
	v_lshlrev_b32_e32 v47, 16, v120
	v_lshlrev_b32_e32 v46, 16, v121
	v_mov_b32_e32 v52, v45
	v_add_f32_e32 v34, v111, v34
	v_pk_mul_f32 v[70:71], v[52:53], v[66:67]
	v_pk_mov_b32 v[66:67], v[46:47], v[66:67] op_sel:[1,0]
	v_add_f32_e32 v34, v110, v34
	v_pk_mul_f32 v[68:69], v[52:53], v[66:67]
	v_add_f32_e32 v40, v54, v40
	v_add_f32_e32 v69, v69, v57
	v_mul_f32_e32 v57, v34, v129
	v_mul_f32_e32 v54, v53, v46
	v_pk_mul_f32 v[66:67], v[52:53], v[46:47]
	v_pk_mul_f32 v[52:53], v[56:57], v[0:1]
	v_add_f32_e32 v67, v67, v40
	v_add_f32_e32 v1, v52, v53
	v_add_f32_e32 v40, v112, v49
	v_mul_f32_e32 v109, v130, v1
	v_mul_f32_e32 v53, v40, v131
	v_mov_b32_e32 v52, v107
	v_pk_fma_f32 v[52:53], v[62:63], v[52:53], v[108:109]
	v_add_f32_e32 v46, v114, v113
	v_pk_add_f32 v[56:57], v[104:105], v[52:53]
	v_pk_mul_f32 v[52:53], v[104:105], v[52:53]
	v_mul_f32_e32 v49, v46, v132
	v_mov_b32_e32 v57, v53
	v_pk_fma_f32 v[52:53], v[64:65], v[48:49], v[56:57]
	v_pk_mul_f32 v[48:49], v[52:53], v[58:59]
	v_lshlrev_b32_e32 v121, 16, v124
	v_fmac_f32_e32 v49, v48, v133
	s_waitcnt lgkmcnt(0)
	v_mov_b32_e32 v249, v44
	v_mov_b32_e32 v51, v44
	s_nop 1
	v_permlane16_swap_b32_e32 v51, v249
	v_cndmask_b32_e64 v51, v249, v51, s[98:99]
	v_mul_f32_e32 v60, v44, v51
	v_lshlrev_b32_e32 v120, 16, v125
	v_mov_b32_e32 v116, v30
	s_waitcnt lgkmcnt(0)
	v_mov_b32_e32 v249, v49
	v_mov_b32_e32 v1, v49
	s_nop 1
	v_permlane16_swap_b32_e32 v1, v249
	v_cndmask_b32_e64 v1, v249, v1, s[98:99]
	v_fma_f32 v44, v44, v1, v49
	v_fmac_f32_e32 v1, v49, v51
	v_cndmask_b32_e64 v1, v44, v1, s[42:43]
	v_mov_b32_e32 v117, v38
	v_pk_mul_f32 v[58:59], v[116:117], v[122:123]
	v_pk_mov_b32 v[56:57], v[120:121], v[122:123] op_sel:[1,0]
	v_pk_mul_f32 v[118:119], v[116:117], v[120:121]
	v_add_f32_e32 v48, v59, v26
	v_pk_mul_f32 v[62:63], v[116:117], v[56:57]
	v_add_f32_e32 v71, v71, v55
	v_add_f32_e32 v55, v119, v26
	v_add_f32_e32 v49, v63, v26
	v_fma_f32 v56, v38, v120, v26
	v_add_f32_e32 v26, v58, v48
	s_waitcnt lgkmcnt(0)
	v_mov_b32_e32 v249, v60
	v_mov_b32_e32 v111, v60
	s_nop 1
	v_permlane32_swap_b32_e32 v111, v249
	v_cndmask_b32_e64 v111, v249, v111, s[100:101]
	v_mov_b32_e32 v249, v1
	v_mov_b32_e32 v44, v1
	s_nop 1
	v_permlane32_swap_b32_e32 v44, v249
	v_cndmask_b32_e64 v44, v249, v44, s[100:101]
	v_fma_f32 v48, v60, v44, v1
	v_fmac_f32_e32 v44, v1, v111
	v_mul_f32_e32 v106, v60, v111
	v_cndmask_b32_e64 v107, v48, v44, s[44:45]
	ds_write_b64 v86, v[106:107] offset:58624
	v_add_f32_e32 v38, v62, v49
	s_waitcnt lgkmcnt(1)
	v_mfma_f32_16x16x32_bf16 v[112:115], v[14:17], v[198:201], 0
	v_mov_b32_e32 v122, v32
	v_mov_b32_e32 v123, v36
	v_lshlrev_b32_e32 v58, 16, v127
	v_pk_mul_f32 v[62:63], v[122:123], v[120:121]
	v_add_f32_e32 v53, v118, v55
	v_mul_f32_e32 v60, v36, v58
	v_add_f32_e32 v36, v63, v26
	s_waitcnt lgkmcnt(1)
	v_mfma_f32_16x16x32_bf16 v[108:111], v[18:21], v[202:205], v[112:115]
	ds_read_b32 v51, v93 offset:57408
	ds_read_b32 v57, v93 offset:57664
	v_lshlrev_b32_e32 v59, 16, v126
	v_pk_mov_b32 v[48:49], v[58:59], v[120:121] op_sel:[1,0]
	v_mfma_f32_16x16x32_bf16 v[104:107], v[14:17], v[206:209], 0
	s_waitcnt lgkmcnt(2)
	s_nop 1
	v_add_f32_e32 v1, v108, v219
	v_mul_f32_e32 v1, 0xbfb8aa3b, v1
	v_exp_f32_e32 v1, v1
	v_mfma_f32_16x16x32_bf16 v[104:107], v[18:21], v[210:213], v[104:107]
	ds_read_b32 v220, v93 offset:57216
	ds_read_b128 v[198:201], v23 offset:23552
	ds_read_b128 v[202:205], v23 offset:23616
	ds_read_b128 v[206:209], v23 offset:32768
	ds_read_b128 v[210:213], v23 offset:32832
	v_mul_f32_e64 v64, v122, v48
	v_mul_f32_e64 v65, v123, v49
	v_lshlrev_b32_e32 v117, 16, v103
	v_add_f32_e32 v1, 1.0, v1
	v_rcp_f32_e32 v1, v1
	v_lshlrev_b32_e32 v116, 16, v128
	s_waitcnt lgkmcnt(1)
	s_nop 0
	v_add_f32_e32 v44, v104, v51
	v_mul_f32_e32 v44, 0xbfb8aa3b, v44
	v_exp_f32_e32 v44, v44
	s_waitcnt lgkmcnt(0)
; #define LAS __attribute__((address_space(3)))
; #define MFMA16(a, b, c) __builtin_amdgcn_mfma_f32_16x16x32_bf16(a, b, c, 0, 0, 0)
; template <bool PHASE_B>
; __device__ __forceinline__ void lru_item(const Params& p, LAS unsigned char* lds, int ci, int ci_next, int jb, const int tid, v4u (&xvn)[3]) {
;     ...
;             for (int ks = 0; ks < 2; ++ks) {
;                 const bf16x8 wa = *(const LAS bf16x8*)(lds + LR_WG + ((dir * 2 + 0) * 64 + 16 * ct + fr) * 144 + (32 * ks + 8 * fq) * 2);
;                 const bf16x8 wx = *(const LAS bf16x8*)(lds + LR_WG + ((dir * 2 + 1) * 64 + 16 * ct + fr) * 144 + (32 * ks + 8 * fq) * 2);
;                 ga = MFMA16(af[ks], wa, ga); gx = MFMA16(af[ks], wx, gx); }
;             const int ch = 16 * ct + fr; const float bav = GC[(dir * 3 + 0) * 64 + ch], bxv = GC[(dir * 3 + 1) * 64 + ch], c8 = GC[(dir * 3 + 2) * 64 + ch];
;             float Al = 1.f, Hl = 0.f;
; #pragma unroll
;             for (int ee = 0; ee < 4; ++ee) { const int e = dir ? 3 - ee : ee;
;                 const float r = __builtin_amdgcn_rcpf(1.f + __expf(-(ga[e] + bav))), ig = __builtin_amdgcn_rcpf(1.f + __expf(-(gx[e] + bxv)));
;                 const float la = -c8 * r; const float a = __expf(la); const float u = __builtin_amdgcn_sqrtf((1.f - a) * (1.f + a)) * (ig * xc[ct][e]);
;                 av[dir][ct][e] = a; uv[dir][ct][e] = u; Hl = a * Hl + u; Al *= a; }
;             const int o = dir ? 3 - fq : fq; const bool odd = (o & 1) != 0, hi2 = (o & 2) != 0;
;             const float A1 = __shfl_xor(Al, 16), H1 = __shfl_xor(Hl, 16);
;             const float pxA = odd ? A1 : 1.f, pxH = odd ? H1 : 0.f;
;             const float gA = Al * A1, gH = odd ? (Al * H1 + Hl) : (A1 * Hl + H1);
;             const float A2 = __shfl_xor(gA, 32), H2 = __shfl_xor(gH, 32);
;             const float PA = hi2 ? pxA * A2 : pxA, PH = hi2 ? (pxA * H2 + pxH) : pxH;
;             const float TA = gA * A2, TH = hi2 ? (gA * H2 + gH) : (A2 * gH + H2);
;             pA[dir][ct] = PA; pH[dir][ct] = PH;
;             ((LAS f32x2*)(lds + LR_SEG))[(dir * 8 + rt) * 64 + ch] = (f32x2){TA, TH};
	v_mul_f32_e32 v1, v1, v57
	v_mul_f32_e32 v1, 0xbfb8aa3b, v1
	v_add_f32_e32 v44, 1.0, v44
	v_rcp_f32_e32 v63, v44
	v_exp_f32_e32 v44, v1
	v_add_f32_e32 v1, v109, v219
	v_mul_f32_e32 v1, 0xbfb8aa3b, v1
	v_exp_f32_e32 v1, v1
	v_sub_f32_e32 v48, 1.0, v44
	v_add_f32_e32 v49, 1.0, v44
	v_mul_f32_e32 v48, v48, v49
	v_add_f32_e32 v1, 1.0, v1
	v_rcp_f32_e32 v1, v1
	v_add_f32_e32 v49, v105, v51
	v_mul_f32_e32 v49, 0xbfb8aa3b, v49
	v_exp_f32_e32 v49, v49
	v_mul_f32_e32 v1, v1, v57
	v_mul_f32_e32 v1, 0xbfb8aa3b, v1
	v_exp_f32_e32 v108, v1
	v_sqrt_f32_e32 v1, v48
	v_add_f32_e32 v48, 1.0, v49
	v_add_f32_e32 v49, v110, v219
	v_mul_f32_e32 v49, 0xbfb8aa3b, v49
	v_add_f32_e32 v26, v111, v219
	v_exp_f32_e32 v55, v49
	v_mul_f32_e32 v26, 0xbfb8aa3b, v26
	v_exp_f32_e32 v26, v26
	v_rcp_f32_e32 v109, v48
	v_sub_f32_e32 v48, 1.0, v108
	v_add_f32_e32 v49, 1.0, v108
	v_mul_f32_e32 v48, v48, v49
	v_sqrt_f32_e32 v49, v48
	v_add_f32_e32 v48, 1.0, v55
	v_rcp_f32_e32 v48, v48
	v_add_f32_e32 v26, 1.0, v26
	v_rcp_f32_e32 v26, v26
	v_add_f32_e32 v55, v106, v51
	v_mul_f32_e32 v48, v48, v57
	v_add_f32_e32 v51, v107, v51
	v_mul_f32_e32 v55, 0xbfb8aa3b, v55
	v_mul_f32_e32 v48, 0xbfb8aa3b, v48
	v_mul_f32_e32 v51, 0xbfb8aa3b, v51
	v_mul_f32_e32 v26, v26, v57
	v_exp_f32_e32 v104, v55
	v_exp_f32_e32 v55, v48
	v_exp_f32_e32 v51, v51
	v_mul_f32_e32 v26, 0xbfb8aa3b, v26
	v_exp_f32_e32 v107, v26
	v_mul_f32_e32 v48, v44, v108
	v_mul_f32_e32 v26, v55, v48
	v_add_f32_e32 v48, 1.0, v51
	v_add_f32_e32 v104, 1.0, v104
	v_rcp_f32_e32 v106, v48
	v_sub_f32_e32 v48, 1.0, v107
	v_add_f32_e32 v51, 1.0, v107
	v_rcp_f32_e32 v110, v104
	v_sub_f32_e32 v104, 1.0, v55
	v_add_f32_e32 v105, 1.0, v55
	v_mul_f32_e32 v48, v48, v51
	v_mul_f32_e32 v104, v104, v105
	v_sqrt_f32_e32 v57, v48
	v_mov_b32_e32 v48, v41
	v_mul_f32_e32 v41, v107, v26
	v_add_f32_e32 v26, v70, v71
	v_sqrt_f32_e32 v105, v104
	v_mov_b32_e32 v104, v45
	v_mul_f32_e32 v45, v26, v63
	v_pk_mul_f32 v[44:45], v[44:45], v[0:1]
	v_mov_b32_e32 v70, v35
	v_add_f32_e32 v1, v44, v45
	v_add_f32_e32 v44, v68, v69
	v_mul_f32_e32 v71, v108, v1
	v_mul_f32_e32 v69, v44, v109
	v_mov_b32_e32 v68, v47
	v_pk_fma_f32 v[48:49], v[48:49], v[68:69], v[70:71]
	v_pk_add_f32 v[68:69], v[54:55], v[48:49]
	v_pk_mul_f32 v[48:49], v[54:55], v[48:49]
	v_add_f32_e32 v35, v65, v38
	v_add_f32_e32 v48, v66, v67
	v_mov_b32_e32 v69, v49
	v_mul_f32_e32 v51, v48, v110
	v_pk_fma_f32 v[54:55], v[104:105], v[50:51], v[68:69]
	s_waitcnt lgkmcnt(0)
	v_mov_b32_e32 v249, v41
	v_mov_b32_e32 v111, v41
	s_nop 1
	v_permlane16_swap_b32_e32 v111, v249
	v_cndmask_b32_e64 v111, v249, v111, s[98:99]
	v_mul_f32_e32 v38, v41, v111
	v_pk_mul_f32 v[50:51], v[54:55], v[106:107]
	v_fmac_f32_e32 v51, v50, v57
	v_pk_mul_f32 v[70:71], v[122:123], v[58:59]
	s_waitcnt lgkmcnt(0)
	v_mov_b32_e32 v249, v38
	v_mov_b32_e32 v45, v38
	s_nop 1
	v_permlane32_swap_b32_e32 v45, v249
	v_cndmask_b32_e64 v45, v249, v45, s[100:101]
	v_mul_f32_e32 v50, v38, v45
	v_add_f32_e32 v47, v71, v53
	s_waitcnt lgkmcnt(0)
	v_mov_b32_e32 v249, v51
	v_mov_b32_e32 v1, v51
	s_nop 1
	v_permlane16_swap_b32_e32 v1, v249
	v_cndmask_b32_e64 v1, v249, v1, s[98:99]
	v_fma_f32 v41, v41, v1, v51
	v_fmac_f32_e32 v1, v51, v111
	v_cndmask_b32_e64 v1, v41, v1, s[42:43]
	s_waitcnt lgkmcnt(0)
	v_mov_b32_e32 v249, v1
	v_mov_b32_e32 v41, v1
	s_nop 1
	v_permlane32_swap_b32_e32 v41, v249
	v_cndmask_b32_e64 v41, v249, v41, s[100:101]
	v_fma_f32 v38, v38, v41, v1
	v_fmac_f32_e32 v41, v1, v45
	v_cndmask_b32_e64 v51, v38, v41, s[44:45]
	ds_write_b64 v86, v[50:51] offset:58752
	s_waitcnt lgkmcnt(1)
	v_mfma_f32_16x16x32_bf16 v[66:69], v[14:17], v[198:201], 0
	v_lshlrev_b32_e32 v51, 16, v43
	s_waitcnt lgkmcnt(1)
	v_mfma_f32_16x16x32_bf16 v[66:69], v[18:21], v[202:205], v[66:69]
	v_mov_b32_e32 v38, v31
	v_lshlrev_b32_e32 v50, 16, v61
	v_pk_mul_f32 v[120:121], v[38:39], v[50:51]
	v_mfma_f32_16x16x32_bf16 v[104:107], v[14:17], v[206:209], 0
	v_pk_mov_b32 v[50:51], v[116:117], v[50:51] op_sel:[1,0]
	s_waitcnt lgkmcnt(0)
	s_nop 1
	v_add_f32_e32 v1, v66, v220
	v_mul_f32_e32 v1, 0xbfb8aa3b, v1
	v_pk_mul_f32 v[118:119], v[38:39], v[116:117]
	v_pk_mul_f32 v[108:109], v[38:39], v[50:51]
	v_mfma_f32_16x16x32_bf16 v[104:107], v[18:21], v[210:213], v[104:107]
	ds_read_b32 v214, v93 offset:57472
	ds_read_b32 v215, v93 offset:57728
	ds_read_b32 v216, v93 offset:57280
	ds_read_b128 v[198:201], v23 offset:25856
	ds_read_b128 v[202:205], v23 offset:25920
	ds_read_b128 v[206:209], v23 offset:35072
	ds_read_b128 v[210:213], v23 offset:35136
	v_exp_f32_e32 v1, v1
	v_add_f32_e32 v61, v68, v220
	v_mul_f32_e32 v61, 0xbfb8aa3b, v61
	s_waitcnt lgkmcnt(1)
	s_nop 1
	v_add_f32_e32 v50, v104, v214
	v_add_f32_e32 v1, 1.0, v1
	v_mul_f32_e32 v50, 0xbfb8aa3b, v50
	v_rcp_f32_e32 v1, v1
	v_exp_f32_e32 v50, v50
	v_exp_f32_e32 v61, v61
	v_mov_b32_e32 v68, v32
	s_waitcnt lgkmcnt(0)
; #define LAS __attribute__((address_space(3)))
; template <bool PHASE_B>
; __device__ __forceinline__ void lru_item(const Params& p, LAS unsigned char* lds, int ci, int ci_next, int jb, const int tid, v4u (&xvn)[3]) {
;     ...
;             const int ch = 16 * ct + fr; const float bav = GC[(dir * 3 + 0) * 64 + ch], bxv = GC[(dir * 3 + 1) * 64 + ch], c8 = GC[(dir * 3 + 2) * 64 + ch];
;             float Al = 1.f, Hl = 0.f;
; #pragma unroll
;             for (int ee = 0; ee < 4; ++ee) { const int e = dir ? 3 - ee : ee;
;                 const float r = __builtin_amdgcn_rcpf(1.f + __expf(-(ga[e] + bav))), ig = __builtin_amdgcn_rcpf(1.f + __expf(-(gx[e] + bxv)));
;                 const float la = -c8 * r; const float a = __expf(la); const float u = __builtin_amdgcn_sqrtf((1.f - a) * (1.f + a)) * (ig * xc[ct][e]);
;                 av[dir][ct][e] = a; uv[dir][ct][e] = u; Hl = a * Hl + u; Al *= a; }
;             const int o = dir ? 3 - fq : fq; const bool odd = (o & 1) != 0, hi2 = (o & 2) != 0;
;             const float A1 = __shfl_xor(Al, 16), H1 = __shfl_xor(Hl, 16);
;             const float pxA = odd ? A1 : 1.f, pxH = odd ? H1 : 0.f;
;             const float gA = Al * A1, gH = odd ? (Al * H1 + Hl) : (A1 * Hl + H1);
;             const float A2 = __shfl_xor(gA, 32), H2 = __shfl_xor(gH, 32);
;             const float PA = hi2 ? pxA * A2 : pxA, PH = hi2 ? (pxA * H2 + pxH) : pxH;
;             const float TA = gA * A2, TH = hi2 ? (gA * H2 + gH) : (A2 * gH + H2);
;             pA[dir][ct] = PA; pH[dir][ct] = PH;
;             ((LAS f32x2*)(lds + LR_SEG))[(dir * 8 + rt) * 64 + ch] = (f32x2){TA, TH};
	v_mul_f32_e32 v1, v1, v215
	v_add_f32_e32 v50, 1.0, v50
	v_mul_f32_e32 v1, 0xbfb8aa3b, v1
	v_rcp_f32_e32 v51, v50
	v_exp_f32_e32 v50, v1
	v_add_f32_e32 v1, v67, v220
	v_mul_f32_e32 v1, 0xbfb8aa3b, v1
	v_exp_f32_e32 v1, v1
	v_sub_f32_e32 v55, 1.0, v50
	v_add_f32_e32 v57, 1.0, v50
	v_mul_f32_e32 v55, v55, v57
	v_add_f32_e32 v1, 1.0, v1
	v_rcp_f32_e32 v1, v1
	v_add_f32_e32 v57, v105, v214
	v_mul_f32_e32 v57, 0xbfb8aa3b, v57
	v_exp_f32_e32 v57, v57
	v_mul_f32_e32 v1, v1, v215
	v_mul_f32_e32 v1, 0xbfb8aa3b, v1
	v_exp_f32_e32 v58, v1
	v_add_f32_e32 v43, v69, v220
	v_mul_f32_e32 v43, 0xbfb8aa3b, v43
	v_sqrt_f32_e32 v1, v55
	v_add_f32_e32 v55, 1.0, v57
	v_sub_f32_e32 v57, 1.0, v58
	v_add_f32_e32 v63, 1.0, v58
	v_exp_f32_e32 v43, v43
	v_mul_f32_e32 v57, v57, v63
	v_sqrt_f32_e32 v67, v57
	v_add_f32_e32 v57, 1.0, v61
	v_rcp_f32_e32 v57, v57
	v_add_f32_e32 v43, 1.0, v43
	v_rcp_f32_e32 v43, v43
	v_add_f32_e32 v61, v106, v214
	v_mul_f32_e32 v57, v57, v215
	v_mul_f32_e32 v61, 0xbfb8aa3b, v61
	v_mul_f32_e32 v57, 0xbfb8aa3b, v57
	v_add_f32_e32 v38, v107, v214
	v_exp_f32_e32 v63, v61
	v_exp_f32_e32 v61, v57
	v_mul_f32_e32 v38, 0xbfb8aa3b, v38
	v_mul_f32_e32 v43, v43, v215
	v_exp_f32_e32 v38, v38
	v_mul_f32_e32 v43, 0xbfb8aa3b, v43
	v_exp_f32_e32 v105, v43
	v_sub_f32_e32 v65, 1.0, v61
	v_add_f32_e32 v66, 1.0, v61
	v_rcp_f32_e32 v55, v55
	v_mul_f32_e32 v65, v65, v66
	v_add_f32_e32 v38, 1.0, v38
	v_mov_b32_e32 v66, v30
	v_add_f32_e32 v30, v62, v36
	v_rcp_f32_e32 v104, v38
	v_sub_f32_e32 v38, 1.0, v105
	v_add_f32_e32 v49, 1.0, v105
	v_mul_f32_e32 v51, v30, v51
	v_mul_f32_e32 v57, v50, v58
	v_mul_f32_e32 v38, v38, v49
	v_pk_mul_f32 v[50:51], v[50:51], v[0:1]
	v_add_f32_e32 v63, 1.0, v63
	v_sqrt_f32_e32 v49, v38
	v_add_f32_e32 v1, v50, v51
	v_add_f32_e32 v38, v64, v35
	v_rcp_f32_e32 v63, v63
	v_mul_f32_e32 v43, v61, v57
	v_mul_f32_e32 v57, v58, v1
	v_mul_f32_e32 v51, v38, v55
	v_mov_b32_e32 v50, v59
	v_sqrt_f32_e32 v69, v65
	v_pk_fma_f32 v[50:51], v[66:67], v[50:51], v[56:57]
	v_mul_f32_e32 v32, v105, v43
	v_pk_add_f32 v[56:57], v[60:61], v[50:51]
	v_pk_mul_f32 v[50:51], v[60:61], v[50:51]
	v_add_f32_e32 v50, v70, v47
	v_mov_b32_e32 v57, v51
	v_mul_f32_e32 v43, v50, v63
	v_pk_fma_f32 v[56:57], v[68:69], v[42:43], v[56:57]
	s_waitcnt lgkmcnt(0)
	v_mov_b32_e32 v249, v32
	v_mov_b32_e32 v65, v32
	s_nop 1
	v_permlane16_swap_b32_e32 v65, v249
	v_cndmask_b32_e64 v65, v249, v65, s[98:99]
	v_mul_f32_e32 v36, v32, v65
	v_pk_mul_f32 v[42:43], v[56:57], v[104:105]
	v_add_f32_e32 v41, v119, v27
	v_fmac_f32_e32 v43, v42, v49
	v_add_f32_e32 v45, v121, v27
	v_add_f32_e32 v53, v109, v27
	v_fmac_f32_e32 v27, v39, v116
	s_waitcnt lgkmcnt(0)
	v_mov_b32_e32 v249, v43
	v_mov_b32_e32 v1, v43
	s_nop 1
	v_permlane16_swap_b32_e32 v1, v249
	v_cndmask_b32_e64 v1, v249, v1, s[98:99]
	v_fma_f32 v32, v32, v1, v43
	v_fmac_f32_e32 v1, v43, v65
	v_cndmask_b32_e64 v1, v32, v1, s[42:43]
	s_waitcnt lgkmcnt(0)
	v_mov_b32_e32 v249, v36
	v_mov_b32_e32 v39, v36
	s_nop 1
	v_permlane32_swap_b32_e32 v39, v249
	v_cndmask_b32_e64 v39, v249, v39, s[100:101]
	v_mul_f32_e32 v58, v36, v39
	v_lshlrev_b32_e32 v43, 16, v102
	v_lshlrev_b32_e32 v42, 16, v29
	v_add_f32_e32 v35, v120, v45
	s_waitcnt lgkmcnt(0)
	v_mov_b32_e32 v249, v1
	v_mov_b32_e32 v32, v1
	s_nop 1
	v_permlane32_swap_b32_e32 v32, v249
	v_cndmask_b32_e64 v32, v249, v32, s[100:101]
	v_fma_f32 v36, v36, v32, v1
	v_fmac_f32_e32 v32, v1, v39
	v_cndmask_b32_e64 v59, v36, v32, s[44:45]
	ds_write_b64 v86, v[58:59] offset:58880
	s_waitcnt lgkmcnt(1)
	v_mfma_f32_16x16x32_bf16 v[58:61], v[14:17], v[198:201], 0
	v_add_f32_e32 v45, v108, v53
	s_waitcnt lgkmcnt(1)
	v_mfma_f32_16x16x32_bf16 v[58:61], v[18:21], v[202:205], v[58:61]
	v_mov_b32_e32 v36, v33
	v_pk_mov_b32 v[108:109], v[42:43], v[116:117] op_sel:[1,0]
	v_mul_f32_e32 v70, v37, v42
	v_mfma_f32_16x16x32_bf16 v[62:65], v[14:17], v[206:209], 0
	v_mul_f32_e64 v106, v36, v116
	v_mul_f32_e64 v107, v37, v117
	s_waitcnt lgkmcnt(0)
	s_nop 0
	v_add_f32_e32 v1, v58, v216
	v_mul_f32_e32 v1, 0xbfb8aa3b, v1
	v_pk_mul_f32 v[108:109], v[36:37], v[108:109]
	v_pk_mul_f32 v[66:67], v[36:37], v[42:43]
	v_mfma_f32_16x16x32_bf16 v[62:65], v[18:21], v[210:213], v[62:65]
	ds_read_b32 v217, v93 offset:57536
	ds_read_b32 v218, v93 offset:57792
	ds_read_b32 v219, v93 offset:57856
	ds_read_b128 v[198:201], v23 offset:37376
	ds_read_b128 v[202:205], v23 offset:37440
	ds_read_b128 v[206:209], v23 offset:46592
	ds_read_b128 v[210:213], v23 offset:46656
	v_exp_f32_e32 v1, v1
	v_add_f32_e32 v29, v107, v35
	v_add_f32_e32 v35, v109, v45
	s_waitcnt lgkmcnt(1)
	s_nop 1
	v_add_f32_e32 v36, v62, v217
	v_add_f32_e32 v1, 1.0, v1
	v_mul_f32_e32 v36, 0xbfb8aa3b, v36
	v_rcp_f32_e32 v1, v1
	v_exp_f32_e32 v36, v36
	v_add_f32_e32 v51, v60, v216
	v_mul_f32_e32 v51, 0xbfb8aa3b, v51
	s_waitcnt lgkmcnt(0)
; #define LAS __attribute__((address_space(3)))
; #define MFMA16(a, b, c) __builtin_amdgcn_mfma_f32_16x16x32_bf16(a, b, c, 0, 0, 0)
; template <bool PHASE_B>
; __device__ __forceinline__ void lru_item(const Params& p, LAS unsigned char* lds, int ci, int ci_next, int jb, const int tid, v4u (&xvn)[3]) {
;     ...
;                 const bf16x8 wa = *(const LAS bf16x8*)(lds + LR_WG + ((dir * 2 + 0) * 64 + 16 * ct + fr) * 144 + (32 * ks + 8 * fq) * 2);
;                 const bf16x8 wx = *(const LAS bf16x8*)(lds + LR_WG + ((dir * 2 + 1) * 64 + 16 * ct + fr) * 144 + (32 * ks + 8 * fq) * 2);
;                 ga = MFMA16(af[ks], wa, ga); gx = MFMA16(af[ks], wx, gx); }
;             const int ch = 16 * ct + fr; const float bav = GC[(dir * 3 + 0) * 64 + ch], bxv = GC[(dir * 3 + 1) * 64 + ch], c8 = GC[(dir * 3 + 2) * 64 + ch];
;             float Al = 1.f, Hl = 0.f;
; #pragma unroll
;             for (int ee = 0; ee < 4; ++ee) { const int e = dir ? 3 - ee : ee;
;                 const float r = __builtin_amdgcn_rcpf(1.f + __expf(-(ga[e] + bav))), ig = __builtin_amdgcn_rcpf(1.f + __expf(-(gx[e] + bxv)));
;                 const float la = -c8 * r; const float a = __expf(la); const float u = __builtin_amdgcn_sqrtf((1.f - a) * (1.f + a)) * (ig * xc[ct][e]);
;                 av[dir][ct][e] = a; uv[dir][ct][e] = u; Hl = a * Hl + u; Al *= a; }
;             const int o = dir ? 3 - fq : fq; const bool odd = (o & 1) != 0, hi2 = (o & 2) != 0;
;             const float A1 = __shfl_xor(Al, 16), H1 = __shfl_xor(Hl, 16);
;             const float pxA = odd ? A1 : 1.f, pxH = odd ? H1 : 0.f;
;             const float gA = Al * A1, gH = odd ? (Al * H1 + Hl) : (A1 * Hl + H1);
;             const float A2 = __shfl_xor(gA, 32), H2 = __shfl_xor(gH, 32);
;             const float PA = hi2 ? pxA * A2 : pxA, PH = hi2 ? (pxA * H2 + pxH) : pxH;
;             const float TA = gA * A2, TH = hi2 ? (gA * H2 + gH) : (A2 * gH + H2);
;             pA[dir][ct] = PA; pH[dir][ct] = PH;
;             ((LAS f32x2*)(lds + LR_SEG))[(dir * 8 + rt) * 64 + ch] = (f32x2){TA, TH};
	v_mul_f32_e32 v1, v1, v218
	v_add_f32_e32 v36, 1.0, v36
	v_mul_f32_e32 v1, 0xbfb8aa3b, v1
	v_rcp_f32_e32 v42, v36
	v_exp_f32_e32 v36, v1
	v_add_f32_e32 v1, v59, v216
	v_mul_f32_e32 v1, 0xbfb8aa3b, v1
	v_exp_f32_e32 v1, v1
	v_sub_f32_e32 v45, 1.0, v36
	v_add_f32_e32 v47, 1.0, v36
	v_mul_f32_e32 v45, v45, v47
	v_add_f32_e32 v1, 1.0, v1
	v_rcp_f32_e32 v1, v1
	v_add_f32_e32 v47, v63, v217
	v_mul_f32_e32 v47, 0xbfb8aa3b, v47
	v_exp_f32_e32 v47, v47
	v_mul_f32_e32 v1, v1, v218
	v_mul_f32_e32 v1, 0xbfb8aa3b, v1
	v_exp_f32_e32 v49, v1
	v_add_f32_e32 v32, v61, v216
	v_mul_f32_e32 v32, 0xbfb8aa3b, v32
	v_exp_f32_e32 v51, v51
	v_exp_f32_e32 v32, v32
	v_sqrt_f32_e32 v1, v45
	v_add_f32_e32 v45, 1.0, v47
	v_sub_f32_e32 v47, 1.0, v49
	v_add_f32_e32 v53, 1.0, v49
	v_mul_f32_e32 v47, v47, v53
	v_sqrt_f32_e32 v59, v47
	v_add_f32_e32 v47, 1.0, v51
	v_add_f32_e32 v32, 1.0, v32
	v_rcp_f32_e32 v47, v47
	v_rcp_f32_e32 v32, v32
	v_add_f32_e32 v51, v64, v217
	v_add_f32_e32 v37, v65, v217
	v_mul_f32_e32 v47, v47, v218
	v_mul_f32_e32 v37, 0xbfb8aa3b, v37
	v_mul_f32_e32 v32, v32, v218
	v_mul_f32_e32 v47, 0xbfb8aa3b, v47
	v_exp_f32_e32 v37, v37
	v_mul_f32_e32 v32, 0xbfb8aa3b, v32
	v_exp_f32_e32 v71, v47
	v_exp_f32_e32 v63, v32
	v_mul_f32_e32 v51, 0xbfb8aa3b, v51
	v_mul_f32_e32 v47, v36, v49
	v_add_f32_e32 v37, 1.0, v37
	v_exp_f32_e32 v51, v51
	v_mul_f32_e32 v32, v71, v47
	v_rcp_f32_e32 v62, v37
	v_sub_f32_e32 v37, 1.0, v63
	v_add_f32_e32 v39, 1.0, v63
	v_rcp_f32_e32 v45, v45
	v_mul_f32_e32 v37, v37, v39
	v_mov_b32_e32 v58, v31
	v_mul_f32_e32 v31, v63, v32
	v_add_f32_e32 v32, v106, v29
	v_sqrt_f32_e32 v39, v37
	v_mul_f32_e32 v37, v32, v42
	v_pk_mul_f32 v[36:37], v[36:37], v[0:1]
	v_add_f32_e32 v51, 1.0, v51
	v_sub_f32_e32 v53, 1.0, v71
	v_add_f32_e32 v55, 1.0, v71
	v_add_f32_e32 v1, v36, v37
	v_add_f32_e32 v36, v108, v35
	v_rcp_f32_e32 v51, v51
	v_mul_f32_e32 v53, v53, v55
	v_mul_f32_e32 v65, v49, v1
	v_mov_b32_e32 v64, v27
	v_mul_f32_e32 v69, v36, v45
	v_mov_b32_e32 v68, v43
	v_add_f32_e32 v41, v118, v41
	v_sqrt_f32_e32 v61, v53
	v_pk_fma_f32 v[42:43], v[58:59], v[68:69], v[64:65]
	v_add_f32_e32 v41, v67, v41
	v_pk_add_f32 v[58:59], v[70:71], v[42:43]
	v_pk_mul_f32 v[42:43], v[70:71], v[42:43]
	v_mov_b32_e32 v60, v33
	v_add_f32_e32 v42, v66, v41
	v_mov_b32_e32 v59, v43
	v_mul_f32_e32 v29, v42, v51
	v_pk_fma_f32 v[28:29], v[60:61], v[28:29], v[58:59]
	v_pk_mul_f32 v[58:59], v[28:29], v[62:63]
	s_waitcnt lgkmcnt(0)
	v_mov_b32_e32 v249, v31
	v_mov_b32_e32 v33, v31
	s_nop 1
	v_permlane16_swap_b32_e32 v33, v249
	v_cndmask_b32_e64 v33, v249, v33, s[98:99]
	v_mul_f32_e32 v27, v31, v33
	v_fmac_f32_e32 v59, v58, v39
	s_waitcnt lgkmcnt(0)
	v_mov_b32_e32 v249, v59
	v_mov_b32_e32 v1, v59
	s_nop 1
	v_permlane16_swap_b32_e32 v1, v249
	v_cndmask_b32_e64 v1, v249, v1, s[98:99]
	v_fma_f32 v31, v31, v1, v59
	v_fmac_f32_e32 v1, v59, v33
	v_cndmask_b32_e64 v1, v31, v1, s[42:43]
	s_waitcnt lgkmcnt(0)
	v_mov_b32_e32 v249, v27
	v_mov_b32_e32 v29, v27
	s_nop 1
	v_permlane32_swap_b32_e32 v29, v249
	v_cndmask_b32_e64 v29, v249, v29, s[100:101]
	v_mul_f32_e32 v58, v27, v29
	s_waitcnt lgkmcnt(0)
	v_mov_b32_e32 v249, v1
	v_mov_b32_e32 v31, v1
	s_nop 1
	v_permlane32_swap_b32_e32 v31, v249
	v_cndmask_b32_e64 v31, v249, v31, s[100:101]
	v_fma_f32 v27, v27, v31, v1
	v_fmac_f32_e32 v31, v1, v29
	v_cndmask_b32_e64 v59, v27, v31, s[44:45]
	ds_write_b64 v86, v[58:59] offset:59008
	s_waitcnt lgkmcnt(1)
	v_mfma_f32_16x16x32_bf16 v[58:61], v[14:17], v[198:201], 0
	ds_read_b32 v29, v93 offset:58112
	ds_read_b32 v31, v93 offset:58368
	s_waitcnt lgkmcnt(3)
	v_mfma_f32_16x16x32_bf16 v[58:61], v[18:21], v[202:205], v[58:61]
	s_waitcnt lgkmcnt(3)
	v_mfma_f32_16x16x32_bf16 v[66:69], v[14:17], v[206:209], 0
	s_waitcnt lgkmcnt(3)
	v_mfma_f32_16x16x32_bf16 v[62:65], v[18:21], v[210:213], v[66:69]
	ds_read_b32 v220, v93 offset:57920
	ds_read_b32 v221, v93 offset:58176
	ds_read_b32 v222, v93 offset:58432
	ds_read_b128 v[198:201], v23 offset:39680
	ds_read_b128 v[202:205], v23 offset:39744
	ds_read_b128 v[206:209], v23 offset:48896
	ds_read_b128 v[210:213], v23 offset:48960
	s_waitcnt lgkmcnt(2)
	s_nop 2
	v_add_f32_e32 v1, v61, v219
	v_mul_f32_e32 v1, 0xbfb8aa3b, v1
	v_exp_f32_e32 v1, v1
	s_nop 0
	v_add_f32_e32 v1, 1.0, v1
	v_rcp_f32_e32 v1, v1
	s_waitcnt lgkmcnt(1)
	v_add_f32_e32 v33, v65, v29
	v_mul_f32_e32 v33, 0xbfb8aa3b, v33
	v_exp_f32_e32 v33, v33
	s_waitcnt lgkmcnt(0)
	v_mul_f32_e32 v1, v1, v31
	v_mul_f32_e32 v1, 0xbfb8aa3b, v1
	v_exp_f32_e32 v66, v1
	v_add_f32_e32 v1, 1.0, v33
	v_rcp_f32_e32 v33, v1
	v_sub_f32_e32 v1, 1.0, v66
	v_add_f32_e32 v35, 1.0, v66
	v_mul_f32_e32 v1, v1, v35
	v_add_f32_e32 v35, v60, v219
	v_mul_f32_e32 v35, 0xbfb8aa3b, v35
	v_exp_f32_e32 v35, v35
	v_mul_f32_e32 v67, v52, v33
	v_sqrt_f32_e32 v1, v1
	v_mul_f32_e32 v52, 0, v66
	v_add_f32_e32 v33, 1.0, v35
	v_rcp_f32_e32 v33, v33
	v_add_f32_e32 v35, v64, v29
	v_mul_f32_e32 v35, 0xbfb8aa3b, v35
	v_exp_f32_e32 v35, v35
	v_mul_f32_e32 v33, v33, v31
	v_mul_f32_e32 v33, 0xbfb8aa3b, v33
	v_exp_f32_e32 v53, v33
	s_nop 0
	v_pk_fma_f32 v[60:61], v[66:67], v[0:1], v[52:53] op_sel_hi:[1,1,0]
	v_add_f32_e32 v1, 1.0, v35
	v_rcp_f32_e32 v52, v1
	v_sub_f32_e32 v1, 1.0, v53
	v_add_f32_e32 v33, 1.0, v53
	v_mul_f32_e32 v1, v1, v33
	v_add_f32_e32 v33, v59, v219
	v_mul_f32_e32 v33, 0xbfb8aa3b, v33
	v_sqrt_f32_e32 v1, v1
	v_exp_f32_e32 v33, v33
	v_add_f32_e32 v27, v58, v219
	v_mov_b32_e32 v47, v61
	v_mul_f32_e32 v27, 0xbfb8aa3b, v27
	v_pk_mul_f32 v[46:47], v[46:47], v[52:53]
	v_exp_f32_e32 v27, v27
	v_fmac_f32_e32 v47, v46, v1
	v_add_f32_e32 v1, 1.0, v33
	v_rcp_f32_e32 v1, v1
	v_add_f32_e32 v27, 1.0, v27
	v_add_f32_e32 v33, v63, v29
	v_rcp_f32_e32 v27, v27
	v_mul_f32_e32 v33, 0xbfb8aa3b, v33
	v_mul_f32_e32 v1, v1, v31
	v_exp_f32_e32 v33, v33
	v_mul_f32_e32 v1, 0xbfb8aa3b, v1
	v_exp_f32_e32 v61, v1
	v_add_f32_e32 v29, v62, v29
	v_mul_f32_e32 v29, 0xbfb8aa3b, v29
	v_mul_f32_e32 v27, v27, v31
	v_exp_f32_e32 v29, v29
	v_mul_f32_e32 v27, 0xbfb8aa3b, v27
	v_add_f32_e32 v33, 1.0, v33
	v_mov_b32_e32 v41, v47
	v_exp_f32_e32 v47, v27
	v_rcp_f32_e32 v60, v33
	v_sub_f32_e32 v33, 1.0, v61
	v_add_f32_e32 v35, 1.0, v61
	v_mul_f32_e32 v33, v33, v35
	v_sqrt_f32_e32 v33, v33
	v_add_f32_e32 v27, 1.0, v29
	v_rcp_f32_e32 v46, v27
	v_sub_f32_e32 v27, 1.0, v47
	v_add_f32_e32 v29, 1.0, v47
	v_mul_f32_e32 v27, v27, v29
	v_pk_mul_f32 v[40:41], v[40:41], v[60:61]
	v_sqrt_f32_e32 v27, v27
	v_fmac_f32_e32 v41, v40, v33
	v_mul_f32_e32 v1, v66, v53
	v_mov_b32_e32 v35, v41
	v_mul_f32_e32 v1, v61, v1
	v_pk_mul_f32 v[34:35], v[34:35], v[46:47]
	v_mul_f32_e32 v1, v47, v1
	v_fmac_f32_e32 v35, v34, v27
	s_waitcnt lgkmcnt(0)
; #define LAS __attribute__((address_space(3)))
; #define MFMA16(a, b, c) __builtin_amdgcn_mfma_f32_16x16x32_bf16(a, b, c, 0, 0, 0)
; template <bool PHASE_B>
; __device__ __forceinline__ void lru_item(const Params& p, LAS unsigned char* lds, int ci, int ci_next, int jb, const int tid, v4u (&xvn)[3]) {
;     ...
;                 const bf16x8 wa = *(const LAS bf16x8*)(lds + LR_WG + ((dir * 2 + 0) * 64 + 16 * ct + fr) * 144 + (32 * ks + 8 * fq) * 2);
;                 const bf16x8 wx = *(const LAS bf16x8*)(lds + LR_WG + ((dir * 2 + 1) * 64 + 16 * ct + fr) * 144 + (32 * ks + 8 * fq) * 2);
;                 ga = MFMA16(af[ks], wa, ga); gx = MFMA16(af[ks], wx, gx); }
;             const int ch = 16 * ct + fr; const float bav = GC[(dir * 3 + 0) * 64 + ch], bxv = GC[(dir * 3 + 1) * 64 + ch], c8 = GC[(dir * 3 + 2) * 64 + ch];
;             float Al = 1.f, Hl = 0.f;
; #pragma unroll
;             for (int ee = 0; ee < 4; ++ee) { const int e = dir ? 3 - ee : ee;
;                 const float r = __builtin_amdgcn_rcpf(1.f + __expf(-(ga[e] + bav))), ig = __builtin_amdgcn_rcpf(1.f + __expf(-(gx[e] + bxv)));
;                 const float la = -c8 * r; const float a = __expf(la); const float u = __builtin_amdgcn_sqrtf((1.f - a) * (1.f + a)) * (ig * xc[ct][e]);
;                 av[dir][ct][e] = a; uv[dir][ct][e] = u; Hl = a * Hl + u; Al *= a; }
;             const int o = dir ? 3 - fq : fq; const bool odd = (o & 1) != 0, hi2 = (o & 2) != 0;
;             const float A1 = __shfl_xor(Al, 16), H1 = __shfl_xor(Hl, 16);
;             const float pxA = odd ? A1 : 1.f, pxH = odd ? H1 : 0.f;
;             const float gA = Al * A1, gH = odd ? (Al * H1 + Hl) : (A1 * Hl + H1);
;             const float A2 = __shfl_xor(gA, 32), H2 = __shfl_xor(gH, 32);
;             const float PA = hi2 ? pxA * A2 : pxA, PH = hi2 ? (pxA * H2 + pxH) : pxH;
;             const float TA = gA * A2, TH = hi2 ? (gA * H2 + gH) : (A2 * gH + H2);
;             pA[dir][ct] = PA; pH[dir][ct] = PH;
;             ((LAS f32x2*)(lds + LR_SEG))[(dir * 8 + rt) * 64 + ch] = (f32x2){TA, TH};
	v_mov_b32_e32 v249, v1
	v_mov_b32_e32 v27, v1
	s_nop 1
	v_permlane16_swap_b32_e32 v27, v249
	v_cndmask_b32_e64 v27, v249, v27, s[98:99]
	v_mul_f32_e32 v31, v1, v27
	s_waitcnt lgkmcnt(0)
	v_mov_b32_e32 v249, v35
	v_mov_b32_e32 v29, v35
	s_nop 1
	v_permlane16_swap_b32_e32 v29, v249
	v_cndmask_b32_e64 v29, v249, v29, s[98:99]
	v_fma_f32 v1, v1, v29, v35
	v_fmac_f32_e32 v29, v35, v27
	v_cndmask_b32_e64 v1, v1, v29, s[46:47]
	s_waitcnt lgkmcnt(0)
	v_mov_b32_e32 v249, v31
	v_mov_b32_e32 v27, v31
	s_nop 1
	v_permlane32_swap_b32_e32 v27, v249
	v_cndmask_b32_e64 v27, v249, v27, s[100:101]
	v_mul_f32_e32 v34, v31, v27
	s_waitcnt lgkmcnt(0)
	v_mov_b32_e32 v249, v1
	v_mov_b32_e32 v29, v1
	s_nop 1
	v_permlane32_swap_b32_e32 v29, v249
	v_cndmask_b32_e64 v29, v249, v29, s[100:101]
	v_fma_f32 v31, v31, v29, v1
	v_fmac_f32_e32 v29, v1, v27
	v_cndmask_b32_e64 v35, v31, v29, s[48:49]
	ds_write_b64 v86, v[34:35] offset:62720
	s_waitcnt lgkmcnt(1)
	v_mfma_f32_16x16x32_bf16 v[58:61], v[14:17], v[198:201], 0
	s_waitcnt lgkmcnt(1)
	v_mfma_f32_16x16x32_bf16 v[58:61], v[18:21], v[202:205], v[58:61]
	s_waitcnt lgkmcnt(1)
	v_mfma_f32_16x16x32_bf16 v[66:69], v[14:17], v[206:209], 0
	s_waitcnt lgkmcnt(1)
	v_mfma_f32_16x16x32_bf16 v[62:65], v[18:21], v[210:213], v[66:69]
	ds_read_b32 v214, v93 offset:57984
	ds_read_b32 v215, v93 offset:58240
	ds_read_b32 v216, v93 offset:58496
	ds_read_b128 v[198:201], v23 offset:41984
	ds_read_b128 v[202:205], v23 offset:42048
	ds_read_b128 v[206:209], v23 offset:51200
	ds_read_b128 v[210:213], v23 offset:51264
	s_waitcnt lgkmcnt(2)
	s_nop 2
	v_add_f32_e32 v1, v61, v220
	v_mul_f32_e32 v1, 0xbfb8aa3b, v1
	v_exp_f32_e32 v1, v1
	s_nop 0
	v_add_f32_e32 v1, 1.0, v1
	v_rcp_f32_e32 v1, v1
	s_waitcnt lgkmcnt(1)
	v_add_f32_e32 v33, v65, v221
	v_mul_f32_e32 v33, 0xbfb8aa3b, v33
	v_exp_f32_e32 v33, v33
	s_waitcnt lgkmcnt(0)
	v_mul_f32_e32 v1, v1, v222
	v_mul_f32_e32 v1, 0xbfb8aa3b, v1
	v_exp_f32_e32 v34, v1
	v_add_f32_e32 v1, 1.0, v33
	v_rcp_f32_e32 v33, v1
	v_sub_f32_e32 v1, 1.0, v34
	v_add_f32_e32 v35, 1.0, v34
	v_mul_f32_e32 v1, v1, v35
	v_add_f32_e32 v35, v60, v220
	v_mul_f32_e32 v35, 0xbfb8aa3b, v35
	v_exp_f32_e32 v37, v35
	v_mul_f32_e32 v35, v54, v33
	v_sqrt_f32_e32 v1, v1
	v_mul_f32_e32 v40, 0, v34
	v_add_f32_e32 v33, 1.0, v37
	v_rcp_f32_e32 v33, v33
	v_add_f32_e32 v37, v64, v221
	v_mul_f32_e32 v37, 0xbfb8aa3b, v37
	v_exp_f32_e32 v37, v37
	v_mul_f32_e32 v33, v33, v222
	v_mul_f32_e32 v33, 0xbfb8aa3b, v33
	v_exp_f32_e32 v41, v33
	s_nop 0
	v_pk_fma_f32 v[46:47], v[34:35], v[0:1], v[40:41] op_sel_hi:[1,1,0]
	v_add_f32_e32 v1, 1.0, v37
	v_rcp_f32_e32 v40, v1
	v_sub_f32_e32 v1, 1.0, v41
	v_add_f32_e32 v33, 1.0, v41
	v_mul_f32_e32 v1, v1, v33
	v_add_f32_e32 v33, v59, v220
	v_mul_f32_e32 v33, 0xbfb8aa3b, v33
	v_sqrt_f32_e32 v1, v1
	v_exp_f32_e32 v33, v33
	v_mov_b32_e32 v49, v47
	v_add_f32_e32 v27, v58, v220
	v_pk_mul_f32 v[46:47], v[48:49], v[40:41]
	v_mul_f32_e32 v27, 0xbfb8aa3b, v27
	v_fmac_f32_e32 v47, v46, v1
	v_add_f32_e32 v1, 1.0, v33
	v_add_f32_e32 v33, v63, v221
	v_exp_f32_e32 v27, v27
	v_rcp_f32_e32 v1, v1
	v_mul_f32_e32 v33, 0xbfb8aa3b, v33
	v_exp_f32_e32 v33, v33
	v_add_f32_e32 v27, 1.0, v27
	v_mul_f32_e32 v1, v1, v222
	v_rcp_f32_e32 v27, v27
	v_mul_f32_e32 v1, 0xbfb8aa3b, v1
	v_add_f32_e32 v33, 1.0, v33
	v_exp_f32_e32 v35, v1
	v_mul_f32_e32 v1, v34, v41
	v_rcp_f32_e32 v34, v33
	v_add_f32_e32 v29, v62, v221
	v_mul_f32_e32 v29, 0xbfb8aa3b, v29
	v_mul_f32_e32 v27, v27, v222
	v_mov_b32_e32 v45, v47
	v_exp_f32_e32 v29, v29
	v_mul_f32_e32 v27, 0xbfb8aa3b, v27
	v_pk_mul_f32 v[40:41], v[44:45], v[34:35]
	v_exp_f32_e32 v45, v27
	v_sub_f32_e32 v33, 1.0, v35
	v_add_f32_e32 v37, 1.0, v35
	v_mul_f32_e32 v33, v33, v37
	v_sqrt_f32_e32 v33, v33
	v_add_f32_e32 v27, 1.0, v29
	v_rcp_f32_e32 v44, v27
	v_sub_f32_e32 v27, 1.0, v45
	v_add_f32_e32 v29, 1.0, v45
	v_mul_f32_e32 v27, v27, v29
	v_sqrt_f32_e32 v29, v27
	v_fmac_f32_e32 v41, v40, v33
	v_mov_b32_e32 v27, v41
	v_mul_f32_e32 v1, v35, v1
	v_pk_mul_f32 v[26:27], v[26:27], v[44:45]
	v_mul_f32_e32 v1, v45, v1
	v_fmac_f32_e32 v27, v26, v29
	s_waitcnt lgkmcnt(0)
	v_mov_b32_e32 v249, v1
	v_mov_b32_e32 v26, v1
	s_nop 1
	v_permlane16_swap_b32_e32 v26, v249
	v_cndmask_b32_e64 v26, v249, v26, s[98:99]
	v_mul_f32_e32 v31, v1, v26
	s_waitcnt lgkmcnt(0)
	v_mov_b32_e32 v249, v27
	v_mov_b32_e32 v29, v27
	s_nop 1
	v_permlane16_swap_b32_e32 v29, v249
	v_cndmask_b32_e64 v29, v249, v29, s[98:99]
	v_fma_f32 v1, v1, v29, v27
	v_fmac_f32_e32 v29, v27, v26
	v_cndmask_b32_e64 v1, v1, v29, s[46:47]
	s_waitcnt lgkmcnt(0)
	v_mov_b32_e32 v249, v31
	v_mov_b32_e32 v27, v31
	s_nop 1
	v_permlane32_swap_b32_e32 v27, v249
	v_cndmask_b32_e64 v27, v249, v27, s[100:101]
	v_mul_f32_e32 v26, v31, v27
	s_waitcnt lgkmcnt(0)
	v_mov_b32_e32 v249, v1
	v_mov_b32_e32 v29, v1
	s_nop 1
	v_permlane32_swap_b32_e32 v29, v249
	v_cndmask_b32_e64 v29, v249, v29, s[100:101]
	v_fma_f32 v31, v31, v29, v1
	v_fmac_f32_e32 v29, v1, v27
	v_cndmask_b32_e64 v27, v31, v29, s[48:49]
	ds_write_b64 v86, v[26:27] offset:62848
	s_waitcnt lgkmcnt(1)
	v_mfma_f32_16x16x32_bf16 v[44:47], v[14:17], v[198:201], 0
	s_waitcnt lgkmcnt(1)
	v_mfma_f32_16x16x32_bf16 v[44:47], v[18:21], v[202:205], v[44:47]
	s_waitcnt lgkmcnt(1)
	v_mfma_f32_16x16x32_bf16 v[58:61], v[14:17], v[206:209], 0
	s_waitcnt lgkmcnt(1)
	v_mfma_f32_16x16x32_bf16 v[52:55], v[18:21], v[210:213], v[58:61]
	ds_read_b32 v217, v93 offset:58048
	ds_read_b32 v218, v93 offset:58304
	ds_read_b32 v219, v93 offset:58560
	ds_read_b128 v[198:201], v23 offset:44288
	ds_read_b128 v[202:205], v23 offset:44352
	ds_read_b128 v[206:209], v23 offset:53504
	ds_read_b128 v[210:213], v23 offset:53568
	s_waitcnt lgkmcnt(2)
; #define LAS __attribute__((address_space(3)))
; template <bool PHASE_B>
; __device__ __forceinline__ void lru_item(const Params& p, LAS unsigned char* lds, int ci, int ci_next, int jb, const int tid, v4u (&xvn)[3]) {
;     ...
;             const int ch = 16 * ct + fr; const float bav = GC[(dir * 3 + 0) * 64 + ch], bxv = GC[(dir * 3 + 1) * 64 + ch], c8 = GC[(dir * 3 + 2) * 64 + ch];
;             float Al = 1.f, Hl = 0.f;
; #pragma unroll
;             for (int ee = 0; ee < 4; ++ee) { const int e = dir ? 3 - ee : ee;
;                 const float r = __builtin_amdgcn_rcpf(1.f + __expf(-(ga[e] + bav))), ig = __builtin_amdgcn_rcpf(1.f + __expf(-(gx[e] + bxv)));
;                 const float la = -c8 * r; const float a = __expf(la); const float u = __builtin_amdgcn_sqrtf((1.f - a) * (1.f + a)) * (ig * xc[ct][e]);
;                 av[dir][ct][e] = a; uv[dir][ct][e] = u; Hl = a * Hl + u; Al *= a; }
;             const int o = dir ? 3 - fq : fq; const bool odd = (o & 1) != 0, hi2 = (o & 2) != 0;
;             const float A1 = __shfl_xor(Al, 16), H1 = __shfl_xor(Hl, 16);
;             const float pxA = odd ? A1 : 1.f, pxH = odd ? H1 : 0.f;
;             const float gA = Al * A1, gH = odd ? (Al * H1 + Hl) : (A1 * Hl + H1);
;             const float A2 = __shfl_xor(gA, 32), H2 = __shfl_xor(gH, 32);
;             const float PA = hi2 ? pxA * A2 : pxA, PH = hi2 ? (pxA * H2 + pxH) : pxH;
;             const float TA = gA * A2, TH = hi2 ? (gA * H2 + gH) : (A2 * gH + H2);
;             pA[dir][ct] = PA; pH[dir][ct] = PH;
;             ((LAS f32x2*)(lds + LR_SEG))[(dir * 8 + rt) * 64 + ch] = (f32x2){TA, TH};
	s_nop 2
	v_add_f32_e32 v1, v47, v214
	v_mul_f32_e32 v1, 0xbfb8aa3b, v1
	v_exp_f32_e32 v1, v1
	s_nop 0
	v_add_f32_e32 v1, 1.0, v1
	v_rcp_f32_e32 v1, v1
	s_waitcnt lgkmcnt(1)
	v_add_f32_e32 v26, v55, v215
	v_mul_f32_e32 v26, 0xbfb8aa3b, v26
	v_exp_f32_e32 v27, v26
	s_waitcnt lgkmcnt(0)
	v_mul_f32_e32 v1, v1, v216
	v_mul_f32_e32 v1, 0xbfb8aa3b, v1
	v_exp_f32_e32 v26, v1
	v_add_f32_e32 v1, 1.0, v27
	v_rcp_f32_e32 v27, v1
	v_add_f32_e32 v37, v54, v215
	v_sub_f32_e32 v1, 1.0, v26
	v_add_f32_e32 v34, 1.0, v26
	v_mul_f32_e32 v1, v1, v34
	v_add_f32_e32 v34, v46, v214
	v_mul_f32_e32 v34, 0xbfb8aa3b, v34
	v_exp_f32_e32 v35, v34
	v_mul_f32_e32 v37, 0xbfb8aa3b, v37
	v_sqrt_f32_e32 v1, v1
	v_exp_f32_e32 v37, v37
	v_add_f32_e32 v35, 1.0, v35
	v_rcp_f32_e32 v35, v35
	v_mul_f32_e32 v27, v56, v27
	v_mul_f32_e32 v34, 0, v26
	v_mul_f32_e32 v35, v35, v216
	v_mul_f32_e32 v35, 0xbfb8aa3b, v35
	v_exp_f32_e32 v35, v35
	s_nop 0
	v_pk_fma_f32 v[40:41], v[26:27], v[0:1], v[34:35] op_sel_hi:[1,1,0]
	v_add_f32_e32 v1, 1.0, v37
	v_rcp_f32_e32 v34, v1
	v_sub_f32_e32 v1, 1.0, v35
	v_add_f32_e32 v27, 1.0, v35
	v_mul_f32_e32 v1, v1, v27
	v_add_f32_e32 v27, v45, v214
	v_mul_f32_e32 v27, 0xbfb8aa3b, v27
	v_sqrt_f32_e32 v1, v1
	v_exp_f32_e32 v27, v27
	v_mov_b32_e32 v51, v41
	v_pk_mul_f32 v[40:41], v[50:51], v[34:35]
	v_add_f32_e32 v29, v44, v214
	v_fmac_f32_e32 v41, v40, v1
	v_add_f32_e32 v1, 1.0, v27
	v_rcp_f32_e32 v1, v1
	v_add_f32_e32 v27, v53, v215
	v_mul_f32_e32 v27, 0xbfb8aa3b, v27
	v_exp_f32_e32 v34, v27
	v_mul_f32_e32 v1, v1, v216
	v_mul_f32_e32 v1, 0xbfb8aa3b, v1
	v_exp_f32_e32 v27, v1
	v_mul_f32_e32 v1, v26, v35
	v_add_f32_e32 v26, 1.0, v34
	v_mul_f32_e32 v29, 0xbfb8aa3b, v29
	v_rcp_f32_e32 v26, v26
	v_exp_f32_e32 v29, v29
	v_sub_f32_e32 v34, 1.0, v27
	v_add_f32_e32 v35, 1.0, v27
	v_mul_f32_e32 v34, v34, v35
	v_mov_b32_e32 v39, v41
	v_sqrt_f32_e32 v37, v34
	v_pk_mul_f32 v[34:35], v[38:39], v[26:27]
	v_add_f32_e32 v26, 1.0, v29
	v_rcp_f32_e32 v26, v26
	v_add_f32_e32 v29, v52, v215
	v_mul_f32_e32 v29, 0xbfb8aa3b, v29
	v_exp_f32_e32 v29, v29
	v_mul_f32_e32 v26, v26, v216
	v_mul_f32_e32 v26, 0xbfb8aa3b, v26
	v_exp_f32_e32 v39, v26
	v_add_f32_e32 v26, 1.0, v29
	v_rcp_f32_e32 v38, v26
	v_fmac_f32_e32 v35, v34, v37
	v_sub_f32_e32 v26, 1.0, v39
	v_add_f32_e32 v29, 1.0, v39
	v_mul_f32_e32 v26, v26, v29
	v_sqrt_f32_e32 v29, v26
	v_mov_b32_e32 v31, v35
	v_mul_f32_e32 v1, v27, v1
	v_pk_mul_f32 v[26:27], v[30:31], v[38:39]
	v_mul_f32_e32 v1, v39, v1
	v_fmac_f32_e32 v27, v26, v29
	s_waitcnt lgkmcnt(0)
	v_mov_b32_e32 v249, v1
	v_mov_b32_e32 v26, v1
	s_nop 1
	v_permlane16_swap_b32_e32 v26, v249
	v_cndmask_b32_e64 v26, v249, v26, s[98:99]
	v_mul_f32_e32 v30, v1, v26
	s_waitcnt lgkmcnt(0)
	v_mov_b32_e32 v249, v27
	v_mov_b32_e32 v29, v27
	s_nop 1
	v_permlane16_swap_b32_e32 v29, v249
	v_cndmask_b32_e64 v29, v249, v29, s[98:99]
	v_fma_f32 v1, v1, v29, v27
	v_fmac_f32_e32 v29, v27, v26
	v_cndmask_b32_e64 v1, v1, v29, s[46:47]
	s_waitcnt lgkmcnt(0)
	v_mov_b32_e32 v249, v30
	v_mov_b32_e32 v27, v30
	s_nop 1
	v_permlane32_swap_b32_e32 v27, v249
	v_cndmask_b32_e64 v27, v249, v27, s[100:101]
	v_mul_f32_e32 v26, v30, v27
	s_waitcnt lgkmcnt(0)
	v_mov_b32_e32 v249, v1
	v_mov_b32_e32 v29, v1
	s_nop 1
	v_permlane32_swap_b32_e32 v29, v249
	v_cndmask_b32_e64 v29, v249, v29, s[100:101]
	v_fma_f32 v30, v30, v29, v1
	v_fmac_f32_e32 v29, v1, v27
	v_cndmask_b32_e64 v27, v30, v29, s[48:49]
	ds_write_b64 v86, v[26:27] offset:62976
	s_waitcnt lgkmcnt(1)
	v_mfma_f32_16x16x32_bf16 v[38:41], v[14:17], v[198:201], 0
	s_waitcnt lgkmcnt(1)
	v_mfma_f32_16x16x32_bf16 v[38:41], v[18:21], v[202:205], v[38:41]
	s_waitcnt lgkmcnt(1)
	v_mfma_f32_16x16x32_bf16 v[14:17], v[14:17], v[206:209], 0
	s_waitcnt lgkmcnt(1)
	v_mfma_f32_16x16x32_bf16 v[14:17], v[18:21], v[210:213], v[14:17]
	s_waitcnt lgkmcnt(1)
	s_nop 2
	v_add_f32_e32 v1, v41, v217
	v_mul_f32_e32 v1, 0xbfb8aa3b, v1
	v_exp_f32_e32 v1, v1
	s_nop 0
	v_add_f32_e32 v1, 1.0, v1
	v_rcp_f32_e32 v1, v1
	s_waitcnt lgkmcnt(1)
	v_add_f32_e32 v17, v17, v218
	v_mul_f32_e32 v17, 0xbfb8aa3b, v17
	v_exp_f32_e32 v17, v17
	s_waitcnt lgkmcnt(0)
; #define LAS __attribute__((address_space(3)))
; template <bool PHASE_B>
; __device__ __forceinline__ void lru_item(const Params& p, LAS unsigned char* lds, int ci, int ci_next, int jb, const int tid, v4u (&xvn)[3]) {
;     ...
;             const int ch = 16 * ct + fr; const float bav = GC[(dir * 3 + 0) * 64 + ch], bxv = GC[(dir * 3 + 1) * 64 + ch], c8 = GC[(dir * 3 + 2) * 64 + ch];
;             float Al = 1.f, Hl = 0.f;
; #pragma unroll
;             for (int ee = 0; ee < 4; ++ee) { const int e = dir ? 3 - ee : ee;
;                 const float r = __builtin_amdgcn_rcpf(1.f + __expf(-(ga[e] + bav))), ig = __builtin_amdgcn_rcpf(1.f + __expf(-(gx[e] + bxv)));
;                 const float la = -c8 * r; const float a = __expf(la); const float u = __builtin_amdgcn_sqrtf((1.f - a) * (1.f + a)) * (ig * xc[ct][e]);
;                 av[dir][ct][e] = a; uv[dir][ct][e] = u; Hl = a * Hl + u; Al *= a; }
;             const int o = dir ? 3 - fq : fq; const bool odd = (o & 1) != 0, hi2 = (o & 2) != 0;
;             const float A1 = __shfl_xor(Al, 16), H1 = __shfl_xor(Hl, 16);
;             const float pxA = odd ? A1 : 1.f, pxH = odd ? H1 : 0.f;
;             const float gA = Al * A1, gH = odd ? (Al * H1 + Hl) : (A1 * Hl + H1);
;             const float A2 = __shfl_xor(gA, 32), H2 = __shfl_xor(gH, 32);
;             const float PA = hi2 ? pxA * A2 : pxA, PH = hi2 ? (pxA * H2 + pxH) : pxH;
;             const float TA = gA * A2, TH = hi2 ? (gA * H2 + gH) : (A2 * gH + H2);
;             pA[dir][ct] = PA; pH[dir][ct] = PH;
;             ((LAS f32x2*)(lds + LR_SEG))[(dir * 8 + rt) * 64 + ch] = (f32x2){TA, TH};
;     ...
;     if constexpr (!PHASE_B) {
;         if (tid < 128) { const int dir = tid >> 6, ch = tid & 63; float A = 1.f, H = 0.f;
; #pragma unroll
;             for (int q = 0; q < 8; ++q) { const f32x2 sh = ((const LAS f32x2*)(lds + LR_SEG))[(dir * 8 + (dir ? 7 - q : q)) * 64 + ch]; H = sh.x * H + sh.y; A *= sh.x; }
;             ((f32x2*)(p.ws + WS_CAR))[(size_t)(ci * 2 + dir) * 768 + jb * 64 + ch] = (f32x2){A, H}; }
	v_mul_f32_e32 v1, v1, v219
	v_mul_f32_e32 v1, 0xbfb8aa3b, v1
	v_exp_f32_e32 v18, v1
	v_add_f32_e32 v1, 1.0, v17
	v_rcp_f32_e32 v17, v1
	v_add_f32_e32 v16, v16, v218
	v_sub_f32_e32 v1, 1.0, v18
	v_add_f32_e32 v19, 1.0, v18
	v_mul_f32_e32 v1, v1, v19
	v_add_f32_e32 v19, v40, v217
	v_mul_f32_e32 v19, 0xbfb8aa3b, v19
	v_exp_f32_e32 v21, v19
	v_mul_f32_e32 v19, v28, v17
	v_mul_f32_e32 v16, 0xbfb8aa3b, v16
	v_sqrt_f32_e32 v1, v1
	v_add_f32_e32 v17, 1.0, v21
	v_rcp_f32_e32 v17, v17
	v_exp_f32_e32 v16, v16
	v_mul_f32_e32 v20, 0, v18
	v_pk_fma_f32 v[20:21], v[18:19], v[0:1], v[20:21] op_sel_hi:[1,1,0]
	v_mul_f32_e32 v17, v17, v219
	v_mul_f32_e32 v17, 0xbfb8aa3b, v17
	v_exp_f32_e32 v17, v17
	v_add_f32_e32 v1, 1.0, v16
	v_rcp_f32_e32 v16, v1
	v_mov_b32_e32 v43, v21
	v_sub_f32_e32 v1, 1.0, v17
	v_add_f32_e32 v19, 1.0, v17
	v_mul_f32_e32 v1, v1, v19
	v_add_f32_e32 v19, v39, v217
	v_mul_f32_e32 v19, 0xbfb8aa3b, v19
	v_sqrt_f32_e32 v1, v1
	v_exp_f32_e32 v19, v19
	v_pk_mul_f32 v[20:21], v[42:43], v[16:17]
	v_add_f32_e32 v15, v15, v218
	v_fmac_f32_e32 v21, v20, v1
	v_add_f32_e32 v1, 1.0, v19
	v_rcp_f32_e32 v1, v1
	v_mul_f32_e32 v15, 0xbfb8aa3b, v15
	v_exp_f32_e32 v15, v15
	v_add_f32_e32 v14, v14, v218
	v_mul_f32_e32 v1, v1, v219
	v_mul_f32_e32 v1, 0xbfb8aa3b, v1
	v_exp_f32_e32 v19, v1
	v_add_f32_e32 v15, 1.0, v15
	v_mul_f32_e32 v1, v18, v17
	v_rcp_f32_e32 v18, v15
	v_sub_f32_e32 v15, 1.0, v19
	v_add_f32_e32 v16, 1.0, v19
	v_mul_f32_e32 v15, v15, v16
	v_add_f32_e32 v16, v38, v217
	v_mul_f32_e32 v16, 0xbfb8aa3b, v16
	v_exp_f32_e32 v20, v16
	v_sqrt_f32_e32 v23, v15
	v_mul_f32_e32 v14, 0xbfb8aa3b, v14
	v_exp_f32_e32 v14, v14
	v_add_f32_e32 v15, 1.0, v20
	v_rcp_f32_e32 v15, v15
	v_mov_b32_e32 v37, v21
	v_pk_mul_f32 v[16:17], v[36:37], v[18:19]
	v_add_f32_e32 v14, 1.0, v14
	v_mul_f32_e32 v15, v15, v219
	v_mul_f32_e32 v15, 0xbfb8aa3b, v15
	v_exp_f32_e32 v15, v15
	v_fmac_f32_e32 v17, v16, v23
	v_rcp_f32_e32 v14, v14
	v_mov_b32_e32 v33, v17
	v_sub_f32_e32 v16, 1.0, v15
	v_add_f32_e32 v18, 1.0, v15
	v_mul_f32_e32 v16, v16, v18
	v_sqrt_f32_e32 v18, v16
	v_mul_f32_e32 v1, v19, v1
	v_pk_mul_f32 v[16:17], v[32:33], v[14:15]
	v_mul_f32_e32 v1, v15, v1
	v_fmac_f32_e32 v17, v16, v18
	s_waitcnt lgkmcnt(0)
	v_mov_b32_e32 v249, v1
	v_mov_b32_e32 v14, v1
	s_nop 1
	v_permlane16_swap_b32_e32 v14, v249
	v_cndmask_b32_e64 v14, v249, v14, s[98:99]
	v_mul_f32_e32 v16, v1, v14
	s_waitcnt lgkmcnt(0)
	v_mov_b32_e32 v249, v17
	v_mov_b32_e32 v15, v17
	s_nop 1
	v_permlane16_swap_b32_e32 v15, v249
	v_cndmask_b32_e64 v15, v249, v15, s[98:99]
	v_fma_f32 v1, v1, v15, v17
	v_fmac_f32_e32 v15, v17, v14
	v_cndmask_b32_e64 v1, v1, v15, s[46:47]
	s_waitcnt lgkmcnt(0)
	v_mov_b32_e32 v249, v16
	v_mov_b32_e32 v15, v16
	s_nop 1
	v_permlane32_swap_b32_e32 v15, v249
	v_cndmask_b32_e64 v15, v249, v15, s[100:101]
	v_mul_f32_e32 v14, v16, v15
	s_waitcnt lgkmcnt(0)
	v_mov_b32_e32 v249, v1
	v_mov_b32_e32 v17, v1
	s_nop 1
	v_permlane32_swap_b32_e32 v17, v249
	v_cndmask_b32_e64 v17, v249, v17, s[100:101]
	v_fma_f32 v16, v16, v17, v1
	v_fmac_f32_e32 v17, v1, v15
	v_cndmask_b32_e64 v15, v16, v17, s[48:49]
	ds_write_b64 v86, v[14:15] offset:63104
	s_waitcnt vmcnt(0) lgkmcnt(0)
	s_barrier
	s_and_saveexec_b64 s[12:13], s[50:51]
	s_cbranch_execz .LBB0_528
	ds_read_b64 v[14:15], v94 offset:58624
	ds_read_b64 v[16:17], v95 offset:58624
	ds_read_b64 v[18:19], v96 offset:58624
	ds_read_b64 v[20:21], v97 offset:58624
	s_waitcnt lgkmcnt(3)
	v_fma_f32 v1, 0, v14, v15
	s_waitcnt lgkmcnt(2)
	v_pk_mul_f32 v[14:15], v[14:15], v[16:17]
	v_fmac_f32_e32 v17, v16, v1
	s_waitcnt lgkmcnt(1)
	v_fma_f32 v1, v18, v17, v19
	ds_read_b64 v[16:17], v98 offset:58624
	ds_read_b64 v[26:27], v99 offset:58624
	ds_read_b64 v[28:29], v100 offset:58624
	ds_read_b64 v[30:31], v101 offset:58624
	s_waitcnt lgkmcnt(4)
	v_fma_f32 v1, v20, v1, v21
	v_mov_b32_e32 v32, v14
	v_mov_b32_e32 v34, v18
	s_waitcnt lgkmcnt(3)
	v_fma_f32 v33, v16, v1, v17
	s_waitcnt lgkmcnt(2)
	v_mov_b32_e32 v35, v26
	v_pk_mul_f32 v[14:15], v[14:15], v[18:19]
	v_pk_fma_f32 v[18:19], v[32:33], v[34:35], v[26:27]
	v_pk_mul_f32 v[14:15], v[14:15], v[20:21]
	s_waitcnt lgkmcnt(1)
	v_mov_b32_e32 v17, v28
	v_mov_b32_e32 v15, v19
	v_pk_mul_f32 v[18:19], v[14:15], v[16:17]
	v_pk_fma_f32 v[14:15], v[14:15], v[16:17], v[28:29]
	v_pk_mul_f32 v[18:19], v[18:19], v[26:27]
	v_mov_b32_e32 v16, v28
	v_mov_b32_e32 v14, v18
	s_waitcnt lgkmcnt(0)
	v_mov_b32_e32 v17, v30
	v_pk_mul_f32 v[18:19], v[18:19], v[28:29]
	v_pk_fma_f32 v[14:15], v[14:15], v[16:17], v[30:31]
	v_pk_mul_f32 v[18:19], v[18:19], v[30:31]
	s_nop 0
	v_mov_b32_e32 v19, v15
	v_mad_i64_i32 v[14:15], s[60:61], v87, s64, v[24:25]
	global_store_dwordx2 v[14:15], v[18:19], off
	s_branch .LBB0_528
